# v009 + nt on GEMM1 epilogue dwordx4 stores
# speedup vs baseline: 1.0012x; 1.0003x over previous
; __device__ __forceinline__ unsigned pk2(float lo, float hi) { return __builtin_bit_cast(unsigned, __builtin_convertvector((f32x2){lo, hi}, bf16x2_t)); }
; __device__ __forceinline__ float fsigmoid(float x) { return __builtin_amdgcn_rcpf(1.0f + fexp(-x)); }
;     __device__ __forceinline__ void operator()(f32x4 (&acc)[2][2][4][2], const pg8::Unit& u, int wr, int wc, int fr, int fq) const {
;     ...
;         const int row0 = u.pm * 256 + wr * 64 + fr, c8 = wc * 32 + 8 * fq;
;         const int bb = u.pm >> 4, nb = 4 * (u.pm & 15) + wr;
;         if (tile < 16) {
;     ...
;             bf16_t* G = (bf16_t*)(ws + (tile < 80 ? WS_GA : WS_GB)) + ((tile - 64) & 15) * 256 + c8;
; #pragma unroll
;             for (int ai = 0; ai < 2; ++ai)
; #pragma unroll
;                 for (int m = 0; m < 4; ++m)
; #pragma unroll
;                     for (int bj = 0; bj < 2; ++bj) {
;                         const f32x4 a0 = acc[ai][bj][m][0], a1 = acc[ai][bj][m][1];
;                         *(u32x4*)(G + (size_t)(row0 + ai * 128 + m * 16) * DM + bj * 128) =
;                             (u32x4){pk2(fsigmoid(a0[0]), fsigmoid(a0[1])), pk2(fsigmoid(a0[2]), fsigmoid(a0[3])), pk2(fsigmoid(a1[0]), fsigmoid(a1[1])), pk2(fsigmoid(a1[2]), fsigmoid(a1[3]))};
;                     }
.LBB0_132:
	s_lshl_b32 s3, s4, 8
	v_mov_b32_e32 v172, v174
	v_mov_b32_e32 v181, v175
	s_add_i32 s3, s3, s83
	s_cmp_gt_i32 s64, 15
	v_add_u32_e32 v134, s3, v172
	v_lshl_add_u32 v136, v181, 3, s84
	s_mov_b64 s[66:67], -1
	s_cbranch_scc0 .LBB0_198
	s_cmp_gt_u32 s64, 23
	s_cbranch_scc0 .LBB0_179
	s_lshl_b32 s3, s4, 2
	s_and_b32 s51, s3, 60
	s_ashr_i32 s47, s4, 4
	s_add_i32 s51, s51, s74
	s_cmp_gt_u32 s64, 39
	s_mov_b64 s[4:5], -1
	s_cbranch_scc0 .LBB0_144
	s_cmp_gt_u32 s64, 47
	s_cbranch_scc0 .LBB0_141
	s_cmp_gt_u32 s64, 63
	v_ashrrev_i32_e32 v137, 31, v136
	s_cbranch_scc0 .LBB0_138
	s_cmpk_lt_u32 s64, 0x50
	s_mov_b32 s3, 0x30700000
	s_cselect_b32 s3, s3, 0x38700000
	s_add_u32 s3, s30, s3
	s_addc_u32 s5, s31, 0
	s_lshl_b32 s4, s64, 9
	s_and_b32 s4, s4, 0x1e00
	s_add_u32 s4, s3, s4
	s_addc_u32 s5, s5, 0
	v_ashrrev_i32_e32 v135, 31, v134
	v_lshl_add_u64 v[138:139], v[136:137], 1, s[4:5]
	v_lshlrev_b64 v[140:141], 13, v[134:135]
	v_lshl_add_u64 v[138:139], v[138:139], 0, v[140:141]
	v_mul_f32_e32 v135, 0xbfb8aa3b, v124
	v_mul_f32_e32 v140, 0xbfb8aa3b, v125
	v_exp_f32_e32 v135, v135
	v_exp_f32_e32 v140, v140
	v_mul_f32_e32 v141, 0xbfb8aa3b, v127
	v_exp_f32_e32 v141, v141
	v_add_f32_e32 v135, 1.0, v135
	v_add_f32_e32 v140, 1.0, v140
	v_rcp_f32_e32 v135, v135
	v_rcp_f32_e32 v140, v140
	v_add_f32_e32 v141, 1.0, v141
	v_rcp_f32_e32 v141, v141
	v_mul_f32_e32 v142, 0xbfb8aa3b, v117
	v_cvt_pk_bf16_f32 v140, v135, v140
	v_mul_f32_e32 v135, 0xbfb8aa3b, v126
	v_exp_f32_e32 v135, v135
	v_exp_f32_e32 v142, v142
	v_mul_f32_e32 v143, 0xbfb8aa3b, v119
	v_exp_f32_e32 v143, v143
	v_add_f32_e32 v135, 1.0, v135
	v_rcp_f32_e32 v135, v135
	v_add_f32_e32 v142, 1.0, v142
	v_rcp_f32_e32 v142, v142
	v_add_f32_e32 v143, 1.0, v143
	v_cvt_pk_bf16_f32 v141, v135, v141
	v_mul_f32_e32 v135, 0xbfb8aa3b, v116
	v_exp_f32_e32 v135, v135
	v_rcp_f32_e32 v143, v143
	v_mul_f32_e32 v144, 0xbfb8aa3b, v101
	v_exp_f32_e32 v144, v144
	v_add_f32_e32 v135, 1.0, v135
	v_rcp_f32_e32 v135, v135
	v_mul_f32_e32 v145, 0xbfb8aa3b, v103
	v_add_f32_e32 v144, 1.0, v144
	v_rcp_f32_e32 v144, v144
	v_cvt_pk_bf16_f32 v142, v135, v142
	v_mul_f32_e32 v135, 0xbfb8aa3b, v118
	v_exp_f32_e32 v135, v135
	v_exp_f32_e32 v145, v145
	v_add_co_u32_e32 v146, vcc, s94, v138
	v_add_f32_e32 v135, 1.0, v135
	v_rcp_f32_e32 v135, v135
	v_add_f32_e32 v145, 1.0, v145
	v_rcp_f32_e32 v145, v145
	v_addc_co_u32_e32 v147, vcc, 0, v139, vcc
	v_cvt_pk_bf16_f32 v143, v135, v143
	global_store_dwordx4 v[138:139], v[140:143], off nt
	v_mul_f32_e32 v135, 0xbfb8aa3b, v120
	v_exp_f32_e32 v135, v135
	v_mul_f32_e32 v140, 0xbfb8aa3b, v121
	v_exp_f32_e32 v140, v140
	v_mul_f32_e32 v141, 0xbfb8aa3b, v123
	v_add_f32_e32 v135, 1.0, v135
	v_rcp_f32_e32 v135, v135
	v_add_f32_e32 v140, 1.0, v140
	v_rcp_f32_e32 v140, v140
	v_exp_f32_e32 v141, v141
	v_mul_f32_e32 v142, 0xbfb8aa3b, v113
	v_exp_f32_e32 v142, v142
	v_cvt_pk_bf16_f32 v140, v135, v140
	v_mul_f32_e32 v135, 0xbfb8aa3b, v122
	v_exp_f32_e32 v135, v135
	v_add_f32_e32 v141, 1.0, v141
	v_rcp_f32_e32 v141, v141
	v_add_f32_e32 v142, 1.0, v142
	v_add_f32_e32 v135, 1.0, v135
	v_rcp_f32_e32 v135, v135
	v_rcp_f32_e32 v142, v142
	v_mul_f32_e32 v143, 0xbfb8aa3b, v115
	v_exp_f32_e32 v143, v143
	v_cvt_pk_bf16_f32 v141, v135, v141
	v_mul_f32_e32 v135, 0xbfb8aa3b, v112
	v_exp_f32_e32 v135, v135
	v_add_f32_e32 v143, 1.0, v143
	v_rcp_f32_e32 v143, v143
	s_mov_b64 s[4:5], 0x20000
	v_add_f32_e32 v135, 1.0, v135
	v_rcp_f32_e32 v135, v135
	s_mov_b32 s3, 0x40000
	v_cvt_pk_bf16_f32 v142, v135, v142
	v_mul_f32_e32 v135, 0xbfb8aa3b, v114
	v_exp_f32_e32 v135, v135
	s_nop 0
	v_add_f32_e32 v135, 1.0, v135
	v_rcp_f32_e32 v135, v135
	s_nop 0
	v_cvt_pk_bf16_f32 v143, v135, v143
	global_store_dwordx4 v[138:139], v[140:143], off offset:256 nt
	v_mul_f32_e32 v135, 0xbfb8aa3b, v108
	v_exp_f32_e32 v135, v135
	v_mul_f32_e32 v142, 0xbfb8aa3b, v109
	v_exp_f32_e32 v142, v142
	v_mul_f32_e32 v143, 0xbfb8aa3b, v111
	v_add_f32_e32 v135, 1.0, v135
	v_rcp_f32_e32 v135, v135
	v_add_f32_e32 v142, 1.0, v142
	v_rcp_f32_e32 v142, v142
	v_exp_f32_e32 v143, v143
	v_lshl_add_u64 v[140:141], v[138:139], 0, s[4:5]
	s_mov_b64 s[4:5], 0x40000
	v_cvt_pk_bf16_f32 v142, v135, v142
	v_mul_f32_e32 v135, 0xbfb8aa3b, v110
	v_exp_f32_e32 v135, v135
	v_add_f32_e32 v143, 1.0, v143
	v_rcp_f32_e32 v143, v143
	v_add_f32_e32 v135, 1.0, v135
	v_rcp_f32_e32 v135, v135
	s_nop 0
	v_cvt_pk_bf16_f32 v143, v135, v143
	v_mul_f32_e32 v135, 0xbfb8aa3b, v100
	v_exp_f32_e32 v135, v135
	s_nop 0
	v_add_f32_e32 v135, 1.0, v135
	v_rcp_f32_e32 v135, v135
	s_nop 0
	v_cvt_pk_bf16_f32 v144, v135, v144
	v_mul_f32_e32 v135, 0xbfb8aa3b, v102
	v_exp_f32_e32 v135, v135
	s_nop 0
	v_add_f32_e32 v135, 1.0, v135
	v_rcp_f32_e32 v135, v135
	s_nop 0
	v_cvt_pk_bf16_f32 v145, v135, v145
	global_store_dwordx4 v[146:147], v[142:145], off nt
	v_mul_f32_e32 v135, 0xbfb8aa3b, v104
	v_exp_f32_e32 v135, v135
	v_mul_f32_e32 v142, 0xbfb8aa3b, v105
	v_exp_f32_e32 v142, v142
	v_mul_f32_e32 v143, 0xbfb8aa3b, v107
	v_add_f32_e32 v135, 1.0, v135
	v_rcp_f32_e32 v135, v135
	v_add_f32_e32 v142, 1.0, v142
	v_rcp_f32_e32 v142, v142
	v_exp_f32_e32 v143, v143
	v_mul_f32_e32 v144, 0xbfb8aa3b, v97
	v_exp_f32_e32 v144, v144
	v_cvt_pk_bf16_f32 v142, v135, v142
	v_mul_f32_e32 v135, 0xbfb8aa3b, v106
	v_exp_f32_e32 v135, v135
	v_add_f32_e32 v143, 1.0, v143
	v_rcp_f32_e32 v143, v143
	v_add_f32_e32 v144, 1.0, v144
	v_add_f32_e32 v135, 1.0, v135
	v_rcp_f32_e32 v135, v135
	v_rcp_f32_e32 v144, v144
	v_mul_f32_e32 v145, 0xbfb8aa3b, v99
	v_exp_f32_e32 v145, v145
	v_cvt_pk_bf16_f32 v143, v135, v143
	v_mul_f32_e32 v135, 0xbfb8aa3b, v96
	v_exp_f32_e32 v135, v135
	v_add_f32_e32 v145, 1.0, v145
	v_rcp_f32_e32 v145, v145
; __device__ __forceinline__ unsigned pk2(float lo, float hi) { return __builtin_bit_cast(unsigned, __builtin_convertvector((f32x2){lo, hi}, bf16x2_t)); }
; __device__ __forceinline__ float fsigmoid(float x) { return __builtin_amdgcn_rcpf(1.0f + fexp(-x)); }
;     __device__ __forceinline__ void operator()(f32x4 (&acc)[2][2][4][2], const pg8::Unit& u, int wr, int wc, int fr, int fq) const {
;     ...
;             bf16_t* G = (bf16_t*)(ws + (tile < 80 ? WS_GA : WS_GB)) + ((tile - 64) & 15) * 256 + c8;
; #pragma unroll
;             for (int ai = 0; ai < 2; ++ai)
; #pragma unroll
;                 for (int m = 0; m < 4; ++m)
; #pragma unroll
;                     for (int bj = 0; bj < 2; ++bj) {
;                         const f32x4 a0 = acc[ai][bj][m][0], a1 = acc[ai][bj][m][1];
;                         *(u32x4*)(G + (size_t)(row0 + ai * 128 + m * 16) * DM + bj * 128) =
;                             (u32x4){pk2(fsigmoid(a0[0]), fsigmoid(a0[1])), pk2(fsigmoid(a0[2]), fsigmoid(a0[3])), pk2(fsigmoid(a1[0]), fsigmoid(a1[1])), pk2(fsigmoid(a1[2]), fsigmoid(a1[3]))};
;                     }
	v_add_co_u32_e32 v146, vcc, s3, v138
	v_add_f32_e32 v135, 1.0, v135
	v_rcp_f32_e32 v135, v135
	v_addc_co_u32_e32 v147, vcc, 0, v139, vcc
	s_mov_b32 s3, 0x60000
	v_cvt_pk_bf16_f32 v144, v135, v144
	v_mul_f32_e32 v135, 0xbfb8aa3b, v98
	v_exp_f32_e32 v135, v135
	s_nop 0
	v_add_f32_e32 v135, 1.0, v135
	v_rcp_f32_e32 v135, v135
	s_nop 0
	v_cvt_pk_bf16_f32 v145, v135, v145
	global_store_dwordx4 v[140:141], v[142:145], off offset:256 nt
	v_mul_f32_e32 v135, 0xbfb8aa3b, v92
	v_exp_f32_e32 v135, v135
	v_mul_f32_e32 v142, 0xbfb8aa3b, v93
	v_exp_f32_e32 v142, v142
	v_mul_f32_e32 v143, 0xbfb8aa3b, v95
	v_add_f32_e32 v135, 1.0, v135
	v_rcp_f32_e32 v135, v135
	v_add_f32_e32 v142, 1.0, v142
	v_rcp_f32_e32 v142, v142
	v_exp_f32_e32 v143, v143
	v_mul_f32_e32 v144, 0xbfb8aa3b, v85
	v_exp_f32_e32 v144, v144
	v_cvt_pk_bf16_f32 v142, v135, v142
	v_mul_f32_e32 v135, 0xbfb8aa3b, v94
	v_exp_f32_e32 v135, v135
	v_add_f32_e32 v143, 1.0, v143
	v_rcp_f32_e32 v143, v143
	v_add_f32_e32 v144, 1.0, v144
	v_add_f32_e32 v135, 1.0, v135
	v_rcp_f32_e32 v135, v135
	v_rcp_f32_e32 v144, v144
	v_mul_f32_e32 v145, 0xbfb8aa3b, v87
	v_exp_f32_e32 v145, v145
	v_cvt_pk_bf16_f32 v143, v135, v143
	v_mul_f32_e32 v135, 0xbfb8aa3b, v84
	v_exp_f32_e32 v135, v135
	v_add_f32_e32 v145, 1.0, v145
	v_rcp_f32_e32 v145, v145
	v_lshl_add_u64 v[140:141], v[138:139], 0, s[4:5]
	v_add_f32_e32 v135, 1.0, v135
	v_rcp_f32_e32 v135, v135
	s_mov_b64 s[4:5], 0x60000
	v_cvt_pk_bf16_f32 v144, v135, v144
	v_mul_f32_e32 v135, 0xbfb8aa3b, v86
	v_exp_f32_e32 v135, v135
	s_nop 0
	v_add_f32_e32 v135, 1.0, v135
	v_rcp_f32_e32 v135, v135
	s_nop 0
	v_cvt_pk_bf16_f32 v145, v135, v145
	global_store_dwordx4 v[146:147], v[142:145], off nt
	v_mul_f32_e32 v135, 0xbfb8aa3b, v88
	v_exp_f32_e32 v135, v135
	v_mul_f32_e32 v142, 0xbfb8aa3b, v89
	v_exp_f32_e32 v142, v142
	v_mul_f32_e32 v143, 0xbfb8aa3b, v91
	v_add_f32_e32 v135, 1.0, v135
	v_rcp_f32_e32 v135, v135
	v_add_f32_e32 v142, 1.0, v142
	v_rcp_f32_e32 v142, v142
	v_exp_f32_e32 v143, v143
	v_mul_f32_e32 v144, 0xbfb8aa3b, v81
	v_exp_f32_e32 v144, v144
	v_cvt_pk_bf16_f32 v142, v135, v142
	v_mul_f32_e32 v135, 0xbfb8aa3b, v90
	v_exp_f32_e32 v135, v135
	v_add_f32_e32 v143, 1.0, v143
	v_rcp_f32_e32 v143, v143
	v_add_f32_e32 v144, 1.0, v144
	v_add_f32_e32 v135, 1.0, v135
	v_rcp_f32_e32 v135, v135
	v_rcp_f32_e32 v144, v144
	v_mul_f32_e32 v145, 0xbfb8aa3b, v83
	v_exp_f32_e32 v145, v145
	v_cvt_pk_bf16_f32 v143, v135, v143
	v_mul_f32_e32 v135, 0xbfb8aa3b, v80
	v_exp_f32_e32 v135, v135
	v_add_f32_e32 v145, 1.0, v145
	v_rcp_f32_e32 v145, v145
	v_add_co_u32_e32 v146, vcc, s3, v138
	v_add_f32_e32 v135, 1.0, v135
	v_rcp_f32_e32 v135, v135
	v_addc_co_u32_e32 v147, vcc, 0, v139, vcc
	s_mov_b32 s3, 0x100000
	v_cvt_pk_bf16_f32 v144, v135, v144
	v_mul_f32_e32 v135, 0xbfb8aa3b, v82
	v_exp_f32_e32 v135, v135
	s_nop 0
	v_add_f32_e32 v135, 1.0, v135
	v_rcp_f32_e32 v135, v135
	s_nop 0
	v_cvt_pk_bf16_f32 v145, v135, v145
	global_store_dwordx4 v[140:141], v[142:145], off offset:256 nt
	v_mul_f32_e32 v135, 0xbfb8aa3b, v76
	v_exp_f32_e32 v135, v135
	v_mul_f32_e32 v142, 0xbfb8aa3b, v77
	v_exp_f32_e32 v142, v142
	v_mul_f32_e32 v143, 0xbfb8aa3b, v79
	v_add_f32_e32 v135, 1.0, v135
	v_rcp_f32_e32 v135, v135
	v_add_f32_e32 v142, 1.0, v142
	v_rcp_f32_e32 v142, v142
	v_exp_f32_e32 v143, v143
	v_mul_f32_e32 v144, 0xbfb8aa3b, v69
	v_exp_f32_e32 v144, v144
	v_cvt_pk_bf16_f32 v142, v135, v142
	v_mul_f32_e32 v135, 0xbfb8aa3b, v78
	v_exp_f32_e32 v135, v135
	v_add_f32_e32 v143, 1.0, v143
	v_rcp_f32_e32 v143, v143
	v_add_f32_e32 v144, 1.0, v144
	v_add_f32_e32 v135, 1.0, v135
	v_rcp_f32_e32 v135, v135
	v_rcp_f32_e32 v144, v144
	v_mul_f32_e32 v145, 0xbfb8aa3b, v71
	v_exp_f32_e32 v145, v145
	v_cvt_pk_bf16_f32 v143, v135, v143
	v_mul_f32_e32 v135, 0xbfb8aa3b, v68
	v_exp_f32_e32 v135, v135
	v_add_f32_e32 v145, 1.0, v145
	v_rcp_f32_e32 v145, v145
	v_lshl_add_u64 v[140:141], v[138:139], 0, s[4:5]
	v_add_f32_e32 v135, 1.0, v135
	v_rcp_f32_e32 v135, v135
	s_mov_b64 s[4:5], 0x120000
	v_cvt_pk_bf16_f32 v144, v135, v144
	v_mul_f32_e32 v135, 0xbfb8aa3b, v70
	v_exp_f32_e32 v135, v135
	s_nop 0
	v_add_f32_e32 v135, 1.0, v135
	v_rcp_f32_e32 v135, v135
	s_nop 0
	v_cvt_pk_bf16_f32 v145, v135, v145
	global_store_dwordx4 v[146:147], v[142:145], off nt
	v_mul_f32_e32 v135, 0xbfb8aa3b, v72
	v_exp_f32_e32 v135, v135
	v_mul_f32_e32 v142, 0xbfb8aa3b, v73
	v_exp_f32_e32 v142, v142
	v_mul_f32_e32 v143, 0xbfb8aa3b, v75
	v_add_f32_e32 v135, 1.0, v135
	v_rcp_f32_e32 v135, v135
	v_add_f32_e32 v142, 1.0, v142
	v_rcp_f32_e32 v142, v142
	v_exp_f32_e32 v143, v143
	v_mul_f32_e32 v144, 0xbfb8aa3b, v65
	v_exp_f32_e32 v144, v144
	v_cvt_pk_bf16_f32 v142, v135, v142
	v_mul_f32_e32 v135, 0xbfb8aa3b, v74
	v_exp_f32_e32 v135, v135
	v_add_f32_e32 v143, 1.0, v143
	v_rcp_f32_e32 v143, v143
	v_add_f32_e32 v144, 1.0, v144
	v_add_f32_e32 v135, 1.0, v135
	v_rcp_f32_e32 v135, v135
	v_rcp_f32_e32 v144, v144
	v_mul_f32_e32 v145, 0xbfb8aa3b, v67
	v_exp_f32_e32 v145, v145
	v_cvt_pk_bf16_f32 v143, v135, v143
	v_mul_f32_e32 v135, 0xbfb8aa3b, v64
	v_exp_f32_e32 v135, v135
	v_add_f32_e32 v145, 1.0, v145
	v_rcp_f32_e32 v145, v145
	v_add_co_u32_e32 v146, vcc, s3, v138
	v_add_f32_e32 v135, 1.0, v135
	v_rcp_f32_e32 v135, v135
	v_addc_co_u32_e32 v147, vcc, 0, v139, vcc
	s_mov_b32 s3, 0x120000
	v_cvt_pk_bf16_f32 v144, v135, v144
	v_mul_f32_e32 v135, 0xbfb8aa3b, v66
	v_exp_f32_e32 v135, v135
	s_nop 0
	v_add_f32_e32 v135, 1.0, v135
	v_rcp_f32_e32 v135, v135
	s_nop 0
	v_cvt_pk_bf16_f32 v145, v135, v145
	global_store_dwordx4 v[140:141], v[142:145], off offset:256 nt
	v_mul_f32_e32 v135, 0xbfb8aa3b, v60
	v_exp_f32_e32 v135, v135
	v_mul_f32_e32 v142, 0xbfb8aa3b, v61
	v_exp_f32_e32 v142, v142
; __device__ __forceinline__ unsigned pk2(float lo, float hi) { return __builtin_bit_cast(unsigned, __builtin_convertvector((f32x2){lo, hi}, bf16x2_t)); }
; __device__ __forceinline__ float fsigmoid(float x) { return __builtin_amdgcn_rcpf(1.0f + fexp(-x)); }
;     __device__ __forceinline__ void operator()(f32x4 (&acc)[2][2][4][2], const pg8::Unit& u, int wr, int wc, int fr, int fq) const {
;     ...
;             bf16_t* G = (bf16_t*)(ws + (tile < 80 ? WS_GA : WS_GB)) + ((tile - 64) & 15) * 256 + c8;
; #pragma unroll
;             for (int ai = 0; ai < 2; ++ai)
; #pragma unroll
;                 for (int m = 0; m < 4; ++m)
; #pragma unroll
;                     for (int bj = 0; bj < 2; ++bj) {
;                         const f32x4 a0 = acc[ai][bj][m][0], a1 = acc[ai][bj][m][1];
;                         *(u32x4*)(G + (size_t)(row0 + ai * 128 + m * 16) * DM + bj * 128) =
;                             (u32x4){pk2(fsigmoid(a0[0]), fsigmoid(a0[1])), pk2(fsigmoid(a0[2]), fsigmoid(a0[3])), pk2(fsigmoid(a1[0]), fsigmoid(a1[1])), pk2(fsigmoid(a1[2]), fsigmoid(a1[3]))};
;                     }
	v_mul_f32_e32 v143, 0xbfb8aa3b, v63
	v_add_f32_e32 v135, 1.0, v135
	v_rcp_f32_e32 v135, v135
	v_add_f32_e32 v142, 1.0, v142
	v_rcp_f32_e32 v142, v142
	v_exp_f32_e32 v143, v143
	v_mul_f32_e32 v144, 0xbfb8aa3b, v53
	v_exp_f32_e32 v144, v144
	v_cvt_pk_bf16_f32 v142, v135, v142
	v_mul_f32_e32 v135, 0xbfb8aa3b, v62
	v_exp_f32_e32 v135, v135
	v_add_f32_e32 v143, 1.0, v143
	v_rcp_f32_e32 v143, v143
	v_add_f32_e32 v144, 1.0, v144
	v_add_f32_e32 v135, 1.0, v135
	v_rcp_f32_e32 v135, v135
	v_rcp_f32_e32 v144, v144
	v_mul_f32_e32 v145, 0xbfb8aa3b, v55
	v_exp_f32_e32 v145, v145
	v_cvt_pk_bf16_f32 v143, v135, v143
	v_mul_f32_e32 v135, 0xbfb8aa3b, v52
	v_exp_f32_e32 v135, v135
	v_add_f32_e32 v145, 1.0, v145
	v_rcp_f32_e32 v145, v145
	v_lshl_add_u64 v[140:141], v[138:139], 0, s[10:11]
	v_add_f32_e32 v135, 1.0, v135
	v_rcp_f32_e32 v135, v135
	s_nop 0
	v_cvt_pk_bf16_f32 v144, v135, v144
	v_mul_f32_e32 v135, 0xbfb8aa3b, v54
	v_exp_f32_e32 v135, v135
	s_nop 0
	v_add_f32_e32 v135, 1.0, v135
	v_rcp_f32_e32 v135, v135
	s_nop 0
	v_cvt_pk_bf16_f32 v145, v135, v145
	global_store_dwordx4 v[146:147], v[142:145], off nt
	v_mul_f32_e32 v135, 0xbfb8aa3b, v56
	v_exp_f32_e32 v135, v135
	v_mul_f32_e32 v142, 0xbfb8aa3b, v57
	v_exp_f32_e32 v142, v142
	v_mul_f32_e32 v143, 0xbfb8aa3b, v59
	v_add_f32_e32 v135, 1.0, v135
	v_rcp_f32_e32 v135, v135
	v_add_f32_e32 v142, 1.0, v142
	v_rcp_f32_e32 v142, v142
	v_exp_f32_e32 v143, v143
	v_mul_f32_e32 v144, 0xbfb8aa3b, v49
	v_exp_f32_e32 v144, v144
	v_cvt_pk_bf16_f32 v142, v135, v142
	v_mul_f32_e32 v135, 0xbfb8aa3b, v58
	v_exp_f32_e32 v135, v135
	v_add_f32_e32 v143, 1.0, v143
	v_rcp_f32_e32 v143, v143
	v_add_f32_e32 v144, 1.0, v144
	v_add_f32_e32 v135, 1.0, v135
	v_rcp_f32_e32 v135, v135
	v_rcp_f32_e32 v144, v144
	v_mul_f32_e32 v145, 0xbfb8aa3b, v51
	v_exp_f32_e32 v145, v145
	v_cvt_pk_bf16_f32 v143, v135, v143
	v_mul_f32_e32 v135, 0xbfb8aa3b, v48
	v_exp_f32_e32 v135, v135
	v_add_f32_e32 v145, 1.0, v145
	v_rcp_f32_e32 v145, v145
	v_add_co_u32_e32 v146, vcc, s3, v138
	v_add_f32_e32 v135, 1.0, v135
	v_rcp_f32_e32 v135, v135
	v_addc_co_u32_e32 v147, vcc, 0, v139, vcc
	s_mov_b32 s3, 0x140000
	v_cvt_pk_bf16_f32 v144, v135, v144
	v_mul_f32_e32 v135, 0xbfb8aa3b, v50
	v_exp_f32_e32 v135, v135
	s_nop 0
	v_add_f32_e32 v135, 1.0, v135
	v_rcp_f32_e32 v135, v135
	s_nop 0
	v_cvt_pk_bf16_f32 v145, v135, v145
	global_store_dwordx4 v[140:141], v[142:145], off offset:256 nt
	v_mul_f32_e32 v135, 0xbfb8aa3b, v44
	v_exp_f32_e32 v135, v135
	v_mul_f32_e32 v142, 0xbfb8aa3b, v45
	v_exp_f32_e32 v142, v142
	v_mul_f32_e32 v143, 0xbfb8aa3b, v47
	v_add_f32_e32 v135, 1.0, v135
	v_rcp_f32_e32 v135, v135
	v_add_f32_e32 v142, 1.0, v142
	v_rcp_f32_e32 v142, v142
	v_exp_f32_e32 v143, v143
	v_mul_f32_e32 v144, 0xbfb8aa3b, v37
	v_exp_f32_e32 v144, v144
	v_cvt_pk_bf16_f32 v142, v135, v142
	v_mul_f32_e32 v135, 0xbfb8aa3b, v46
	v_exp_f32_e32 v135, v135
	v_add_f32_e32 v143, 1.0, v143
	v_rcp_f32_e32 v143, v143
	v_add_f32_e32 v144, 1.0, v144
	v_add_f32_e32 v135, 1.0, v135
	v_rcp_f32_e32 v135, v135
	v_rcp_f32_e32 v144, v144
	v_mul_f32_e32 v145, 0xbfb8aa3b, v39
	v_exp_f32_e32 v145, v145
	v_cvt_pk_bf16_f32 v143, v135, v143
	v_mul_f32_e32 v135, 0xbfb8aa3b, v36
	v_exp_f32_e32 v135, v135
	v_add_f32_e32 v145, 1.0, v145
	v_rcp_f32_e32 v145, v145
	v_lshl_add_u64 v[140:141], v[138:139], 0, s[4:5]
	v_add_f32_e32 v135, 1.0, v135
	v_rcp_f32_e32 v135, v135
	s_mov_b64 s[4:5], 0x140000
	v_cvt_pk_bf16_f32 v144, v135, v144
	v_mul_f32_e32 v135, 0xbfb8aa3b, v38
	v_exp_f32_e32 v135, v135
	s_nop 0
	v_add_f32_e32 v135, 1.0, v135
	v_rcp_f32_e32 v135, v135
	s_nop 0
	v_cvt_pk_bf16_f32 v145, v135, v145
	global_store_dwordx4 v[146:147], v[142:145], off nt
	v_mul_f32_e32 v135, 0xbfb8aa3b, v40
	v_exp_f32_e32 v135, v135
	v_mul_f32_e32 v142, 0xbfb8aa3b, v41
	v_exp_f32_e32 v142, v142
	v_mul_f32_e32 v143, 0xbfb8aa3b, v43
	v_add_f32_e32 v135, 1.0, v135
	v_rcp_f32_e32 v135, v135
	v_add_f32_e32 v142, 1.0, v142
	v_rcp_f32_e32 v142, v142
	v_exp_f32_e32 v143, v143
	v_mul_f32_e32 v144, 0xbfb8aa3b, v33
	v_exp_f32_e32 v144, v144
	v_cvt_pk_bf16_f32 v142, v135, v142
	v_mul_f32_e32 v135, 0xbfb8aa3b, v42
	v_exp_f32_e32 v135, v135
	v_add_f32_e32 v143, 1.0, v143
	v_rcp_f32_e32 v143, v143
	v_add_f32_e32 v144, 1.0, v144
	v_add_f32_e32 v135, 1.0, v135
	v_rcp_f32_e32 v135, v135
	v_rcp_f32_e32 v144, v144
	v_mul_f32_e32 v145, 0xbfb8aa3b, v35
	v_exp_f32_e32 v145, v145
	v_cvt_pk_bf16_f32 v143, v135, v143
	v_mul_f32_e32 v135, 0xbfb8aa3b, v32
	v_exp_f32_e32 v135, v135
	v_add_f32_e32 v145, 1.0, v145
	v_rcp_f32_e32 v145, v145
	v_add_co_u32_e32 v146, vcc, s3, v138
	v_add_f32_e32 v135, 1.0, v135
	v_rcp_f32_e32 v135, v135
	v_addc_co_u32_e32 v147, vcc, 0, v139, vcc
	s_mov_b32 s3, 0x160000
	v_cvt_pk_bf16_f32 v144, v135, v144
	v_mul_f32_e32 v135, 0xbfb8aa3b, v34
	v_exp_f32_e32 v135, v135
	s_nop 0
	v_add_f32_e32 v135, 1.0, v135
	v_rcp_f32_e32 v135, v135
	s_nop 0
	v_cvt_pk_bf16_f32 v145, v135, v145
	global_store_dwordx4 v[140:141], v[142:145], off offset:256 nt
	v_mul_f32_e32 v135, 0xbfb8aa3b, v28
	v_exp_f32_e32 v135, v135
	v_mul_f32_e32 v142, 0xbfb8aa3b, v29
	v_exp_f32_e32 v142, v142
	v_mul_f32_e32 v143, 0xbfb8aa3b, v31
	v_add_f32_e32 v135, 1.0, v135
	v_rcp_f32_e32 v135, v135
	v_add_f32_e32 v142, 1.0, v142
	v_rcp_f32_e32 v142, v142
	v_exp_f32_e32 v143, v143
	v_mul_f32_e32 v144, 0xbfb8aa3b, v21
	v_exp_f32_e32 v144, v144
	v_cvt_pk_bf16_f32 v142, v135, v142
	v_mul_f32_e32 v135, 0xbfb8aa3b, v30
	v_exp_f32_e32 v135, v135
	v_add_f32_e32 v143, 1.0, v143
	v_rcp_f32_e32 v143, v143
	v_add_f32_e32 v144, 1.0, v144
	v_add_f32_e32 v135, 1.0, v135
	v_rcp_f32_e32 v135, v135
	v_rcp_f32_e32 v144, v144
	v_mul_f32_e32 v145, 0xbfb8aa3b, v23
	v_exp_f32_e32 v145, v145
; __device__ __forceinline__ unsigned pk2(float lo, float hi) { return __builtin_bit_cast(unsigned, __builtin_convertvector((f32x2){lo, hi}, bf16x2_t)); }
; __device__ __forceinline__ float fsigmoid(float x) { return __builtin_amdgcn_rcpf(1.0f + fexp(-x)); }
;     __device__ __forceinline__ void operator()(f32x4 (&acc)[2][2][4][2], const pg8::Unit& u, int wr, int wc, int fr, int fq) const {
;     ...
;             bf16_t* G = (bf16_t*)(ws + (tile < 80 ? WS_GA : WS_GB)) + ((tile - 64) & 15) * 256 + c8;
; #pragma unroll
;             for (int ai = 0; ai < 2; ++ai)
; #pragma unroll
;                 for (int m = 0; m < 4; ++m)
; #pragma unroll
;                     for (int bj = 0; bj < 2; ++bj) {
;                         const f32x4 a0 = acc[ai][bj][m][0], a1 = acc[ai][bj][m][1];
;                         *(u32x4*)(G + (size_t)(row0 + ai * 128 + m * 16) * DM + bj * 128) =
;                             (u32x4){pk2(fsigmoid(a0[0]), fsigmoid(a0[1])), pk2(fsigmoid(a0[2]), fsigmoid(a0[3])), pk2(fsigmoid(a1[0]), fsigmoid(a1[1])), pk2(fsigmoid(a1[2]), fsigmoid(a1[3]))};
;                     }
	v_cvt_pk_bf16_f32 v143, v135, v143
	v_mul_f32_e32 v135, 0xbfb8aa3b, v20
	v_exp_f32_e32 v135, v135
	v_add_f32_e32 v145, 1.0, v145
	v_rcp_f32_e32 v145, v145
	v_lshl_add_u64 v[140:141], v[138:139], 0, s[4:5]
	v_add_f32_e32 v135, 1.0, v135
	v_rcp_f32_e32 v135, v135
	s_mov_b64 s[4:5], 0x160000
	v_cvt_pk_bf16_f32 v144, v135, v144
	v_mul_f32_e32 v135, 0xbfb8aa3b, v22
	v_exp_f32_e32 v135, v135
	s_nop 0
	v_add_f32_e32 v135, 1.0, v135
	v_rcp_f32_e32 v135, v135
	s_nop 0
	v_cvt_pk_bf16_f32 v145, v135, v145
	global_store_dwordx4 v[146:147], v[142:145], off nt
	v_mul_f32_e32 v135, 0xbfb8aa3b, v24
	v_exp_f32_e32 v135, v135
	v_mul_f32_e32 v142, 0xbfb8aa3b, v25
	v_exp_f32_e32 v142, v142
	v_mul_f32_e32 v143, 0xbfb8aa3b, v27
	v_add_f32_e32 v135, 1.0, v135
	v_rcp_f32_e32 v135, v135
	v_add_f32_e32 v142, 1.0, v142
	v_rcp_f32_e32 v142, v142
	v_exp_f32_e32 v143, v143
	v_mul_f32_e32 v144, 0xbfb8aa3b, v17
	v_exp_f32_e32 v144, v144
	v_cvt_pk_bf16_f32 v142, v135, v142
	v_mul_f32_e32 v135, 0xbfb8aa3b, v26
	v_exp_f32_e32 v135, v135
	v_add_f32_e32 v143, 1.0, v143
	v_rcp_f32_e32 v143, v143
	v_add_f32_e32 v144, 1.0, v144
	v_add_f32_e32 v135, 1.0, v135
	v_rcp_f32_e32 v135, v135
	v_rcp_f32_e32 v144, v144
	v_mul_f32_e32 v145, 0xbfb8aa3b, v19
	v_exp_f32_e32 v145, v145
	v_cvt_pk_bf16_f32 v143, v135, v143
	v_mul_f32_e32 v135, 0xbfb8aa3b, v16
	v_exp_f32_e32 v135, v135
	v_add_f32_e32 v145, 1.0, v145
	v_rcp_f32_e32 v145, v145
	v_add_f32_e32 v135, 1.0, v135
	v_rcp_f32_e32 v135, v135
	s_nop 0
	v_cvt_pk_bf16_f32 v144, v135, v144
	v_mul_f32_e32 v135, 0xbfb8aa3b, v18
	v_exp_f32_e32 v135, v135
	s_nop 0
	v_add_f32_e32 v135, 1.0, v135
	v_rcp_f32_e32 v135, v135
	s_nop 0
	v_cvt_pk_bf16_f32 v145, v135, v145
	global_store_dwordx4 v[140:141], v[142:145], off offset:256 nt
	v_mul_f32_e32 v135, 0xbfb8aa3b, v12
	v_exp_f32_e32 v135, v135
	v_mul_f32_e32 v142, 0xbfb8aa3b, v13
	v_exp_f32_e32 v142, v142
	v_mul_f32_e32 v143, 0xbfb8aa3b, v15
	v_add_f32_e32 v135, 1.0, v135
	v_rcp_f32_e32 v135, v135
	v_add_f32_e32 v142, 1.0, v142
	v_rcp_f32_e32 v142, v142
	v_exp_f32_e32 v143, v143
	v_mul_f32_e32 v144, 0xbfb8aa3b, v5
	v_exp_f32_e32 v144, v144
	v_cvt_pk_bf16_f32 v142, v135, v142
	v_mul_f32_e32 v135, 0xbfb8aa3b, v14
	v_exp_f32_e32 v135, v135
	v_add_f32_e32 v143, 1.0, v143
	v_rcp_f32_e32 v143, v143
	v_add_f32_e32 v144, 1.0, v144
	v_add_f32_e32 v135, 1.0, v135
	v_rcp_f32_e32 v135, v135
	v_rcp_f32_e32 v144, v144
	v_mul_f32_e32 v145, 0xbfb8aa3b, v7
	v_exp_f32_e32 v145, v145
	v_cvt_pk_bf16_f32 v143, v135, v143
	v_mul_f32_e32 v135, 0xbfb8aa3b, v4
	v_exp_f32_e32 v135, v135
	v_add_f32_e32 v145, 1.0, v145
	v_rcp_f32_e32 v145, v145
	v_lshl_add_u64 v[140:141], v[138:139], 0, s[4:5]
	v_add_f32_e32 v135, 1.0, v135
	v_rcp_f32_e32 v135, v135
	v_add_co_u32_e32 v138, vcc, s3, v138
	s_mov_b64 s[4:5], 0
	v_cvt_pk_bf16_f32 v144, v135, v144
	v_mul_f32_e32 v135, 0xbfb8aa3b, v6
	v_exp_f32_e32 v135, v135
	v_addc_co_u32_e32 v139, vcc, 0, v139, vcc
	v_add_f32_e32 v135, 1.0, v135
	v_rcp_f32_e32 v135, v135
	s_nop 0
	v_cvt_pk_bf16_f32 v145, v135, v145
	global_store_dwordx4 v[138:139], v[142:145], off nt
	v_mul_f32_e32 v135, 0xbfb8aa3b, v8
	v_mul_f32_e32 v138, 0xbfb8aa3b, v9
	v_exp_f32_e32 v135, v135
	v_exp_f32_e32 v138, v138
	v_add_f32_e32 v135, 1.0, v135
	v_add_f32_e32 v138, 1.0, v138
	v_rcp_f32_e32 v135, v135
	v_rcp_f32_e32 v138, v138
	s_nop 0
	v_cvt_pk_bf16_f32 v142, v135, v138
	v_mul_f32_e32 v135, 0xbfb8aa3b, v10
	v_mul_f32_e32 v138, 0xbfb8aa3b, v11
	v_exp_f32_e32 v135, v135
	v_exp_f32_e32 v138, v138
	v_add_f32_e32 v135, 1.0, v135
	v_add_f32_e32 v138, 1.0, v138
	v_rcp_f32_e32 v135, v135
	v_rcp_f32_e32 v138, v138
	s_nop 0
	v_cvt_pk_bf16_f32 v143, v135, v138
	v_mul_f32_e32 v135, 0xbfb8aa3b, v0
	v_mul_f32_e32 v138, 0xbfb8aa3b, v1
	v_exp_f32_e32 v135, v135
	v_exp_f32_e32 v138, v138
	v_add_f32_e32 v135, 1.0, v135
	v_add_f32_e32 v138, 1.0, v138
	v_rcp_f32_e32 v135, v135
	v_rcp_f32_e32 v138, v138
	s_nop 0
	v_cvt_pk_bf16_f32 v144, v135, v138
	v_mul_f32_e32 v135, 0xbfb8aa3b, v2
	v_mul_f32_e32 v138, 0xbfb8aa3b, v3
	v_exp_f32_e32 v135, v135
	v_exp_f32_e32 v138, v138
	v_add_f32_e32 v135, 1.0, v135
	v_add_f32_e32 v138, 1.0, v138
	v_rcp_f32_e32 v135, v135
	v_rcp_f32_e32 v138, v138
	s_nop 0
	v_cvt_pk_bf16_f32 v145, v135, v138
	global_store_dwordx4 v[140:141], v[142:145], off offset:256 nt
; __device__ __forceinline__ unsigned pk2(float lo, float hi) { return __builtin_bit_cast(unsigned, __builtin_convertvector((f32x2){lo, hi}, bf16x2_t)); }
; __device__ __forceinline__ float fsigmoid(float x) { return __builtin_amdgcn_rcpf(1.0f + fexp(-x)); }
;     __device__ __forceinline__ void operator()(f32x4 (&acc)[2][2][4][2], const pg8::Unit& u, int wr, int wc, int fr, int fq) const {
;     ...
;         } else if (tile < 64) {
; #pragma unroll
;             for (int ai = 0; ai < 2; ++ai) {
;                 const size_t cb = ((size_t)(bb * 64 + nb + 2 * ai) * 16 + (tile - 48));
;                 bf16_t* gp = (bf16_t*)(ws + WS_GZ) + cb * 8192 + fr * 128 + c8;
; #pragma unroll
;                 for (int m = 0; m < 4; ++m) {
;                     float y[8];
; #pragma unroll
;                     for (int n = 0; n < 2; ++n)
; #pragma unroll
;                         for (int j = 0; j < 4; ++j) { const float og = acc[ai][0][m][n][j], zz = acc[ai][1][m][n][j]; y[4 * n + j] = fsigmoid(og) * zz * fsigmoid(zz); }
;                     *(u32x4*)(gp + m * 2048) = (u32x4){pk2(y[0], y[1]), pk2(y[2], y[3]), pk2(y[4], y[5]), pk2(y[6], y[7])};
;                 }
;             }
.LBB0_138:
	s_andn2_b64 vcc, exec, s[4:5]
	s_cbranch_vccnz .LBB0_140
	v_mul_f32_e32 v135, 0xbfb8aa3b, v124
	v_exp_f32_e32 v135, v135
	s_lshl_b32 s3, s47, 6
	s_add_i32 s4, s51, s3
	s_sub_i32 s14, s64, 48
	v_add_f32_e32 v135, 1.0, v135
	v_rcp_f32_e32 v140, v135
	v_mul_f32_e32 v135, 0xbfb8aa3b, v120
	v_exp_f32_e32 v135, v135
	s_ashr_i32 s5, s4, 31
	s_lshl_b64 s[26:27], s[14:15], 14
	s_lshl_b64 s[4:5], s[4:5], 18
	v_add_f32_e32 v135, 1.0, v135
	v_rcp_f32_e32 v142, v135
	v_mul_f32_e32 v135, 0xbfb8aa3b, v125
	v_exp_f32_e32 v135, v135
	v_readlane_b32 s3, v252, 22
	s_add_u32 s3, s3, s4
	v_readlane_b32 s4, v252, 23
	v_add_f32_e32 v135, 1.0, v135
	v_rcp_f32_e32 v141, v135
	v_mul_f32_e32 v135, 0xbfb8aa3b, v121
	v_exp_f32_e32 v135, v135
	s_addc_u32 s5, s4, s5
	v_pk_mul_f32 v[140:141], v[140:141], v[120:121]
	v_lshlrev_b32_e32 v138, 7, v172
	v_add_f32_e32 v135, 1.0, v135
	v_rcp_f32_e32 v143, v135
	v_mul_f32_e32 v135, 0xbfb8aa3b, v126
	v_exp_f32_e32 v135, v135
	s_add_u32 s4, s3, s26
	v_pk_mul_f32 v[140:141], v[140:141], v[142:143]
	v_ashrrev_i32_e32 v139, 31, v138
	v_add_f32_e32 v135, 1.0, v135
	v_rcp_f32_e32 v142, v135
	v_mul_f32_e32 v135, 0xbfb8aa3b, v122
	v_exp_f32_e32 v135, v135
	s_addc_u32 s5, s5, s27
	v_lshl_add_u64 v[138:139], v[138:139], 1, s[4:5]
	v_lshl_add_u64 v[138:139], v[136:137], 1, v[138:139]
	v_add_f32_e32 v135, 1.0, v135
	v_rcp_f32_e32 v144, v135
	v_mul_f32_e32 v135, 0xbfb8aa3b, v127
	v_exp_f32_e32 v135, v135
	v_cvt_pk_bf16_f32 v140, v140, v141
	s_mov_b32 s3, 0x81000
	v_add_f32_e32 v135, 1.0, v135
	v_rcp_f32_e32 v143, v135
	v_mul_f32_e32 v135, 0xbfb8aa3b, v123
	v_exp_f32_e32 v135, v135
	v_pk_mul_f32 v[142:143], v[142:143], v[122:123]
	v_add_f32_e32 v135, 1.0, v135
	v_rcp_f32_e32 v145, v135
	v_mul_f32_e32 v135, 0xbfb8aa3b, v116
	v_exp_f32_e32 v135, v135
	v_pk_mul_f32 v[142:143], v[142:143], v[144:145]
	s_nop 0
	v_cvt_pk_bf16_f32 v141, v142, v143
	v_add_f32_e32 v135, 1.0, v135
	v_rcp_f32_e32 v144, v135
	v_mul_f32_e32 v135, 0xbfb8aa3b, v112
	v_exp_f32_e32 v135, v135
	s_nop 0
	v_add_f32_e32 v135, 1.0, v135
	v_rcp_f32_e32 v146, v135
	v_mul_f32_e32 v135, 0xbfb8aa3b, v117
	v_exp_f32_e32 v135, v135
	s_nop 0
	v_add_f32_e32 v135, 1.0, v135
	v_rcp_f32_e32 v145, v135
	v_mul_f32_e32 v135, 0xbfb8aa3b, v113
	v_exp_f32_e32 v135, v135
	v_pk_mul_f32 v[144:145], v[144:145], v[112:113]
	v_add_f32_e32 v135, 1.0, v135
	v_rcp_f32_e32 v147, v135
	v_mul_f32_e32 v135, 0xbfb8aa3b, v118
	v_exp_f32_e32 v135, v135
	v_pk_mul_f32 v[144:145], v[144:145], v[146:147]
	s_nop 0
	v_cvt_pk_bf16_f32 v142, v144, v145
	v_add_f32_e32 v135, 1.0, v135
	v_rcp_f32_e32 v146, v135
	v_mul_f32_e32 v135, 0xbfb8aa3b, v114
	v_exp_f32_e32 v135, v135
	s_nop 0
	v_add_f32_e32 v135, 1.0, v135
	v_rcp_f32_e32 v148, v135
	v_mul_f32_e32 v135, 0xbfb8aa3b, v119
	v_exp_f32_e32 v135, v135
	s_nop 0
	v_add_f32_e32 v135, 1.0, v135
	v_rcp_f32_e32 v147, v135
	v_mul_f32_e32 v135, 0xbfb8aa3b, v115
	v_exp_f32_e32 v135, v135
	v_pk_mul_f32 v[146:147], v[146:147], v[114:115]
	v_add_f32_e32 v135, 1.0, v135
	v_rcp_f32_e32 v149, v135
	v_mul_f32_e32 v135, 0xbfb8aa3b, v108
	v_exp_f32_e32 v135, v135
	v_pk_mul_f32 v[146:147], v[146:147], v[148:149]
	s_nop 0
	v_cvt_pk_bf16_f32 v143, v146, v147
	v_add_f32_e32 v135, 1.0, v135
	global_store_dwordx4 v[138:139], v[140:143], off nt
	s_nop 1
	v_rcp_f32_e32 v140, v135
	v_mul_f32_e32 v135, 0xbfb8aa3b, v104
	v_exp_f32_e32 v135, v135
	s_nop 0
	v_add_f32_e32 v135, 1.0, v135
	v_rcp_f32_e32 v142, v135
	v_mul_f32_e32 v135, 0xbfb8aa3b, v109
	v_exp_f32_e32 v135, v135
	s_nop 0
	v_add_f32_e32 v135, 1.0, v135
	v_rcp_f32_e32 v141, v135
	v_mul_f32_e32 v135, 0xbfb8aa3b, v105
	v_exp_f32_e32 v135, v135
	v_pk_mul_f32 v[140:141], v[140:141], v[104:105]
	v_add_f32_e32 v135, 1.0, v135
	v_rcp_f32_e32 v143, v135
	v_mul_f32_e32 v135, 0xbfb8aa3b, v110
	v_exp_f32_e32 v135, v135
	v_pk_mul_f32 v[140:141], v[140:141], v[142:143]
	v_add_f32_e32 v135, 1.0, v135
	v_rcp_f32_e32 v142, v135
	v_mul_f32_e32 v135, 0xbfb8aa3b, v106
	v_exp_f32_e32 v135, v135
	s_nop 0
	v_add_f32_e32 v135, 1.0, v135
	v_rcp_f32_e32 v144, v135
	v_mul_f32_e32 v135, 0xbfb8aa3b, v111
	v_exp_f32_e32 v135, v135
	s_nop 0
	v_add_f32_e32 v135, 1.0, v135
	v_rcp_f32_e32 v143, v135
	v_mul_f32_e32 v135, 0xbfb8aa3b, v107
	v_exp_f32_e32 v135, v135
	v_pk_mul_f32 v[142:143], v[142:143], v[106:107]
	v_add_f32_e32 v135, 1.0, v135
	v_rcp_f32_e32 v145, v135
	v_mul_f32_e32 v135, 0xbfb8aa3b, v100
	v_exp_f32_e32 v135, v135
	v_pk_mul_f32 v[144:145], v[142:143], v[144:145]
	v_add_f32_e32 v135, 1.0, v135
	v_rcp_f32_e32 v142, v135
	v_mul_f32_e32 v135, 0xbfb8aa3b, v96
	v_exp_f32_e32 v135, v135
	s_nop 0
	v_add_f32_e32 v135, 1.0, v135
	v_rcp_f32_e32 v146, v135
	v_mul_f32_e32 v135, 0xbfb8aa3b, v101
	v_exp_f32_e32 v135, v135
	s_nop 0
	v_add_f32_e32 v135, 1.0, v135
	v_rcp_f32_e32 v143, v135
	v_mul_f32_e32 v135, 0xbfb8aa3b, v97
	v_exp_f32_e32 v135, v135
	v_pk_mul_f32 v[142:143], v[142:143], v[96:97]
	v_add_f32_e32 v135, 1.0, v135
	v_rcp_f32_e32 v147, v135
	v_mul_f32_e32 v135, 0xbfb8aa3b, v102
	v_exp_f32_e32 v135, v135
	v_pk_mul_f32 v[146:147], v[142:143], v[146:147]
	v_add_f32_e32 v135, 1.0, v135
	v_rcp_f32_e32 v142, v135
	v_mul_f32_e32 v135, 0xbfb8aa3b, v98
	v_exp_f32_e32 v135, v135
	s_nop 0
	v_add_f32_e32 v135, 1.0, v135
	v_rcp_f32_e32 v148, v135
	v_mul_f32_e32 v135, 0xbfb8aa3b, v103
	v_exp_f32_e32 v135, v135
	s_nop 0
	v_add_f32_e32 v135, 1.0, v135
	v_rcp_f32_e32 v143, v135
	v_mul_f32_e32 v135, 0xbfb8aa3b, v99
	v_exp_f32_e32 v135, v135
	v_pk_mul_f32 v[142:143], v[142:143], v[98:99]
	v_add_f32_e32 v135, 1.0, v135
	v_rcp_f32_e32 v149, v135
	v_mul_f32_e32 v135, 0xbfb8aa3b, v92
	v_exp_f32_e32 v135, v135
	v_pk_mul_f32 v[148:149], v[142:143], v[148:149]
; __device__ __forceinline__ unsigned pk2(float lo, float hi) { return __builtin_bit_cast(unsigned, __builtin_convertvector((f32x2){lo, hi}, bf16x2_t)); }
; __device__ __forceinline__ float fsigmoid(float x) { return __builtin_amdgcn_rcpf(1.0f + fexp(-x)); }
;     __device__ __forceinline__ void operator()(f32x4 (&acc)[2][2][4][2], const pg8::Unit& u, int wr, int wc, int fr, int fq) const {
;     ...
;         } else if (tile < 64) {
; #pragma unroll
;             for (int ai = 0; ai < 2; ++ai) {
;                 const size_t cb = ((size_t)(bb * 64 + nb + 2 * ai) * 16 + (tile - 48));
;                 bf16_t* gp = (bf16_t*)(ws + WS_GZ) + cb * 8192 + fr * 128 + c8;
; #pragma unroll
;                 for (int m = 0; m < 4; ++m) {
;                     float y[8];
; #pragma unroll
;                     for (int n = 0; n < 2; ++n)
; #pragma unroll
;                         for (int j = 0; j < 4; ++j) { const float og = acc[ai][0][m][n][j], zz = acc[ai][1][m][n][j]; y[4 * n + j] = fsigmoid(og) * zz * fsigmoid(zz); }
;                     *(u32x4*)(gp + m * 2048) = (u32x4){pk2(y[0], y[1]), pk2(y[2], y[3]), pk2(y[4], y[5]), pk2(y[6], y[7])};
;                 }
;             }
	v_cvt_pk_bf16_f32 v142, v140, v141
	v_add_co_u32_e32 v140, vcc, s79, v138
	v_cvt_pk_bf16_f32 v143, v144, v145
	v_cvt_pk_bf16_f32 v144, v146, v147
	v_cvt_pk_bf16_f32 v145, v148, v149
	v_addc_co_u32_e32 v141, vcc, 0, v139, vcc
	v_add_f32_e32 v135, 1.0, v135
	global_store_dwordx4 v[140:141], v[142:145], off offset:-4096 nt
	s_nop 1
	v_rcp_f32_e32 v142, v135
	v_mul_f32_e32 v135, 0xbfb8aa3b, v88
	v_exp_f32_e32 v135, v135
	s_nop 0
	v_add_f32_e32 v135, 1.0, v135
	v_rcp_f32_e32 v144, v135
	v_mul_f32_e32 v135, 0xbfb8aa3b, v93
	v_exp_f32_e32 v135, v135
	s_nop 0
	v_add_f32_e32 v135, 1.0, v135
	v_rcp_f32_e32 v143, v135
	v_mul_f32_e32 v135, 0xbfb8aa3b, v89
	v_exp_f32_e32 v135, v135
	v_pk_mul_f32 v[142:143], v[142:143], v[88:89]
	v_add_f32_e32 v135, 1.0, v135
	v_rcp_f32_e32 v145, v135
	v_mul_f32_e32 v135, 0xbfb8aa3b, v94
	v_exp_f32_e32 v135, v135
	v_pk_mul_f32 v[142:143], v[142:143], v[144:145]
	s_nop 0
	v_cvt_pk_bf16_f32 v142, v142, v143
	v_add_f32_e32 v135, 1.0, v135
	v_rcp_f32_e32 v144, v135
	v_mul_f32_e32 v135, 0xbfb8aa3b, v90
	v_exp_f32_e32 v135, v135
	s_nop 0
	v_add_f32_e32 v135, 1.0, v135
	v_rcp_f32_e32 v146, v135
	v_mul_f32_e32 v135, 0xbfb8aa3b, v95
	v_exp_f32_e32 v135, v135
	s_nop 0
	v_add_f32_e32 v135, 1.0, v135
	v_rcp_f32_e32 v145, v135
	v_mul_f32_e32 v135, 0xbfb8aa3b, v91
	v_exp_f32_e32 v135, v135
	v_pk_mul_f32 v[144:145], v[144:145], v[90:91]
	v_add_f32_e32 v135, 1.0, v135
	v_rcp_f32_e32 v147, v135
	v_mul_f32_e32 v135, 0xbfb8aa3b, v84
	v_exp_f32_e32 v135, v135
	v_pk_mul_f32 v[144:145], v[144:145], v[146:147]
	s_nop 0
	v_cvt_pk_bf16_f32 v143, v144, v145
	v_add_f32_e32 v135, 1.0, v135
	v_rcp_f32_e32 v146, v135
	v_mul_f32_e32 v135, 0xbfb8aa3b, v80
	v_exp_f32_e32 v135, v135
	s_nop 0
	v_add_f32_e32 v135, 1.0, v135
	v_rcp_f32_e32 v148, v135
	v_mul_f32_e32 v135, 0xbfb8aa3b, v85
	v_exp_f32_e32 v135, v135
	s_nop 0
	v_add_f32_e32 v135, 1.0, v135
	v_rcp_f32_e32 v147, v135
	v_mul_f32_e32 v135, 0xbfb8aa3b, v81
	v_exp_f32_e32 v135, v135
	v_pk_mul_f32 v[146:147], v[146:147], v[80:81]
	v_add_f32_e32 v135, 1.0, v135
	v_rcp_f32_e32 v149, v135
	v_mul_f32_e32 v135, 0xbfb8aa3b, v86
	v_exp_f32_e32 v135, v135
	v_pk_mul_f32 v[146:147], v[146:147], v[148:149]
	s_nop 0
	v_cvt_pk_bf16_f32 v144, v146, v147
	v_add_f32_e32 v135, 1.0, v135
	v_rcp_f32_e32 v148, v135
	v_mul_f32_e32 v135, 0xbfb8aa3b, v82
	v_exp_f32_e32 v135, v135
	s_nop 0
	v_add_f32_e32 v135, 1.0, v135
	v_rcp_f32_e32 v150, v135
	v_mul_f32_e32 v135, 0xbfb8aa3b, v87
	v_exp_f32_e32 v135, v135
	s_nop 0
	v_add_f32_e32 v135, 1.0, v135
	v_rcp_f32_e32 v149, v135
	v_mul_f32_e32 v135, 0xbfb8aa3b, v83
	v_exp_f32_e32 v135, v135
	v_pk_mul_f32 v[148:149], v[148:149], v[82:83]
	v_add_f32_e32 v135, 1.0, v135
	v_rcp_f32_e32 v151, v135
	v_mul_f32_e32 v135, 0xbfb8aa3b, v76
	v_exp_f32_e32 v135, v135
	v_pk_mul_f32 v[148:149], v[148:149], v[150:151]
	s_nop 0
	v_cvt_pk_bf16_f32 v145, v148, v149
	v_add_f32_e32 v135, 1.0, v135
	global_store_dwordx4 v[140:141], v[142:145], off nt
	v_rcp_f32_e32 v140, v135
	v_mul_f32_e32 v135, 0xbfb8aa3b, v72
	v_exp_f32_e32 v135, v135
	s_nop 0
	v_add_f32_e32 v135, 1.0, v135
	v_rcp_f32_e32 v142, v135
	v_mul_f32_e32 v135, 0xbfb8aa3b, v77
	v_exp_f32_e32 v135, v135
	s_nop 0
	v_add_f32_e32 v135, 1.0, v135
	v_rcp_f32_e32 v141, v135
	v_mul_f32_e32 v135, 0xbfb8aa3b, v73
	v_exp_f32_e32 v135, v135
	v_pk_mul_f32 v[140:141], v[140:141], v[72:73]
	v_add_f32_e32 v135, 1.0, v135
	v_rcp_f32_e32 v143, v135
	v_mul_f32_e32 v135, 0xbfb8aa3b, v78
	v_exp_f32_e32 v135, v135
	v_pk_mul_f32 v[140:141], v[140:141], v[142:143]
	s_nop 0
	v_cvt_pk_bf16_f32 v140, v140, v141
	v_add_f32_e32 v135, 1.0, v135
	v_rcp_f32_e32 v142, v135
	v_mul_f32_e32 v135, 0xbfb8aa3b, v74
	v_exp_f32_e32 v135, v135
	s_nop 0
	v_add_f32_e32 v135, 1.0, v135
	v_rcp_f32_e32 v144, v135
	v_mul_f32_e32 v135, 0xbfb8aa3b, v79
	v_exp_f32_e32 v135, v135
	s_nop 0
	v_add_f32_e32 v135, 1.0, v135
	v_rcp_f32_e32 v143, v135
	v_mul_f32_e32 v135, 0xbfb8aa3b, v75
	v_exp_f32_e32 v135, v135
	v_pk_mul_f32 v[142:143], v[142:143], v[74:75]
	v_add_f32_e32 v135, 1.0, v135
	v_rcp_f32_e32 v145, v135
	v_mul_f32_e32 v135, 0xbfb8aa3b, v68
	v_exp_f32_e32 v135, v135
	v_pk_mul_f32 v[142:143], v[142:143], v[144:145]
	s_nop 0
	v_cvt_pk_bf16_f32 v141, v142, v143
	v_add_f32_e32 v135, 1.0, v135
	v_rcp_f32_e32 v144, v135
	v_mul_f32_e32 v135, 0xbfb8aa3b, v64
	v_exp_f32_e32 v135, v135
	s_nop 0
	v_add_f32_e32 v135, 1.0, v135
	v_rcp_f32_e32 v146, v135
	v_mul_f32_e32 v135, 0xbfb8aa3b, v69
	v_exp_f32_e32 v135, v135
	s_nop 0
	v_add_f32_e32 v135, 1.0, v135
	v_rcp_f32_e32 v145, v135
	v_mul_f32_e32 v135, 0xbfb8aa3b, v65
	v_exp_f32_e32 v135, v135
	v_pk_mul_f32 v[144:145], v[144:145], v[64:65]
	v_add_f32_e32 v135, 1.0, v135
	v_rcp_f32_e32 v147, v135
	v_mul_f32_e32 v135, 0xbfb8aa3b, v70
	v_exp_f32_e32 v135, v135
	v_pk_mul_f32 v[144:145], v[144:145], v[146:147]
	s_nop 0
	v_cvt_pk_bf16_f32 v142, v144, v145
	v_add_f32_e32 v135, 1.0, v135
	v_rcp_f32_e32 v146, v135
	v_mul_f32_e32 v135, 0xbfb8aa3b, v66
	v_exp_f32_e32 v135, v135
	v_add_co_u32_e32 v144, vcc, s62, v138
	v_add_f32_e32 v135, 1.0, v135
	v_rcp_f32_e32 v148, v135
	v_mul_f32_e32 v135, 0xbfb8aa3b, v71
	v_exp_f32_e32 v135, v135
	v_addc_co_u32_e32 v145, vcc, 0, v139, vcc
	v_add_f32_e32 v135, 1.0, v135
	v_rcp_f32_e32 v147, v135
	v_mul_f32_e32 v135, 0xbfb8aa3b, v67
	v_exp_f32_e32 v135, v135
	v_pk_mul_f32 v[146:147], v[146:147], v[66:67]
	v_add_f32_e32 v135, 1.0, v135
	v_rcp_f32_e32 v149, v135
	v_mul_f32_e32 v135, 0xbfb8aa3b, v60
	v_exp_f32_e32 v135, v135
	v_pk_mul_f32 v[146:147], v[146:147], v[148:149]
	s_nop 0
	v_cvt_pk_bf16_f32 v143, v146, v147
	v_add_f32_e32 v135, 1.0, v135
	global_store_dwordx4 v[144:145], v[140:143], off nt
	s_nop 1
	v_rcp_f32_e32 v140, v135
; __device__ __forceinline__ unsigned pk2(float lo, float hi) { return __builtin_bit_cast(unsigned, __builtin_convertvector((f32x2){lo, hi}, bf16x2_t)); }
; __device__ __forceinline__ float fsigmoid(float x) { return __builtin_amdgcn_rcpf(1.0f + fexp(-x)); }
;     __device__ __forceinline__ void operator()(f32x4 (&acc)[2][2][4][2], const pg8::Unit& u, int wr, int wc, int fr, int fq) const {
;     ...
;         } else if (tile < 64) {
; #pragma unroll
;             for (int ai = 0; ai < 2; ++ai) {
;                 const size_t cb = ((size_t)(bb * 64 + nb + 2 * ai) * 16 + (tile - 48));
;                 bf16_t* gp = (bf16_t*)(ws + WS_GZ) + cb * 8192 + fr * 128 + c8;
; #pragma unroll
;                 for (int m = 0; m < 4; ++m) {
;                     float y[8];
; #pragma unroll
;                     for (int n = 0; n < 2; ++n)
; #pragma unroll
;                         for (int j = 0; j < 4; ++j) { const float og = acc[ai][0][m][n][j], zz = acc[ai][1][m][n][j]; y[4 * n + j] = fsigmoid(og) * zz * fsigmoid(zz); }
;                     *(u32x4*)(gp + m * 2048) = (u32x4){pk2(y[0], y[1]), pk2(y[2], y[3]), pk2(y[4], y[5]), pk2(y[6], y[7])};
;                 }
;             }
	v_mul_f32_e32 v135, 0xbfb8aa3b, v56
	v_exp_f32_e32 v135, v135
	s_nop 0
	v_add_f32_e32 v135, 1.0, v135
	v_rcp_f32_e32 v142, v135
	v_mul_f32_e32 v135, 0xbfb8aa3b, v61
	v_exp_f32_e32 v135, v135
	s_nop 0
	v_add_f32_e32 v135, 1.0, v135
	v_rcp_f32_e32 v141, v135
	v_mul_f32_e32 v135, 0xbfb8aa3b, v57
	v_exp_f32_e32 v135, v135
	v_pk_mul_f32 v[140:141], v[140:141], v[56:57]
	v_add_f32_e32 v135, 1.0, v135
	v_rcp_f32_e32 v143, v135
	v_mul_f32_e32 v135, 0xbfb8aa3b, v62
	v_exp_f32_e32 v135, v135
	v_pk_mul_f32 v[140:141], v[140:141], v[142:143]
	v_add_f32_e32 v135, 1.0, v135
	v_rcp_f32_e32 v142, v135
	v_mul_f32_e32 v135, 0xbfb8aa3b, v58
	v_exp_f32_e32 v135, v135
	s_nop 0
	v_add_f32_e32 v135, 1.0, v135
	v_rcp_f32_e32 v144, v135
	v_mul_f32_e32 v135, 0xbfb8aa3b, v63
	v_exp_f32_e32 v135, v135
	s_nop 0
	v_add_f32_e32 v135, 1.0, v135
	v_rcp_f32_e32 v143, v135
	v_mul_f32_e32 v135, 0xbfb8aa3b, v59
	v_exp_f32_e32 v135, v135
	v_pk_mul_f32 v[142:143], v[142:143], v[58:59]
	v_add_f32_e32 v135, 1.0, v135
	v_rcp_f32_e32 v145, v135
	v_mul_f32_e32 v135, 0xbfb8aa3b, v52
	v_exp_f32_e32 v135, v135
	v_pk_mul_f32 v[144:145], v[142:143], v[144:145]
	v_add_f32_e32 v135, 1.0, v135
	v_rcp_f32_e32 v142, v135
	v_mul_f32_e32 v135, 0xbfb8aa3b, v48
	v_exp_f32_e32 v135, v135
	s_nop 0
	v_add_f32_e32 v135, 1.0, v135
	v_rcp_f32_e32 v146, v135
	v_mul_f32_e32 v135, 0xbfb8aa3b, v53
	v_exp_f32_e32 v135, v135
	s_nop 0
	v_add_f32_e32 v135, 1.0, v135
	v_rcp_f32_e32 v143, v135
	v_mul_f32_e32 v135, 0xbfb8aa3b, v49
	v_exp_f32_e32 v135, v135
	v_pk_mul_f32 v[142:143], v[142:143], v[48:49]
	v_add_f32_e32 v135, 1.0, v135
	v_rcp_f32_e32 v147, v135
	v_mul_f32_e32 v135, 0xbfb8aa3b, v54
	v_exp_f32_e32 v135, v135
	v_pk_mul_f32 v[146:147], v[142:143], v[146:147]
	v_add_f32_e32 v135, 1.0, v135
	v_rcp_f32_e32 v142, v135
	v_mul_f32_e32 v135, 0xbfb8aa3b, v50
	v_exp_f32_e32 v135, v135
	s_nop 0
	v_add_f32_e32 v135, 1.0, v135
	v_rcp_f32_e32 v148, v135
	v_mul_f32_e32 v135, 0xbfb8aa3b, v55
	v_exp_f32_e32 v135, v135
	s_nop 0
	v_add_f32_e32 v135, 1.0, v135
	v_rcp_f32_e32 v143, v135
	v_mul_f32_e32 v135, 0xbfb8aa3b, v51
	v_exp_f32_e32 v135, v135
	v_pk_mul_f32 v[142:143], v[142:143], v[50:51]
	v_add_f32_e32 v135, 1.0, v135
	v_rcp_f32_e32 v149, v135
	v_mul_f32_e32 v135, 0xbfb8aa3b, v44
	v_exp_f32_e32 v135, v135
	v_pk_mul_f32 v[148:149], v[142:143], v[148:149]
	v_cvt_pk_bf16_f32 v142, v140, v141
	v_add_co_u32_e32 v140, vcc, s3, v138
	v_cvt_pk_bf16_f32 v143, v144, v145
	v_cvt_pk_bf16_f32 v144, v146, v147
	v_cvt_pk_bf16_f32 v145, v148, v149
	v_addc_co_u32_e32 v141, vcc, 0, v139, vcc
	v_add_f32_e32 v135, 1.0, v135
	global_store_dwordx4 v[140:141], v[142:145], off offset:-4096 nt
	s_mov_b32 s3, 0x82000
	s_nop 0
	v_rcp_f32_e32 v142, v135
	v_mul_f32_e32 v135, 0xbfb8aa3b, v40
	v_exp_f32_e32 v135, v135
	s_nop 0
	v_add_f32_e32 v135, 1.0, v135
	v_rcp_f32_e32 v144, v135
	v_mul_f32_e32 v135, 0xbfb8aa3b, v45
	v_exp_f32_e32 v135, v135
	s_nop 0
	v_add_f32_e32 v135, 1.0, v135
	v_rcp_f32_e32 v143, v135
	v_mul_f32_e32 v135, 0xbfb8aa3b, v41
	v_exp_f32_e32 v135, v135
	v_pk_mul_f32 v[142:143], v[142:143], v[40:41]
	v_add_f32_e32 v135, 1.0, v135
	v_rcp_f32_e32 v145, v135
	v_mul_f32_e32 v135, 0xbfb8aa3b, v46
	v_exp_f32_e32 v135, v135
	v_pk_mul_f32 v[142:143], v[142:143], v[144:145]
	s_nop 0
	v_cvt_pk_bf16_f32 v142, v142, v143
	v_add_f32_e32 v135, 1.0, v135
	v_rcp_f32_e32 v144, v135
	v_mul_f32_e32 v135, 0xbfb8aa3b, v42
	v_exp_f32_e32 v135, v135
	s_nop 0
	v_add_f32_e32 v135, 1.0, v135
	v_rcp_f32_e32 v146, v135
	v_mul_f32_e32 v135, 0xbfb8aa3b, v47
	v_exp_f32_e32 v135, v135
	s_nop 0
	v_add_f32_e32 v135, 1.0, v135
	v_rcp_f32_e32 v145, v135
	v_mul_f32_e32 v135, 0xbfb8aa3b, v43
	v_exp_f32_e32 v135, v135
	v_pk_mul_f32 v[144:145], v[144:145], v[42:43]
	v_add_f32_e32 v135, 1.0, v135
	v_rcp_f32_e32 v147, v135
	v_mul_f32_e32 v135, 0xbfb8aa3b, v36
	v_exp_f32_e32 v135, v135
	v_pk_mul_f32 v[144:145], v[144:145], v[146:147]
	s_nop 0
	v_cvt_pk_bf16_f32 v143, v144, v145
	v_add_f32_e32 v135, 1.0, v135
	v_rcp_f32_e32 v146, v135
	v_mul_f32_e32 v135, 0xbfb8aa3b, v32
	v_exp_f32_e32 v135, v135
	s_nop 0
	v_add_f32_e32 v135, 1.0, v135
	v_rcp_f32_e32 v148, v135
	v_mul_f32_e32 v135, 0xbfb8aa3b, v37
	v_exp_f32_e32 v135, v135
	s_nop 0
	v_add_f32_e32 v135, 1.0, v135
	v_rcp_f32_e32 v147, v135
	v_mul_f32_e32 v135, 0xbfb8aa3b, v33
	v_exp_f32_e32 v135, v135
	v_pk_mul_f32 v[146:147], v[146:147], v[32:33]
	v_add_f32_e32 v135, 1.0, v135
	v_rcp_f32_e32 v149, v135
	v_mul_f32_e32 v135, 0xbfb8aa3b, v38
	v_exp_f32_e32 v135, v135
	v_pk_mul_f32 v[146:147], v[146:147], v[148:149]
	s_nop 0
	v_cvt_pk_bf16_f32 v144, v146, v147
	v_add_f32_e32 v135, 1.0, v135
	v_rcp_f32_e32 v148, v135
	v_mul_f32_e32 v135, 0xbfb8aa3b, v34
	v_exp_f32_e32 v135, v135
	s_nop 0
	v_add_f32_e32 v135, 1.0, v135
	v_rcp_f32_e32 v150, v135
	v_mul_f32_e32 v135, 0xbfb8aa3b, v39
	v_exp_f32_e32 v135, v135
	s_nop 0
	v_add_f32_e32 v135, 1.0, v135
	v_rcp_f32_e32 v149, v135
	v_mul_f32_e32 v135, 0xbfb8aa3b, v35
	v_exp_f32_e32 v135, v135
	v_pk_mul_f32 v[148:149], v[148:149], v[34:35]
	v_add_f32_e32 v135, 1.0, v135
	v_rcp_f32_e32 v151, v135
	v_mul_f32_e32 v135, 0xbfb8aa3b, v28
	v_exp_f32_e32 v135, v135
	v_pk_mul_f32 v[148:149], v[148:149], v[150:151]
	s_nop 0
	v_cvt_pk_bf16_f32 v145, v148, v149
	v_add_f32_e32 v135, 1.0, v135
	global_store_dwordx4 v[140:141], v[142:145], off nt
; __device__ __forceinline__ unsigned pk2(float lo, float hi) { return __builtin_bit_cast(unsigned, __builtin_convertvector((f32x2){lo, hi}, bf16x2_t)); }
; __device__ __forceinline__ float fsigmoid(float x) { return __builtin_amdgcn_rcpf(1.0f + fexp(-x)); }
;     __device__ __forceinline__ void operator()(f32x4 (&acc)[2][2][4][2], const pg8::Unit& u, int wr, int wc, int fr, int fq) const {
;     ...
;         } else if (tile < 64) {
; #pragma unroll
;             for (int ai = 0; ai < 2; ++ai) {
;                 const size_t cb = ((size_t)(bb * 64 + nb + 2 * ai) * 16 + (tile - 48));
;                 bf16_t* gp = (bf16_t*)(ws + WS_GZ) + cb * 8192 + fr * 128 + c8;
; #pragma unroll
;                 for (int m = 0; m < 4; ++m) {
;                     float y[8];
; #pragma unroll
;                     for (int n = 0; n < 2; ++n)
; #pragma unroll
;                         for (int j = 0; j < 4; ++j) { const float og = acc[ai][0][m][n][j], zz = acc[ai][1][m][n][j]; y[4 * n + j] = fsigmoid(og) * zz * fsigmoid(zz); }
;                     *(u32x4*)(gp + m * 2048) = (u32x4){pk2(y[0], y[1]), pk2(y[2], y[3]), pk2(y[4], y[5]), pk2(y[6], y[7])};
;                 }
;             }
	v_rcp_f32_e32 v140, v135
	v_mul_f32_e32 v135, 0xbfb8aa3b, v24
	v_exp_f32_e32 v135, v135
	s_nop 0
	v_add_f32_e32 v135, 1.0, v135
	v_rcp_f32_e32 v142, v135
	v_mul_f32_e32 v135, 0xbfb8aa3b, v29
	v_exp_f32_e32 v135, v135
	s_nop 0
	v_add_f32_e32 v135, 1.0, v135
	v_rcp_f32_e32 v141, v135
	v_mul_f32_e32 v135, 0xbfb8aa3b, v25
	v_exp_f32_e32 v135, v135
	v_pk_mul_f32 v[140:141], v[140:141], v[24:25]
	v_add_f32_e32 v135, 1.0, v135
	v_rcp_f32_e32 v143, v135
	v_mul_f32_e32 v135, 0xbfb8aa3b, v30
	v_exp_f32_e32 v135, v135
	v_pk_mul_f32 v[140:141], v[140:141], v[142:143]
	s_nop 0
	v_cvt_pk_bf16_f32 v140, v140, v141
	v_add_f32_e32 v135, 1.0, v135
	v_rcp_f32_e32 v142, v135
	v_mul_f32_e32 v135, 0xbfb8aa3b, v26
	v_exp_f32_e32 v135, v135
	s_nop 0
	v_add_f32_e32 v135, 1.0, v135
	v_rcp_f32_e32 v144, v135
	v_mul_f32_e32 v135, 0xbfb8aa3b, v31
	v_exp_f32_e32 v135, v135
	s_nop 0
	v_add_f32_e32 v135, 1.0, v135
	v_rcp_f32_e32 v143, v135
	v_mul_f32_e32 v135, 0xbfb8aa3b, v27
	v_exp_f32_e32 v135, v135
	v_pk_mul_f32 v[142:143], v[142:143], v[26:27]
	v_add_f32_e32 v135, 1.0, v135
	v_rcp_f32_e32 v145, v135
	v_mul_f32_e32 v135, 0xbfb8aa3b, v20
	v_exp_f32_e32 v135, v135
	v_pk_mul_f32 v[142:143], v[142:143], v[144:145]
	s_nop 0
	v_cvt_pk_bf16_f32 v141, v142, v143
	v_add_f32_e32 v135, 1.0, v135
	v_rcp_f32_e32 v144, v135
	v_mul_f32_e32 v135, 0xbfb8aa3b, v16
	v_exp_f32_e32 v135, v135
	s_nop 0
	v_add_f32_e32 v135, 1.0, v135
	v_rcp_f32_e32 v146, v135
	v_mul_f32_e32 v135, 0xbfb8aa3b, v21
	v_exp_f32_e32 v135, v135
	s_nop 0
	v_add_f32_e32 v135, 1.0, v135
	v_rcp_f32_e32 v145, v135
	v_mul_f32_e32 v135, 0xbfb8aa3b, v17
	v_exp_f32_e32 v135, v135
	v_pk_mul_f32 v[144:145], v[144:145], v[16:17]
	v_add_f32_e32 v135, 1.0, v135
	v_rcp_f32_e32 v147, v135
	v_mul_f32_e32 v135, 0xbfb8aa3b, v22
	v_exp_f32_e32 v135, v135
	v_pk_mul_f32 v[144:145], v[144:145], v[146:147]
	s_nop 0
	v_cvt_pk_bf16_f32 v142, v144, v145
	v_add_f32_e32 v135, 1.0, v135
	v_rcp_f32_e32 v146, v135
	v_mul_f32_e32 v135, 0xbfb8aa3b, v18
	v_exp_f32_e32 v135, v135
	v_add_co_u32_e32 v144, vcc, s3, v138
	v_add_f32_e32 v135, 1.0, v135
	v_rcp_f32_e32 v148, v135
	v_mul_f32_e32 v135, 0xbfb8aa3b, v23
	v_exp_f32_e32 v135, v135
	v_addc_co_u32_e32 v145, vcc, 0, v139, vcc
	v_add_co_u32_e32 v138, vcc, 0x83000, v138
	v_add_f32_e32 v135, 1.0, v135
	v_rcp_f32_e32 v147, v135
	v_mul_f32_e32 v135, 0xbfb8aa3b, v19
	v_exp_f32_e32 v135, v135
	v_addc_co_u32_e32 v139, vcc, 0, v139, vcc
	v_pk_mul_f32 v[146:147], v[146:147], v[18:19]
	v_add_f32_e32 v135, 1.0, v135
	v_rcp_f32_e32 v149, v135
	v_mul_f32_e32 v135, 0xbfb8aa3b, v12
	v_exp_f32_e32 v135, v135
	v_pk_mul_f32 v[146:147], v[146:147], v[148:149]
	s_nop 0
	v_cvt_pk_bf16_f32 v143, v146, v147
	v_add_f32_e32 v135, 1.0, v135
	global_store_dwordx4 v[144:145], v[140:143], off nt
	s_nop 1
	v_rcp_f32_e32 v140, v135
	v_mul_f32_e32 v135, 0xbfb8aa3b, v8
	v_exp_f32_e32 v135, v135
	s_nop 0
	v_add_f32_e32 v135, 1.0, v135
	v_rcp_f32_e32 v142, v135
	v_mul_f32_e32 v135, 0xbfb8aa3b, v13
	v_exp_f32_e32 v135, v135
	s_nop 0
	v_add_f32_e32 v135, 1.0, v135
	v_rcp_f32_e32 v141, v135
	v_mul_f32_e32 v135, 0xbfb8aa3b, v9
	v_exp_f32_e32 v135, v135
	v_pk_mul_f32 v[140:141], v[140:141], v[8:9]
	v_add_f32_e32 v135, 1.0, v135
	v_rcp_f32_e32 v143, v135
	v_mul_f32_e32 v135, 0xbfb8aa3b, v14
	v_exp_f32_e32 v135, v135
	v_pk_mul_f32 v[140:141], v[140:141], v[142:143]
	s_nop 0
	v_cvt_pk_bf16_f32 v140, v140, v141
	v_add_f32_e32 v135, 1.0, v135
	v_rcp_f32_e32 v142, v135
	v_mul_f32_e32 v135, 0xbfb8aa3b, v10
	v_exp_f32_e32 v135, v135
	s_nop 0
	v_add_f32_e32 v135, 1.0, v135
	v_rcp_f32_e32 v144, v135
	v_mul_f32_e32 v135, 0xbfb8aa3b, v15
	v_exp_f32_e32 v135, v135
	s_nop 0
	v_add_f32_e32 v135, 1.0, v135
	v_rcp_f32_e32 v143, v135
	v_mul_f32_e32 v135, 0xbfb8aa3b, v11
	v_exp_f32_e32 v135, v135
	v_pk_mul_f32 v[142:143], v[142:143], v[10:11]
	v_add_f32_e32 v135, 1.0, v135
	v_rcp_f32_e32 v145, v135
	v_mul_f32_e32 v135, 0xbfb8aa3b, v4
	v_exp_f32_e32 v135, v135
	v_pk_mul_f32 v[142:143], v[142:143], v[144:145]
	s_nop 0
	v_cvt_pk_bf16_f32 v141, v142, v143
	v_add_f32_e32 v135, 1.0, v135
	v_rcp_f32_e32 v144, v135
	v_mul_f32_e32 v135, 0xbfb8aa3b, v0
	v_exp_f32_e32 v135, v135
	s_nop 0
	v_add_f32_e32 v135, 1.0, v135
	v_rcp_f32_e32 v146, v135
	v_mul_f32_e32 v135, 0xbfb8aa3b, v5
	v_exp_f32_e32 v135, v135
	s_nop 0
	v_add_f32_e32 v135, 1.0, v135
	v_rcp_f32_e32 v145, v135
	v_mul_f32_e32 v135, 0xbfb8aa3b, v1
	v_exp_f32_e32 v135, v135
	v_pk_mul_f32 v[144:145], v[144:145], v[0:1]
	v_add_f32_e32 v135, 1.0, v135
	v_rcp_f32_e32 v147, v135
	v_mul_f32_e32 v135, 0xbfb8aa3b, v6
	v_exp_f32_e32 v135, v135
	v_pk_mul_f32 v[144:145], v[144:145], v[146:147]
	s_nop 0
	v_cvt_pk_bf16_f32 v142, v144, v145
	v_add_f32_e32 v135, 1.0, v135
	v_rcp_f32_e32 v146, v135
	v_mul_f32_e32 v135, 0xbfb8aa3b, v2
	v_exp_f32_e32 v135, v135
	s_nop 0
	v_add_f32_e32 v135, 1.0, v135
	v_rcp_f32_e32 v148, v135
	v_mul_f32_e32 v135, 0xbfb8aa3b, v7
	v_exp_f32_e32 v135, v135
	s_nop 0
	v_add_f32_e32 v135, 1.0, v135
	v_rcp_f32_e32 v147, v135
	v_mul_f32_e32 v135, 0xbfb8aa3b, v3
	v_exp_f32_e32 v135, v135
	v_pk_mul_f32 v[146:147], v[146:147], v[2:3]
	v_add_f32_e32 v135, 1.0, v135
	v_rcp_f32_e32 v149, v135
	s_nop 0
	v_pk_mul_f32 v[146:147], v[146:147], v[148:149]
	s_nop 0
	v_cvt_pk_bf16_f32 v143, v146, v147
	global_store_dwordx4 v[138:139], v[140:143], off nt

; __device__ __forceinline__ unsigned pk2(float lo, float hi) { return __builtin_bit_cast(unsigned, __builtin_convertvector((f32x2){lo, hi}, bf16x2_t)); }
;     __device__ __forceinline__ void operator()(f32x4 (&acc)[2][2][4][2], const pg8::Unit& u, int wr, int wc, int fr, int fq) const {
;     ...
;         } else if (tile < 48) {
; #pragma unroll
;             for (int ai = 0; ai < 2; ++ai)
; #pragma unroll
;                 for (int bj = 0; bj < 2; ++bj) {
;                     const size_t cb = ((size_t)(bb * 64 + nb + 2 * ai) * 16 + (tile - 40) * 2 + bj);
;                     bf16_t* vp = (bf16_t*)(ws + WS_VI) + cb * 8192 + fr * 128 + c8;
; #pragma unroll
;                     for (int m = 0; m < 4; ++m) { const f32x4 a0 = acc[ai][bj][m][0], a1 = acc[ai][bj][m][1];
;                         *(u32x4*)(vp + m * 2048) = (u32x4){pk2(a0[0], a0[1]), pk2(a0[2], a0[3]), pk2(a1[0], a1[1]), pk2(a1[2], a1[3])}; }
;                 }
.LBB0_141:
	s_andn2_b64 vcc, exec, s[4:5]
	s_cbranch_vccnz .LBB0_143
	s_lshl_b32 s3, s47, 6
	s_add_i32 s4, s51, s3
	s_lshl_b32 s3, s64, 1
	s_add_i32 s14, s3, 0xffffffb0
	s_ashr_i32 s5, s4, 31
	s_lshl_b64 s[4:5], s[4:5], 18
	s_lshl_b64 s[26:27], s[14:15], 14
	s_add_u32 s3, s4, s26
	v_lshlrev_b32_e32 v138, 7, v172
	s_addc_u32 s14, s5, s27
	v_readlane_b32 s26, v252, 17
	v_ashrrev_i32_e32 v139, 31, v138
	s_add_u32 s4, s26, s3
	v_ashrrev_i32_e32 v137, 31, v136
	s_addc_u32 s5, s61, s14
	v_lshlrev_b64 v[142:143], 1, v[138:139]
	v_lshl_add_u64 v[138:139], s[4:5], 0, v[142:143]
	v_lshlrev_b64 v[144:145], 1, v[136:137]
	v_lshl_add_u64 v[146:147], v[138:139], 0, v[144:145]
	v_cvt_pk_bf16_f32 v138, v124, v125
	v_cvt_pk_bf16_f32 v139, v126, v127
	v_cvt_pk_bf16_f32 v140, v116, v117
	v_cvt_pk_bf16_f32 v141, v118, v119
	v_add_co_u32_e32 v148, vcc, s79, v146
	global_store_dwordx4 v[146:147], v[138:141], off nt
	s_nop 0
	v_addc_co_u32_e32 v149, vcc, 0, v147, vcc
	v_cvt_pk_bf16_f32 v138, v108, v109
	v_cvt_pk_bf16_f32 v139, v110, v111
	v_cvt_pk_bf16_f32 v140, v100, v101
	v_cvt_pk_bf16_f32 v141, v102, v103
	v_readlane_b32 s27, v252, 24
	global_store_dwordx4 v[148:149], v[138:141], off offset:-4096 nt
	v_add_co_u32_e32 v146, vcc, s62, v146
	s_nop 0
	v_cvt_pk_bf16_f32 v138, v92, v93
	v_cvt_pk_bf16_f32 v139, v94, v95
	v_cvt_pk_bf16_f32 v140, v84, v85
	v_cvt_pk_bf16_f32 v141, v86, v87
	s_add_u32 s4, s27, s3
	global_store_dwordx4 v[148:149], v[138:141], off nt
	v_addc_co_u32_e32 v147, vcc, 0, v147, vcc
	s_nop 0
	v_cvt_pk_bf16_f32 v138, v76, v77
	v_cvt_pk_bf16_f32 v139, v78, v79
	v_cvt_pk_bf16_f32 v140, v68, v69
	v_cvt_pk_bf16_f32 v141, v70, v71
	s_addc_u32 s5, s60, s14
	global_store_dwordx4 v[146:147], v[138:141], off nt
	s_add_u32 s3, s3, 0x80000
	s_addc_u32 s14, s14, 0
	v_lshl_add_u64 v[138:139], s[4:5], 0, v[142:143]
	v_lshl_add_u64 v[146:147], v[138:139], 0, v[144:145]
	v_cvt_pk_bf16_f32 v138, v120, v121
	v_cvt_pk_bf16_f32 v139, v122, v123
	v_cvt_pk_bf16_f32 v140, v112, v113
	v_cvt_pk_bf16_f32 v141, v114, v115
	v_add_co_u32_e32 v148, vcc, s79, v146
	global_store_dwordx4 v[146:147], v[138:141], off nt
	s_nop 0
	v_addc_co_u32_e32 v149, vcc, 0, v147, vcc
	v_cvt_pk_bf16_f32 v138, v104, v105
	v_cvt_pk_bf16_f32 v139, v106, v107
	v_cvt_pk_bf16_f32 v140, v96, v97
	v_cvt_pk_bf16_f32 v141, v98, v99
	global_store_dwordx4 v[148:149], v[138:141], off offset:-4096 nt
	v_add_co_u32_e32 v146, vcc, s62, v146
	s_nop 0
	v_cvt_pk_bf16_f32 v138, v88, v89
	v_cvt_pk_bf16_f32 v139, v90, v91
	v_cvt_pk_bf16_f32 v140, v80, v81
	v_cvt_pk_bf16_f32 v141, v82, v83
	s_add_u32 s4, s26, s3
	global_store_dwordx4 v[148:149], v[138:141], off nt
	v_addc_co_u32_e32 v147, vcc, 0, v147, vcc
	s_nop 0
	v_cvt_pk_bf16_f32 v138, v72, v73
	v_cvt_pk_bf16_f32 v139, v74, v75
	v_cvt_pk_bf16_f32 v140, v64, v65
	v_cvt_pk_bf16_f32 v141, v66, v67
	s_addc_u32 s5, s61, s14
	global_store_dwordx4 v[146:147], v[138:141], off nt
	s_nop 1
	v_lshl_add_u64 v[138:139], s[4:5], 0, v[142:143]
	v_lshl_add_u64 v[146:147], v[138:139], 0, v[144:145]
	v_cvt_pk_bf16_f32 v138, v60, v61
	v_cvt_pk_bf16_f32 v139, v62, v63
	v_cvt_pk_bf16_f32 v140, v52, v53
	v_cvt_pk_bf16_f32 v141, v54, v55
	v_add_co_u32_e32 v148, vcc, s79, v146
	global_store_dwordx4 v[146:147], v[138:141], off nt
	s_nop 0
	v_addc_co_u32_e32 v149, vcc, 0, v147, vcc
	v_cvt_pk_bf16_f32 v138, v44, v45
	v_cvt_pk_bf16_f32 v139, v46, v47
	v_cvt_pk_bf16_f32 v140, v36, v37
	v_cvt_pk_bf16_f32 v141, v38, v39
	global_store_dwordx4 v[148:149], v[138:141], off offset:-4096 nt
	v_add_co_u32_e32 v146, vcc, s62, v146
	s_nop 0
	v_cvt_pk_bf16_f32 v138, v28, v29
	v_cvt_pk_bf16_f32 v139, v30, v31
	v_cvt_pk_bf16_f32 v140, v20, v21
	v_cvt_pk_bf16_f32 v141, v22, v23
	s_add_u32 s4, s27, s3
	global_store_dwordx4 v[148:149], v[138:141], off nt
	v_addc_co_u32_e32 v147, vcc, 0, v147, vcc
	s_nop 0
	v_cvt_pk_bf16_f32 v138, v12, v13
	v_cvt_pk_bf16_f32 v139, v14, v15
	v_cvt_pk_bf16_f32 v140, v4, v5
	v_cvt_pk_bf16_f32 v141, v6, v7
	s_addc_u32 s5, s60, s14
	global_store_dwordx4 v[146:147], v[138:141], off nt
	s_nop 1
	v_lshl_add_u64 v[138:139], s[4:5], 0, v[142:143]
	v_lshl_add_u64 v[142:143], v[138:139], 0, v[144:145]
	v_cvt_pk_bf16_f32 v138, v56, v57
	v_cvt_pk_bf16_f32 v139, v58, v59
	v_cvt_pk_bf16_f32 v140, v48, v49
	v_cvt_pk_bf16_f32 v141, v50, v51
	v_add_co_u32_e32 v144, vcc, s79, v142
	global_store_dwordx4 v[142:143], v[138:141], off nt
	s_nop 0
	v_addc_co_u32_e32 v145, vcc, 0, v143, vcc
	v_cvt_pk_bf16_f32 v138, v40, v41
	v_cvt_pk_bf16_f32 v139, v42, v43
	v_cvt_pk_bf16_f32 v140, v32, v33
	v_cvt_pk_bf16_f32 v141, v34, v35
	global_store_dwordx4 v[144:145], v[138:141], off offset:-4096 nt
	v_add_co_u32_e32 v142, vcc, 0x3000, v142
	s_nop 0
	v_cvt_pk_bf16_f32 v138, v24, v25
	v_cvt_pk_bf16_f32 v139, v26, v27
	v_cvt_pk_bf16_f32 v140, v16, v17
	v_cvt_pk_bf16_f32 v141, v18, v19
	global_store_dwordx4 v[144:145], v[138:141], off nt
	v_addc_co_u32_e32 v143, vcc, 0, v143, vcc
	s_nop 0
	v_cvt_pk_bf16_f32 v138, v8, v9
	v_cvt_pk_bf16_f32 v139, v10, v11
	v_cvt_pk_bf16_f32 v140, v0, v1
	v_cvt_pk_bf16_f32 v141, v2, v3
	global_store_dwordx4 v[142:143], v[138:141], off nt

; __device__ __forceinline__ float fexp(float x) { return __builtin_amdgcn_exp2f(x * 1.44269504089f); }
; __device__ __forceinline__ float fsigmoid(float x) { return __builtin_amdgcn_rcpf(1.0f + fexp(-x)); }
; __device__ __forceinline__ float row16_scan(float t) { t += dpp0<0x111>(t); t += dpp0<0x112>(t); t += dpp0<0x114>(t); t += dpp0<0x118>(t); return t; }
;     __device__ __forceinline__ void operator()(f32x4 (&acc)[2][2][4][2], const pg8::Unit& u, int wr, int wc, int fr, int fq) const {
;     ...
;                         for (int m = 0; m < 4; ++m) { const float s = fsigmoid(acc[ai][1][m][n][j]); const float f = lbv + (1.0f - lbv) * s;
;                             acc[ai][1][m][n][j] = 1.0f - f; cc[m] = row16_scan(__builtin_amdgcn_logf(f) * 0.69314718056f); }
;                         const float t0 = __shfl(cc[0], src15), t1 = __shfl(cc[1], src15), t2 = __shfl(cc[2], src15), t3 = __shfl(cc[3], src15);
;                         const float cmid = t0 + t1, clast = cmid + t2 + t3;
;                         cc[1] += t0; cc[2] += cmid; cc[3] += cmid + t2;
; #pragma unroll
;                         for (int m = 0; m < 4; ++m) { const float x = cc[m] - cmid; const float qv = acc[ai][0][m][n][j];
;                             acc[ai][0][m][n][j] = qv * fsigmoid(qv) * fexp(x); acc[ai][1][m][n][j] *= fexp(-x); }
.LBB0_161:
	s_or_b64 exec, exec, s[70:71]
	s_waitcnt lgkmcnt(0)
	v_sub_f32_e32 v168, 1.0, v162
	v_sub_f32_e32 v239, 1.0, v160
	v_sub_f32_e32 v160, v236, v167
	v_mul_f32_e32 v162, 0xbfb8aa3b, v118
	v_add_f32_e32 v171, v237, v171
	v_add_f32_e32 v237, v238, v167
	v_add_f32_e32 v238, v166, v170
	v_exp_f32_e32 v162, v162
	v_mul_f32_e32 v166, 0x3fb8aa3b, v160
	v_mul_f32_e32 v160, 0xbfb8aa3b, v160
	v_exp_f32_e32 v160, v160
	v_add_f32_e32 v162, 1.0, v162
	v_rcp_f32_e32 v162, v162
	v_exp_f32_e32 v166, v166
	v_mul_f32_e32 v160, v168, v160
	v_mul_f32_e32 v168, 0xbfb8aa3b, v102
	v_exp_f32_e32 v168, v168
	v_mul_f32_e32 v162, v118, v162
	v_mul_f32_e32 v162, v162, v166
	v_sub_f32_e32 v166, v171, v167
	v_add_f32_e32 v168, 1.0, v168
	v_rcp_f32_e32 v168, v168
	v_mul_f32_e32 v170, 0x3fb8aa3b, v166
	v_mul_f32_e32 v171, 0xbfb8aa3b, v86
	v_exp_f32_e32 v170, v170
	v_mul_f32_e32 v166, 0xbfb8aa3b, v166
	v_exp_f32_e32 v171, v171
	v_exp_f32_e32 v166, v166
	v_mul_f32_e32 v168, v102, v168
	v_sub_f32_e32 v209, 1.0, v209
	v_mul_f32_e32 v168, v168, v170
	v_sub_f32_e32 v170, v237, v167
	v_add_f32_e32 v171, 1.0, v171
	v_mul_f32_e32 v166, v209, v166
	v_rcp_f32_e32 v171, v171
	v_mul_f32_e32 v209, 0x3fb8aa3b, v170
	v_exp_f32_e32 v209, v209
	v_sub_f32_e32 v236, 1.0, v211
	v_add_f32_e32 v211, v232, v169
	v_mul_f32_e32 v169, 0xbfb8aa3b, v119
	v_exp_f32_e32 v169, v169
	v_mul_f32_e32 v171, v86, v171
	v_mul_f32_e32 v171, v171, v209
	v_sub_f32_e32 v209, v238, v167
	v_mul_f32_e32 v167, 0xbfb8aa3b, v70
	v_mul_f32_e32 v170, 0xbfb8aa3b, v170
	v_exp_f32_e32 v167, v167
	v_add_f32_e32 v232, v164, v234
	v_sub_f32_e32 v164, v215, v165
	v_add_f32_e32 v169, 1.0, v169
	v_exp_f32_e32 v170, v170
	v_rcp_f32_e32 v169, v169
	v_mul_f32_e32 v215, 0x3fb8aa3b, v164
	v_mul_f32_e32 v164, 0xbfb8aa3b, v164
	v_exp_f32_e32 v215, v215
	v_exp_f32_e32 v164, v164
	v_sub_f32_e32 v235, 1.0, v235
	v_add_f32_e32 v167, 1.0, v167
	v_mul_f32_e32 v170, v235, v170
	v_rcp_f32_e32 v167, v167
	v_mul_f32_e32 v235, 0x3fb8aa3b, v209
	v_sub_f32_e32 v212, 1.0, v212
	v_mul_f32_e32 v169, v119, v169
	v_sub_f32_e32 v211, v211, v165
	v_exp_f32_e32 v235, v235
	v_mul_f32_e32 v169, v169, v215
	v_mul_f32_e32 v164, v212, v164
	v_mul_f32_e32 v212, 0xbfb8aa3b, v103
	v_mul_f32_e32 v215, 0x3fb8aa3b, v211
	v_mul_f32_e32 v211, 0xbfb8aa3b, v211
	v_exp_f32_e32 v212, v212
	v_exp_f32_e32 v211, v211
	v_mul_f32_e32 v167, v70, v167
	v_mul_f32_e32 v167, v167, v235
	v_sub_f32_e32 v213, 1.0, v213
	v_sub_f32_e32 v235, 1.0, v214
	v_add_f32_e32 v214, v233, v165
	v_add_f32_e32 v212, 1.0, v212
	v_mul_f32_e32 v211, v213, v211
	v_sub_f32_e32 v213, v214, v165
	v_mul_f32_e32 v214, 0xbfb8aa3b, v87
	v_rcp_f32_e32 v212, v212
	v_exp_f32_e32 v214, v214
	v_exp_f32_e32 v215, v215
	v_sub_f32_e32 v233, 1.0, v216
	v_mul_f32_e32 v212, v103, v212
	v_add_f32_e32 v214, 1.0, v214
	v_mul_f32_e32 v212, v212, v215
	v_rcp_f32_e32 v214, v214
	v_mul_f32_e32 v215, 0x3fb8aa3b, v213
	v_exp_f32_e32 v215, v215
	v_add_f32_e32 v216, v229, v163
	v_mul_f32_e32 v163, 0xbfb8aa3b, v116
	v_exp_f32_e32 v163, v163
	v_mul_f32_e32 v214, v87, v214
	v_mul_f32_e32 v214, v214, v215
	v_sub_f32_e32 v215, v232, v165
	v_mul_f32_e32 v165, 0xbfb8aa3b, v71
	v_exp_f32_e32 v165, v165
	v_add_f32_e32 v229, v158, v231
	v_sub_f32_e32 v158, v220, v159
	v_add_f32_e32 v163, 1.0, v163
	v_rcp_f32_e32 v163, v163
	v_mul_f32_e32 v220, 0x3fb8aa3b, v158
	v_mul_f32_e32 v158, 0xbfb8aa3b, v158
	v_exp_f32_e32 v220, v220
	v_exp_f32_e32 v158, v158
	v_add_f32_e32 v165, 1.0, v165
	v_rcp_f32_e32 v165, v165
	v_mul_f32_e32 v232, 0x3fb8aa3b, v215
	v_sub_f32_e32 v217, 1.0, v217
	v_mul_f32_e32 v163, v116, v163
	v_sub_f32_e32 v216, v216, v159
	v_exp_f32_e32 v232, v232
	v_mul_f32_e32 v163, v163, v220
	v_mul_f32_e32 v158, v217, v158
	v_mul_f32_e32 v217, 0xbfb8aa3b, v100
	v_mul_f32_e32 v220, 0x3fb8aa3b, v216
	v_mul_f32_e32 v216, 0xbfb8aa3b, v216
	v_exp_f32_e32 v217, v217
	v_exp_f32_e32 v216, v216
	v_mul_f32_e32 v165, v71, v165
	v_mul_f32_e32 v165, v165, v232
	v_sub_f32_e32 v218, 1.0, v218
	v_sub_f32_e32 v232, 1.0, v219
	v_add_f32_e32 v219, v230, v159
	v_add_f32_e32 v217, 1.0, v217
	v_mul_f32_e32 v216, v218, v216
	v_sub_f32_e32 v218, v219, v159
	v_mul_f32_e32 v219, 0xbfb8aa3b, v84
	v_rcp_f32_e32 v217, v217
	v_exp_f32_e32 v219, v219
	v_exp_f32_e32 v220, v220
	v_sub_f32_e32 v230, 1.0, v221
	v_mul_f32_e32 v217, v100, v217
	v_add_f32_e32 v219, 1.0, v219
	v_mul_f32_e32 v217, v217, v220
	v_rcp_f32_e32 v219, v219
	v_mul_f32_e32 v220, 0x3fb8aa3b, v218
	v_exp_f32_e32 v220, v220
	v_add_f32_e32 v221, v226, v161
	v_mul_f32_e32 v161, 0xbfb8aa3b, v117
	v_exp_f32_e32 v161, v161
	v_mul_f32_e32 v219, v84, v219
	v_mul_f32_e32 v219, v219, v220
	v_sub_f32_e32 v220, v229, v159
	v_mul_f32_e32 v159, 0xbfb8aa3b, v68
	v_exp_f32_e32 v159, v159
	v_add_f32_e32 v226, v156, v228
	v_sub_f32_e32 v156, v225, v157
	v_add_f32_e32 v161, 1.0, v161
	v_rcp_f32_e32 v161, v161
	v_mul_f32_e32 v225, 0x3fb8aa3b, v156
	v_mul_f32_e32 v156, 0xbfb8aa3b, v156
	v_exp_f32_e32 v225, v225
	v_exp_f32_e32 v156, v156
	v_add_f32_e32 v159, 1.0, v159
	v_rcp_f32_e32 v159, v159
	v_mul_f32_e32 v229, 0x3fb8aa3b, v220
	v_sub_f32_e32 v222, 1.0, v222
	v_mul_f32_e32 v161, v117, v161
	v_sub_f32_e32 v221, v221, v157
	v_exp_f32_e32 v229, v229
	v_mul_f32_e32 v161, v161, v225
	v_mul_f32_e32 v156, v222, v156
	v_mul_f32_e32 v222, 0xbfb8aa3b, v101
	v_mul_f32_e32 v225, 0x3fb8aa3b, v221
	v_mul_f32_e32 v221, 0xbfb8aa3b, v221
	v_exp_f32_e32 v222, v222
	v_exp_f32_e32 v221, v221
	v_mul_f32_e32 v159, v68, v159
	v_mul_f32_e32 v159, v159, v229
	v_sub_f32_e32 v223, 1.0, v223
	v_sub_f32_e32 v229, 1.0, v224
	v_add_f32_e32 v224, v227, v157
	v_add_f32_e32 v222, 1.0, v222
	v_mul_f32_e32 v221, v223, v221
	v_sub_f32_e32 v223, v224, v157
; __device__ __forceinline__ float fexp(float x) { return __builtin_amdgcn_exp2f(x * 1.44269504089f); }
; __device__ __forceinline__ float fsigmoid(float x) { return __builtin_amdgcn_rcpf(1.0f + fexp(-x)); }
;     __device__ __forceinline__ void operator()(f32x4 (&acc)[2][2][4][2], const pg8::Unit& u, int wr, int wc, int fr, int fq) const {
;     ...
;                         for (int m = 0; m < 4; ++m) { const float x = cc[m] - cmid; const float qv = acc[ai][0][m][n][j];
;                             acc[ai][0][m][n][j] = qv * fsigmoid(qv) * fexp(x); acc[ai][1][m][n][j] *= fexp(-x); }
	v_mul_f32_e32 v224, 0xbfb8aa3b, v85
	v_rcp_f32_e32 v222, v222
	v_exp_f32_e32 v224, v224
	v_exp_f32_e32 v225, v225
	v_sub_f32_e32 v227, 1.0, v199
	v_mul_f32_e32 v222, v101, v222
	v_add_f32_e32 v224, 1.0, v224
	v_mul_f32_e32 v222, v222, v225
	v_rcp_f32_e32 v224, v224
	v_mul_f32_e32 v225, 0x3fb8aa3b, v223
	v_exp_f32_e32 v225, v225
	v_add_f32_e32 v199, v206, v155
	v_mul_f32_e32 v155, 0xbfb8aa3b, v126
	v_exp_f32_e32 v155, v155
	v_mul_f32_e32 v224, v85, v224
	v_mul_f32_e32 v224, v224, v225
	v_sub_f32_e32 v225, v226, v157
	v_mul_f32_e32 v157, 0xbfb8aa3b, v69
	v_exp_f32_e32 v157, v157
	v_add_f32_e32 v206, v150, v208
	v_sub_f32_e32 v150, v205, v151
	v_add_f32_e32 v155, 1.0, v155
	v_rcp_f32_e32 v155, v155
	v_mul_f32_e32 v205, 0x3fb8aa3b, v150
	v_mul_f32_e32 v150, 0xbfb8aa3b, v150
	v_exp_f32_e32 v205, v205
	v_exp_f32_e32 v150, v150
	v_add_f32_e32 v157, 1.0, v157
	v_rcp_f32_e32 v157, v157
	v_mul_f32_e32 v226, 0x3fb8aa3b, v225
	v_sub_f32_e32 v202, 1.0, v202
	v_mul_f32_e32 v155, v126, v155
	v_sub_f32_e32 v199, v199, v151
	v_exp_f32_e32 v226, v226
	v_mul_f32_e32 v155, v155, v205
	v_mul_f32_e32 v150, v202, v150
	v_mul_f32_e32 v202, 0xbfb8aa3b, v110
	v_mul_f32_e32 v205, 0x3fb8aa3b, v199
	v_mul_f32_e32 v199, 0xbfb8aa3b, v199
	v_exp_f32_e32 v202, v202
	v_exp_f32_e32 v199, v199
	v_mul_f32_e32 v157, v69, v157
	v_mul_f32_e32 v157, v157, v226
	v_sub_f32_e32 v203, 1.0, v203
	v_sub_f32_e32 v226, 1.0, v204
	v_add_f32_e32 v204, v207, v151
	v_add_f32_e32 v202, 1.0, v202
	v_mul_f32_e32 v199, v203, v199
	v_sub_f32_e32 v203, v204, v151
	v_mul_f32_e32 v204, 0xbfb8aa3b, v94
	v_rcp_f32_e32 v202, v202
	v_exp_f32_e32 v204, v204
	v_exp_f32_e32 v205, v205
	v_add_f32_e32 v147, v192, v147
	v_mul_f32_e32 v202, v110, v202
	v_add_f32_e32 v204, 1.0, v204
	v_mul_f32_e32 v202, v202, v205
	v_rcp_f32_e32 v204, v204
	v_mul_f32_e32 v205, 0x3fb8aa3b, v203
	v_exp_f32_e32 v205, v205
	v_add_f32_e32 v192, v193, v143
	v_mul_f32_e32 v204, v94, v204
	v_sub_f32_e32 v191, v191, v143
	v_mul_f32_e32 v204, v204, v205
	v_sub_f32_e32 v205, v206, v151
	v_mul_f32_e32 v151, 0xbfb8aa3b, v78
	v_exp_f32_e32 v151, v151
	v_mul_f32_e32 v193, 0xbfb8aa3b, v124
	v_add_f32_e32 v142, v142, v194
	v_exp_f32_e32 v193, v193
	v_mul_f32_e32 v194, 0x3fb8aa3b, v191
	v_mul_f32_e32 v191, 0xbfb8aa3b, v191
	v_exp_f32_e32 v191, v191
	v_add_f32_e32 v151, 1.0, v151
	v_add_f32_e32 v153, v200, v153
	v_add_f32_e32 v200, v201, v149
	v_add_f32_e32 v201, v148, v152
	v_mul_f32_e32 v152, 0xbfb8aa3b, v127
	v_rcp_f32_e32 v151, v151
	v_mul_f32_e32 v206, 0x3fb8aa3b, v205
	v_exp_f32_e32 v152, v152
	v_exp_f32_e32 v206, v206
	v_sub_f32_e32 v188, 1.0, v188
	v_add_f32_e32 v193, 1.0, v193
	v_rcp_f32_e32 v193, v193
	v_mul_f32_e32 v188, v188, v191
	v_mul_f32_e32 v191, 0xbfb8aa3b, v108
	v_exp_f32_e32 v194, v194
	v_exp_f32_e32 v191, v191
	v_mul_f32_e32 v151, v78, v151
	v_sub_f32_e32 v148, v198, v149
	v_add_f32_e32 v152, 1.0, v152
	v_mul_f32_e32 v151, v151, v206
	v_sub_f32_e32 v206, 1.0, v154
	v_rcp_f32_e32 v152, v152
	v_mul_f32_e32 v154, 0x3fb8aa3b, v148
	v_exp_f32_e32 v154, v154
	v_mul_f32_e32 v193, v124, v193
	v_sub_f32_e32 v147, v147, v143
	v_mul_f32_e32 v193, v193, v194
	v_add_f32_e32 v191, 1.0, v191
	v_mul_f32_e32 v194, 0x3fb8aa3b, v147
	v_mul_f32_e32 v147, 0xbfb8aa3b, v147
	v_rcp_f32_e32 v191, v191
	v_exp_f32_e32 v147, v147
	v_mul_f32_e32 v152, v127, v152
	v_exp_f32_e32 v194, v194
	v_mul_f32_e32 v152, v152, v154
	v_mul_f32_e32 v154, 0xbfb8aa3b, v111
	v_mul_f32_e32 v148, 0xbfb8aa3b, v148
	v_exp_f32_e32 v154, v154
	v_sub_f32_e32 v189, 1.0, v189
	v_exp_f32_e32 v148, v148
	v_mul_f32_e32 v191, v108, v191
	v_mul_f32_e32 v189, v189, v147
	v_sub_f32_e32 v147, v192, v143
	v_mul_f32_e32 v192, 0xbfb8aa3b, v92
	v_sub_f32_e32 v142, v142, v143
	v_mul_f32_e32 v143, 0xbfb8aa3b, v76
	v_mul_f32_e32 v191, v191, v194
	v_exp_f32_e32 v192, v192
	v_mul_f32_e32 v194, 0x3fb8aa3b, v147
	v_mul_f32_e32 v147, 0xbfb8aa3b, v147
	v_exp_f32_e32 v143, v143
	v_exp_f32_e32 v147, v147
	v_sub_f32_e32 v195, 1.0, v195
	v_sub_f32_e32 v153, v153, v149
	v_add_f32_e32 v154, 1.0, v154
	v_mul_f32_e32 v148, v195, v148
	v_rcp_f32_e32 v154, v154
	v_mul_f32_e32 v195, 0x3fb8aa3b, v153
	v_exp_f32_e32 v195, v195
	v_mul_f32_e32 v153, 0xbfb8aa3b, v153
	v_sub_f32_e32 v190, 1.0, v190
	v_add_f32_e32 v192, 1.0, v192
	v_add_f32_e32 v143, 1.0, v143
	v_exp_f32_e32 v153, v153
	v_rcp_f32_e32 v192, v192
	v_mul_f32_e32 v190, v190, v147
	v_rcp_f32_e32 v143, v143
	v_mul_f32_e32 v147, 0x3fb8aa3b, v142
	v_exp_f32_e32 v194, v194
	v_exp_f32_e32 v147, v147
	v_mul_f32_e32 v154, v111, v154
	v_sub_f32_e32 v196, 1.0, v196
	v_mul_f32_e32 v154, v154, v195
	v_sub_f32_e32 v195, v200, v149
	v_mul_f32_e32 v153, v196, v153
	v_mul_f32_e32 v196, 0xbfb8aa3b, v95
	v_mul_f32_e32 v198, 0x3fb8aa3b, v195
	v_mul_f32_e32 v195, 0xbfb8aa3b, v195
	v_mul_f32_e32 v192, v92, v192
	v_mul_f32_e32 v143, v76, v143
	v_mul_f32_e32 v142, 0xbfb8aa3b, v142
	v_add_f32_e32 v140, v140, v144
	v_sub_f32_e32 v144, v184, v141
	v_exp_f32_e32 v196, v196
	v_exp_f32_e32 v195, v195
	v_mul_f32_e32 v192, v192, v194
	v_mul_f32_e32 v194, v143, v147
	v_exp_f32_e32 v142, v142
	v_sub_f32_e32 v147, 1.0, v183
	v_mul_f32_e32 v183, 0x3fb8aa3b, v144
	v_mul_f32_e32 v144, 0xbfb8aa3b, v144
	v_exp_f32_e32 v144, v144
	v_sub_f32_e32 v197, 1.0, v197
	v_sub_f32_e32 v187, 1.0, v187
	v_add_f32_e32 v196, 1.0, v196
	v_mul_f32_e32 v195, v197, v195
	v_sub_f32_e32 v197, v201, v149
	v_mul_f32_e32 v149, 0xbfb8aa3b, v79
	v_mul_f32_e32 v187, v187, v142
	v_sub_f32_e32 v142, 1.0, v173
	v_rcp_f32_e32 v196, v196
	v_exp_f32_e32 v149, v149
	v_add_f32_e32 v145, v185, v145
	v_mul_f32_e32 v185, v142, v144
	v_mul_f32_e32 v144, 0xbfb8aa3b, v109
	v_exp_f32_e32 v198, v198
	v_exp_f32_e32 v144, v144
; __device__ __forceinline__ unsigned pk2(float lo, float hi) { return __builtin_bit_cast(unsigned, __builtin_convertvector((f32x2){lo, hi}, bf16x2_t)); }
; __device__ __forceinline__ float fexp(float x) { return __builtin_amdgcn_exp2f(x * 1.44269504089f); }
; __device__ __forceinline__ float fsigmoid(float x) { return __builtin_amdgcn_rcpf(1.0f + fexp(-x)); }
;     __device__ __forceinline__ void operator()(f32x4 (&acc)[2][2][4][2], const pg8::Unit& u, int wr, int wc, int fr, int fq) const {
;     ...
;                         for (int m = 0; m < 4; ++m) { const float x = cc[m] - cmid; const float qv = acc[ai][0][m][n][j];
;                             acc[ai][0][m][n][j] = qv * fsigmoid(qv) * fexp(x); acc[ai][1][m][n][j] *= fexp(-x); }
;                         if (fr == 0) { float* sp = (float*)(ws + WS_SCL) + cb * 384 + c8 + 4 * n + j; sp[0] = fexp(cmid); sp[128] = fexp(clast); sp[256] = fexp(clast - cmid); }
;                         asm volatile("" ::: "memory");
;                     }
;                 bf16_t* qp = (bf16_t*)(ws + WS_QI) + cb * 8192 + fr * 128 + c8; bf16_t* kp = (bf16_t*)(ws + WS_KI) + cb * 8192 + fr * 128 + c8;
; #pragma unroll
;                 for (int m = 0; m < 4; ++m) {
;                     const f32x4 a0 = acc[ai][0][m][0], a1 = acc[ai][0][m][1], b0 = acc[ai][1][m][0], b1 = acc[ai][1][m][1];
;                     *(u32x4*)(qp + m * 2048) = (u32x4){pk2(a0[0], a0[1]), pk2(a0[2], a0[3]), pk2(a1[0], a1[1]), pk2(a1[2], a1[3])};
;                     *(u32x4*)(kp + m * 2048) = (u32x4){pk2(b0[0], b0[1]), pk2(b0[2], b0[3]), pk2(b1[0], b1[1]), pk2(b1[2], b1[3])};
;                 }
	v_mul_f32_e32 v196, v95, v196
	v_add_f32_e32 v149, 1.0, v149
	v_sub_f32_e32 v142, v145, v141
	v_mul_f32_e32 v196, v196, v198
	v_rcp_f32_e32 v149, v149
	v_mul_f32_e32 v198, 0x3fb8aa3b, v197
	v_add_f32_e32 v144, 1.0, v144
	v_mul_f32_e32 v145, 0x3fb8aa3b, v142
	v_mul_f32_e32 v142, 0xbfb8aa3b, v142
	v_exp_f32_e32 v198, v198
	v_rcp_f32_e32 v144, v144
	v_exp_f32_e32 v142, v142
	v_exp_f32_e32 v145, v145
	v_mul_f32_e32 v149, v79, v149
	v_sub_f32_e32 v143, 1.0, v182
	v_add_f32_e32 v173, v186, v141
	v_mul_f32_e32 v149, v149, v198
	v_mul_f32_e32 v144, v109, v144
	v_mul_f32_e32 v198, v143, v142
	v_sub_f32_e32 v142, v173, v141
	v_mul_f32_e32 v186, v144, v145
	v_mul_f32_e32 v144, 0x3fb8aa3b, v142
	v_mul_f32_e32 v142, 0xbfb8aa3b, v142
	v_sub_f32_e32 v140, v140, v141
	v_mul_f32_e32 v141, 0xbfb8aa3b, v77
	v_exp_f32_e32 v142, v142
	v_exp_f32_e32 v141, v141
	v_mul_f32_e32 v143, 0xbfb8aa3b, v93
	v_mul_f32_e32 v182, 0xbfb8aa3b, v125
	v_exp_f32_e32 v143, v143
	v_exp_f32_e32 v182, v182
	v_mul_f32_e32 v201, v147, v142
	v_add_f32_e32 v141, 1.0, v141
	v_mul_f32_e32 v142, 0x3fb8aa3b, v140
	v_mul_f32_e32 v140, 0xbfb8aa3b, v140
	v_mul_f32_e32 v197, 0xbfb8aa3b, v197
	v_rcp_f32_e32 v141, v141
	v_exp_f32_e32 v140, v140
	v_exp_f32_e32 v197, v197
	v_add_f32_e32 v143, 1.0, v143
	v_exp_f32_e32 v142, v142
	v_add_f32_e32 v182, 1.0, v182
	v_rcp_f32_e32 v143, v143
	v_sub_f32_e32 v146, 1.0, v146
	v_rcp_f32_e32 v182, v182
	v_exp_f32_e32 v144, v144
	s_lshl_b64 s[26:27], s[68:69], 14
	v_exp_f32_e32 v183, v183
	v_mul_f32_e32 v141, v77, v141
	v_mul_f32_e32 v207, v146, v140
	v_lshlrev_b32_e32 v140, 7, v172
	s_add_u32 s34, s95, s26
	v_mul_f32_e32 v197, v206, v197
	v_mul_f32_e32 v206, v141, v142
	v_ashrrev_i32_e32 v141, 31, v140
	s_addc_u32 s35, s96, s27
	v_mul_f32_e32 v143, v93, v143
	v_lshlrev_b64 v[140:141], 1, v[140:141]
	s_add_u32 s26, s97, s26
	v_mul_f32_e32 v182, v125, v182
	v_mul_f32_e32 v200, v143, v144
	v_lshl_add_u64 v[144:145], s[34:35], 0, v[140:141]
	v_lshlrev_b64 v[142:143], 1, v[136:137]
	s_addc_u32 s27, s85, s27
	v_mul_f32_e32 v184, v182, v183
	v_lshl_add_u64 v[172:173], v[144:145], 0, v[142:143]
	v_lshl_add_u64 v[144:145], s[26:27], 0, v[140:141]
	v_lshl_add_u64 v[182:183], v[144:145], 0, v[142:143]
	v_cvt_pk_bf16_f32 v144, v193, v184
	v_cvt_pk_bf16_f32 v145, v155, v152
	v_cvt_pk_bf16_f32 v146, v163, v161
	v_cvt_pk_bf16_f32 v147, v162, v169
	v_mul_f32_e32 v213, 0xbfb8aa3b, v213
	v_mul_f32_e32 v218, 0xbfb8aa3b, v218
	v_mul_f32_e32 v223, 0xbfb8aa3b, v223
	v_mul_f32_e32 v203, 0xbfb8aa3b, v203
	global_store_dwordx4 v[172:173], v[144:147], off nt
	v_exp_f32_e32 v213, v213
	v_exp_f32_e32 v218, v218
	v_cvt_pk_bf16_f32 v144, v188, v185
	v_cvt_pk_bf16_f32 v145, v150, v148
	v_cvt_pk_bf16_f32 v146, v158, v156
	v_cvt_pk_bf16_f32 v147, v160, v164
	v_exp_f32_e32 v223, v223
	v_exp_f32_e32 v203, v203
	global_store_dwordx4 v[182:183], v[144:147], off nt
	v_mul_f32_e32 v209, 0xbfb8aa3b, v209
	v_mul_f32_e32 v215, 0xbfb8aa3b, v215
	v_cvt_pk_bf16_f32 v145, v202, v154
	v_add_co_u32_e32 v154, vcc, s79, v172
	v_mul_f32_e32 v220, 0xbfb8aa3b, v220
	s_nop 0
	v_addc_co_u32_e32 v155, vcc, 0, v173, vcc
	v_mul_f32_e32 v225, 0xbfb8aa3b, v225
	v_mul_f32_e32 v205, 0xbfb8aa3b, v205
	v_cvt_pk_bf16_f32 v144, v191, v186
	v_cvt_pk_bf16_f32 v146, v217, v222
	v_cvt_pk_bf16_f32 v147, v168, v212
	v_add_co_u32_e32 v152, vcc, s79, v182
	v_exp_f32_e32 v209, v209
	v_exp_f32_e32 v215, v215
	v_exp_f32_e32 v220, v220
	v_exp_f32_e32 v225, v225
	v_exp_f32_e32 v205, v205
	global_store_dwordx4 v[154:155], v[144:147], off offset:-4096 nt
	v_mul_f32_e32 v213, v235, v213
	v_mul_f32_e32 v218, v232, v218
	v_cvt_pk_bf16_f32 v144, v189, v198
	v_cvt_pk_bf16_f32 v145, v199, v153
	v_cvt_pk_bf16_f32 v146, v216, v221
	v_cvt_pk_bf16_f32 v147, v166, v211
	v_addc_co_u32_e32 v153, vcc, 0, v183, vcc
	v_mul_f32_e32 v223, v229, v223
	v_mul_f32_e32 v203, v226, v203
	global_store_dwordx4 v[152:153], v[144:147], off offset:-4096 nt
	v_add_co_u32_e32 v148, vcc, s62, v172
	s_nop 0
	v_cvt_pk_bf16_f32 v144, v192, v200
	v_cvt_pk_bf16_f32 v145, v204, v196
	v_cvt_pk_bf16_f32 v146, v219, v224
	v_cvt_pk_bf16_f32 v147, v171, v214
	global_store_dwordx4 v[154:155], v[144:147], off nt
	v_mul_f32_e32 v209, v239, v209
	v_mul_f32_e32 v215, v236, v215
	v_cvt_pk_bf16_f32 v144, v190, v201
	v_cvt_pk_bf16_f32 v145, v203, v195
	v_cvt_pk_bf16_f32 v146, v218, v223
	v_cvt_pk_bf16_f32 v147, v170, v213
; __device__ __forceinline__ unsigned pk2(float lo, float hi) { return __builtin_bit_cast(unsigned, __builtin_convertvector((f32x2){lo, hi}, bf16x2_t)); }
; __device__ __forceinline__ float fexp(float x) { return __builtin_amdgcn_exp2f(x * 1.44269504089f); }
; __device__ __forceinline__ float fsigmoid(float x) { return __builtin_amdgcn_rcpf(1.0f + fexp(-x)); }
; __device__ __forceinline__ float row16_scan(float t) { t += dpp0<0x111>(t); t += dpp0<0x112>(t); t += dpp0<0x114>(t); t += dpp0<0x118>(t); return t; }
;     __device__ __forceinline__ void operator()(f32x4 (&acc)[2][2][4][2], const pg8::Unit& u, int wr, int wc, int fr, int fq) const {
;     ...
;                         const float lbv = lbp[4 * n + j];
;                         float cc[4];
; #pragma unroll
;                         for (int m = 0; m < 4; ++m) { const float s = fsigmoid(acc[ai][1][m][n][j]); const float f = lbv + (1.0f - lbv) * s;
;                             acc[ai][1][m][n][j] = 1.0f - f; cc[m] = row16_scan(__builtin_amdgcn_logf(f) * 0.69314718056f); }
;                         const float t0 = __shfl(cc[0], src15), t1 = __shfl(cc[1], src15), t2 = __shfl(cc[2], src15), t3 = __shfl(cc[3], src15);
;                         const float cmid = t0 + t1, clast = cmid + t2 + t3;
;                         cc[1] += t0; cc[2] += cmid; cc[3] += cmid + t2;
; #pragma unroll
;                         for (int m = 0; m < 4; ++m) { const float x = cc[m] - cmid; const float qv = acc[ai][0][m][n][j];
;                             acc[ai][0][m][n][j] = qv * fsigmoid(qv) * fexp(x); acc[ai][1][m][n][j] *= fexp(-x); }
;                         if (fr == 0) { float* sp = (float*)(ws + WS_SCL) + cb * 384 + c8 + 4 * n + j; sp[0] = fexp(cmid); sp[128] = fexp(clast); sp[256] = fexp(clast - cmid); }
;     ...
;                     *(u32x4*)(qp + m * 2048) = (u32x4){pk2(a0[0], a0[1]), pk2(a0[2], a0[3]), pk2(a1[0], a1[1]), pk2(a1[2], a1[3])};
;                     *(u32x4*)(kp + m * 2048) = (u32x4){pk2(b0[0], b0[1]), pk2(b0[2], b0[3]), pk2(b1[0], b1[1]), pk2(b1[2], b1[3])};
	global_store_dwordx4 v[152:153], v[144:147], off nt
	v_mul_f32_e32 v220, v233, v220
	v_mul_f32_e32 v225, v230, v225
	v_cvt_pk_bf16_f32 v144, v194, v206
	v_cvt_pk_bf16_f32 v145, v151, v149
	v_cvt_pk_bf16_f32 v146, v159, v157
	v_cvt_pk_bf16_f32 v147, v167, v165
	v_addc_co_u32_e32 v149, vcc, 0, v173, vcc
	v_mul_f32_e32 v205, v227, v205
	global_store_dwordx4 v[148:149], v[144:147], off nt
	v_add_co_u32_e32 v148, vcc, s62, v182
	s_nop 0
	v_cvt_pk_bf16_f32 v144, v187, v207
	v_cvt_pk_bf16_f32 v145, v205, v197
	v_cvt_pk_bf16_f32 v146, v220, v225
	v_cvt_pk_bf16_f32 v147, v209, v215
	v_addc_co_u32_e32 v149, vcc, 0, v183, vcc
	global_store_dwordx4 v[148:149], v[144:147], off nt
	v_mov_b32_e32 v182, v242
	s_lshl_b64 s[26:27], s[66:67], 4
	v_mul_f32_e32 v145, 0xbfb8aa3b, v56
	v_exp_f32_e32 v145, v145
	s_add_u32 s3, s26, s3
	s_addc_u32 s14, s27, 0
	s_add_u32 s66, s3, 32
	v_add_f32_e32 v145, 1.0, v145
	v_rcp_f32_e32 v145, v145
	s_addc_u32 s67, s14, 0
	s_mul_i32 s3, s67, 0x600
	s_mul_hi_u32 s14, s66, 0x600
	s_add_i32 s3, s14, s3
	s_mul_i32 s14, s66, 0x600
	v_sub_f32_e32 v144, 1.0, v182
	v_fma_f32 v183, v145, v144, v182
	v_log_f32_e32 v145, v183
	s_nop 0
	v_mul_f32_e32 v146, 0x3f317218, v145
	s_nop 1
	v_mov_b32_dpp v146, v146 row_shr:1 row_mask:0xf bank_mask:0xf bound_ctrl:1
	v_fmac_f32_e32 v146, 0x3f317218, v145
	s_nop 1
	v_add_f32_dpp v145, v146, v146 row_shr:2 row_mask:0xf bank_mask:0xf bound_ctrl:1
	s_nop 1
	v_add_f32_dpp v145, v145, v145 row_shr:4 row_mask:0xf bank_mask:0xf bound_ctrl:1
	s_nop 1
	v_add_f32_dpp v184, v145, v145 row_shr:8 row_mask:0xf bank_mask:0xf bound_ctrl:1
	v_mul_f32_e32 v145, 0xbfb8aa3b, v40
	v_exp_f32_e32 v145, v145
	ds_bpermute_b32 v151, v135, v184
	v_add_f32_e32 v145, 1.0, v145
	v_rcp_f32_e32 v145, v145
	s_nop 0
	v_fma_f32 v185, v145, v144, v182
	v_log_f32_e32 v145, v185
	s_nop 0
	v_mul_f32_e32 v146, 0x3f317218, v145
	s_nop 1
	v_mov_b32_dpp v146, v146 row_shr:1 row_mask:0xf bank_mask:0xf bound_ctrl:1
	v_fmac_f32_e32 v146, 0x3f317218, v145
	s_nop 1
	v_add_f32_dpp v145, v146, v146 row_shr:2 row_mask:0xf bank_mask:0xf bound_ctrl:1
	s_nop 1
	v_add_f32_dpp v145, v145, v145 row_shr:4 row_mask:0xf bank_mask:0xf bound_ctrl:1
	s_nop 1
	v_add_f32_dpp v186, v145, v145 row_shr:8 row_mask:0xf bank_mask:0xf bound_ctrl:1
	v_mul_f32_e32 v145, 0xbfb8aa3b, v24
	v_exp_f32_e32 v145, v145
	s_nop 0
	v_add_f32_e32 v145, 1.0, v145
	v_rcp_f32_e32 v145, v145
	s_nop 0
	v_fma_f32 v190, v145, v144, v182
	v_log_f32_e32 v145, v190
	s_nop 0
	v_mul_f32_e32 v146, 0x3f317218, v145
	s_nop 1
	v_mov_b32_dpp v146, v146 row_shr:1 row_mask:0xf bank_mask:0xf bound_ctrl:1
	v_fmac_f32_e32 v146, 0x3f317218, v145
	s_nop 1
	v_add_f32_dpp v145, v146, v146 row_shr:2 row_mask:0xf bank_mask:0xf bound_ctrl:1
	s_nop 1
	v_add_f32_dpp v145, v145, v145 row_shr:4 row_mask:0xf bank_mask:0xf bound_ctrl:1
	s_nop 1
	v_add_f32_dpp v192, v145, v145 row_shr:8 row_mask:0xf bank_mask:0xf bound_ctrl:1
	v_mul_f32_e32 v145, 0xbfb8aa3b, v8
	v_exp_f32_e32 v145, v145
	ds_bpermute_b32 v148, v135, v192
	v_add_f32_e32 v145, 1.0, v145
	v_rcp_f32_e32 v145, v145
	s_nop 0
	v_fmac_f32_e32 v182, v145, v144
	v_log_f32_e32 v144, v182
	s_nop 0
	v_mul_f32_e32 v145, 0x3f317218, v144
	s_nop 1
	v_mov_b32_dpp v145, v145 row_shr:1 row_mask:0xf bank_mask:0xf bound_ctrl:1
	v_fmac_f32_e32 v145, 0x3f317218, v144
	s_nop 1
	v_add_f32_dpp v144, v145, v145 row_shr:2 row_mask:0xf bank_mask:0xf bound_ctrl:1
	ds_bpermute_b32 v145, v135, v186
	s_nop 0
	v_add_f32_dpp v150, v144, v144 row_shr:4 row_mask:0xf bank_mask:0xf bound_ctrl:1
	s_nop 1
	v_mov_b32_dpp v144, v150 row_shr:8 row_mask:0xf bank_mask:0xf bound_ctrl:1
	s_waitcnt lgkmcnt(0)
	v_pk_add_f32 v[146:147], v[150:151], v[144:145]
	ds_bpermute_b32 v144, v135, v146
	v_add_f32_e32 v195, v147, v148
	s_and_saveexec_b64 s[68:69], s[4:5]
	s_cbranch_execz .LBB0_163
	s_waitcnt lgkmcnt(0)
	v_add_f32_e32 v144, v195, v144
	v_mul_f32_e32 v145, 0x3fb8aa3b, v147
	v_readlane_b32 s26, v252, 20
	v_exp_f32_e32 v148, v145
	v_mul_f32_e32 v145, 0x3fb8aa3b, v144
	v_sub_f32_e32 v144, v144, v147
	s_add_u32 s26, s26, s14
	v_readlane_b32 s27, v252, 21
	v_exp_f32_e32 v149, v145
	v_mul_f32_e32 v144, 0x3fb8aa3b, v144
	s_addc_u32 s27, s27, s3
	v_exp_f32_e32 v150, v144
	v_lshl_add_u64 v[144:145], v[136:137], 2, s[26:27]
	global_store_dword v[144:145], v148, off
	global_store_dword v[144:145], v149, off offset:512
	global_store_dword v[144:145], v150, off offset:1024

; __device__ __forceinline__ float fexp(float x) { return __builtin_amdgcn_exp2f(x * 1.44269504089f); }
; __device__ __forceinline__ float fsigmoid(float x) { return __builtin_amdgcn_rcpf(1.0f + fexp(-x)); }
; __device__ __forceinline__ float row16_scan(float t) { t += dpp0<0x111>(t); t += dpp0<0x112>(t); t += dpp0<0x114>(t); t += dpp0<0x118>(t); return t; }
;     __device__ __forceinline__ void operator()(f32x4 (&acc)[2][2][4][2], const pg8::Unit& u, int wr, int wc, int fr, int fq) const {
;     ...
;                         for (int m = 0; m < 4; ++m) { const float s = fsigmoid(acc[ai][1][m][n][j]); const float f = lbv + (1.0f - lbv) * s;
;                             acc[ai][1][m][n][j] = 1.0f - f; cc[m] = row16_scan(__builtin_amdgcn_logf(f) * 0.69314718056f); }
;                         const float t0 = __shfl(cc[0], src15), t1 = __shfl(cc[1], src15), t2 = __shfl(cc[2], src15), t3 = __shfl(cc[3], src15);
;                         const float cmid = t0 + t1, clast = cmid + t2 + t3;
;                         cc[1] += t0; cc[2] += cmid; cc[3] += cmid + t2;
; #pragma unroll
;                         for (int m = 0; m < 4; ++m) { const float x = cc[m] - cmid; const float qv = acc[ai][0][m][n][j];
;                             acc[ai][0][m][n][j] = qv * fsigmoid(qv) * fexp(x); acc[ai][1][m][n][j] *= fexp(-x); }
.LBB0_177:
	s_or_b64 exec, exec, s[68:69]
	v_mul_f32_e32 v137, 0xbfb8aa3b, v54
	v_exp_f32_e32 v137, v137
	s_waitcnt lgkmcnt(0)
	v_sub_f32_e32 v135, 1.0, v166
	v_sub_f32_e32 v166, v237, v169
	v_add_f32_e32 v172, v168, v172
	v_add_f32_e32 v137, 1.0, v137
	v_mul_f32_e32 v168, 0x3fb8aa3b, v166
	v_mul_f32_e32 v166, 0xbfb8aa3b, v166
	v_rcp_f32_e32 v137, v137
	v_exp_f32_e32 v166, v166
	v_exp_f32_e32 v168, v168
	v_sub_f32_e32 v170, 1.0, v235
	v_sub_f32_e32 v235, 1.0, v236
	v_sub_f32_e32 v236, 1.0, v164
	v_add_f32_e32 v164, v238, v173
	v_mul_f32_e32 v137, v54, v137
	v_mul_f32_e32 v135, v135, v166
	v_sub_f32_e32 v164, v164, v169
	v_mul_f32_e32 v166, 0xbfb8aa3b, v38
	v_mul_f32_e32 v137, v137, v168
	v_exp_f32_e32 v166, v166
	v_mul_f32_e32 v168, 0x3fb8aa3b, v164
	v_mul_f32_e32 v164, 0xbfb8aa3b, v164
	v_exp_f32_e32 v164, v164
	v_add_f32_e32 v166, 1.0, v166
	v_rcp_f32_e32 v166, v166
	v_exp_f32_e32 v168, v168
	v_mul_f32_e32 v164, v170, v164
	v_mul_f32_e32 v170, 0xbfb8aa3b, v22
	v_exp_f32_e32 v170, v170
	v_add_f32_e32 v173, v239, v169
	v_mul_f32_e32 v166, v38, v166
	v_mul_f32_e32 v166, v166, v168
	v_sub_f32_e32 v168, v173, v169
	v_add_f32_e32 v170, 1.0, v170
	v_sub_f32_e32 v172, v172, v169
	v_mul_f32_e32 v169, 0xbfb8aa3b, v6
	v_rcp_f32_e32 v170, v170
	v_mul_f32_e32 v173, 0x3fb8aa3b, v168
	v_mul_f32_e32 v168, 0xbfb8aa3b, v168
	v_exp_f32_e32 v169, v169
	v_exp_f32_e32 v173, v173
	v_exp_f32_e32 v168, v168
	v_mul_f32_e32 v170, v22, v170
	v_add_f32_e32 v169, 1.0, v169
	v_mul_f32_e32 v170, v170, v173
	v_mul_f32_e32 v168, v235, v168
	v_rcp_f32_e32 v169, v169
	v_mul_f32_e32 v173, 0x3fb8aa3b, v172
	v_sub_f32_e32 v235, 1.0, v211
	v_add_f32_e32 v211, v232, v171
	v_add_f32_e32 v232, v138, v234
	v_sub_f32_e32 v138, v231, v139
	v_mul_f32_e32 v171, 0xbfb8aa3b, v55
	v_exp_f32_e32 v173, v173
	v_exp_f32_e32 v171, v171
	v_mul_f32_e32 v231, 0x3fb8aa3b, v138
	v_mul_f32_e32 v138, 0xbfb8aa3b, v138
	v_exp_f32_e32 v138, v138
	v_mul_f32_e32 v169, v6, v169
	v_mul_f32_e32 v169, v169, v173
	v_sub_f32_e32 v173, 1.0, v212
	v_add_f32_e32 v171, 1.0, v171
	v_rcp_f32_e32 v171, v171
	v_mul_f32_e32 v138, v173, v138
	v_sub_f32_e32 v173, v211, v139
	v_mul_f32_e32 v211, 0xbfb8aa3b, v39
	v_exp_f32_e32 v231, v231
	v_exp_f32_e32 v211, v211
	v_mul_f32_e32 v171, v55, v171
	v_sub_f32_e32 v212, 1.0, v213
	v_mul_f32_e32 v171, v171, v231
	v_add_f32_e32 v211, 1.0, v211
	v_mul_f32_e32 v231, 0x3fb8aa3b, v173
	v_mul_f32_e32 v173, 0xbfb8aa3b, v173
	v_rcp_f32_e32 v211, v211
	v_exp_f32_e32 v173, v173
	v_exp_f32_e32 v231, v231
	v_add_f32_e32 v213, v233, v139
	v_mul_f32_e32 v211, v39, v211
	v_mul_f32_e32 v173, v212, v173
	v_sub_f32_e32 v212, v213, v139
	v_mul_f32_e32 v211, v211, v231
	v_mul_f32_e32 v231, 0x3fb8aa3b, v212
	v_mul_f32_e32 v212, 0xbfb8aa3b, v212
	v_exp_f32_e32 v212, v212
	v_sub_f32_e32 v214, 1.0, v214
	v_mul_f32_e32 v213, 0xbfb8aa3b, v23
	v_exp_f32_e32 v213, v213
	v_mul_f32_e32 v212, v214, v212
	v_sub_f32_e32 v214, v232, v139
	v_sub_f32_e32 v232, 1.0, v215
	v_add_f32_e32 v215, v228, v167
	v_mul_f32_e32 v167, 0xbfb8aa3b, v52
	v_exp_f32_e32 v167, v167
	v_add_f32_e32 v213, 1.0, v213
	v_mul_f32_e32 v139, 0xbfb8aa3b, v7
	v_rcp_f32_e32 v213, v213
	v_exp_f32_e32 v139, v139
	v_add_f32_e32 v228, v162, v230
	v_sub_f32_e32 v162, v219, v163
	v_add_f32_e32 v167, 1.0, v167
	v_exp_f32_e32 v231, v231
	v_rcp_f32_e32 v167, v167
	v_mul_f32_e32 v219, 0x3fb8aa3b, v162
	v_mul_f32_e32 v162, 0xbfb8aa3b, v162
	v_exp_f32_e32 v219, v219
	v_exp_f32_e32 v162, v162
	v_mul_f32_e32 v213, v23, v213
	v_add_f32_e32 v139, 1.0, v139
	v_mul_f32_e32 v213, v213, v231
	v_rcp_f32_e32 v139, v139
	v_mul_f32_e32 v231, 0x3fb8aa3b, v214
	v_sub_f32_e32 v216, 1.0, v216
	v_mul_f32_e32 v167, v52, v167
	v_sub_f32_e32 v215, v215, v163
	v_exp_f32_e32 v231, v231
	v_mul_f32_e32 v167, v167, v219
	v_mul_f32_e32 v162, v216, v162
	v_mul_f32_e32 v216, 0xbfb8aa3b, v36
	v_mul_f32_e32 v219, 0x3fb8aa3b, v215
	v_mul_f32_e32 v215, 0xbfb8aa3b, v215
	v_exp_f32_e32 v216, v216
	v_exp_f32_e32 v215, v215
	v_mul_f32_e32 v139, v7, v139
	v_mul_f32_e32 v139, v139, v231
	v_sub_f32_e32 v217, 1.0, v217
	v_sub_f32_e32 v231, 1.0, v218
	v_add_f32_e32 v218, v229, v163
	v_add_f32_e32 v216, 1.0, v216
	v_mul_f32_e32 v215, v217, v215
	v_sub_f32_e32 v217, v218, v163
	v_mul_f32_e32 v218, 0xbfb8aa3b, v20
	v_rcp_f32_e32 v216, v216
	v_exp_f32_e32 v218, v218
	v_exp_f32_e32 v219, v219
	v_sub_f32_e32 v229, 1.0, v220
	v_mul_f32_e32 v216, v36, v216
	v_add_f32_e32 v218, 1.0, v218
	v_mul_f32_e32 v216, v216, v219
	v_rcp_f32_e32 v218, v218
	v_mul_f32_e32 v219, 0x3fb8aa3b, v217
	v_exp_f32_e32 v219, v219
	v_add_f32_e32 v220, v225, v165
	v_mul_f32_e32 v165, 0xbfb8aa3b, v53
	v_exp_f32_e32 v165, v165
	v_mul_f32_e32 v218, v20, v218
	v_mul_f32_e32 v218, v218, v219
	v_sub_f32_e32 v219, v228, v163
	v_mul_f32_e32 v163, 0xbfb8aa3b, v4
	v_exp_f32_e32 v163, v163
	v_add_f32_e32 v225, v160, v227
	v_sub_f32_e32 v160, v224, v161
	v_add_f32_e32 v165, 1.0, v165
	v_rcp_f32_e32 v165, v165
	v_mul_f32_e32 v224, 0x3fb8aa3b, v160
	v_mul_f32_e32 v160, 0xbfb8aa3b, v160
	v_exp_f32_e32 v224, v224
	v_exp_f32_e32 v160, v160
	v_add_f32_e32 v163, 1.0, v163
	v_rcp_f32_e32 v163, v163
	v_mul_f32_e32 v228, 0x3fb8aa3b, v219
	v_sub_f32_e32 v221, 1.0, v221
	v_mul_f32_e32 v165, v53, v165
	v_sub_f32_e32 v220, v220, v161
	v_exp_f32_e32 v228, v228
	v_mul_f32_e32 v165, v165, v224
	v_mul_f32_e32 v160, v221, v160
	v_mul_f32_e32 v221, 0xbfb8aa3b, v37
	v_mul_f32_e32 v224, 0x3fb8aa3b, v220
	v_mul_f32_e32 v220, 0xbfb8aa3b, v220
	v_exp_f32_e32 v221, v221
	v_exp_f32_e32 v220, v220
	v_mul_f32_e32 v163, v4, v163
	v_mul_f32_e32 v163, v163, v228
	v_sub_f32_e32 v222, 1.0, v222
	v_sub_f32_e32 v228, 1.0, v223
	v_add_f32_e32 v223, v226, v161
; __device__ __forceinline__ float fexp(float x) { return __builtin_amdgcn_exp2f(x * 1.44269504089f); }
; __device__ __forceinline__ float fsigmoid(float x) { return __builtin_amdgcn_rcpf(1.0f + fexp(-x)); }
;     __device__ __forceinline__ void operator()(f32x4 (&acc)[2][2][4][2], const pg8::Unit& u, int wr, int wc, int fr, int fq) const {
;     ...
;                         for (int m = 0; m < 4; ++m) { const float x = cc[m] - cmid; const float qv = acc[ai][0][m][n][j];
;                             acc[ai][0][m][n][j] = qv * fsigmoid(qv) * fexp(x); acc[ai][1][m][n][j] *= fexp(-x); }
	v_add_f32_e32 v221, 1.0, v221
	v_mul_f32_e32 v220, v222, v220
	v_sub_f32_e32 v222, v223, v161
	v_mul_f32_e32 v223, 0xbfb8aa3b, v21
	v_rcp_f32_e32 v221, v221
	v_exp_f32_e32 v223, v223
	v_exp_f32_e32 v224, v224
	v_sub_f32_e32 v226, 1.0, v200
	v_mul_f32_e32 v221, v37, v221
	v_add_f32_e32 v223, 1.0, v223
	v_mul_f32_e32 v221, v221, v224
	v_rcp_f32_e32 v223, v223
	v_mul_f32_e32 v224, 0x3fb8aa3b, v222
	v_exp_f32_e32 v224, v224
	v_add_f32_e32 v200, v207, v159
	v_mul_f32_e32 v159, 0xbfb8aa3b, v62
	v_exp_f32_e32 v159, v159
	v_mul_f32_e32 v223, v21, v223
	v_mul_f32_e32 v223, v223, v224
	v_sub_f32_e32 v224, v225, v161
	v_mul_f32_e32 v161, 0xbfb8aa3b, v5
	v_exp_f32_e32 v161, v161
	v_add_f32_e32 v207, v154, v209
	v_sub_f32_e32 v154, v206, v155
	v_add_f32_e32 v159, 1.0, v159
	v_rcp_f32_e32 v159, v159
	v_mul_f32_e32 v206, 0x3fb8aa3b, v154
	v_mul_f32_e32 v154, 0xbfb8aa3b, v154
	v_exp_f32_e32 v206, v206
	v_exp_f32_e32 v154, v154
	v_add_f32_e32 v161, 1.0, v161
	v_rcp_f32_e32 v161, v161
	v_mul_f32_e32 v225, 0x3fb8aa3b, v224
	v_sub_f32_e32 v203, 1.0, v203
	v_mul_f32_e32 v159, v62, v159
	v_sub_f32_e32 v200, v200, v155
	v_add_f32_e32 v151, v186, v151
	v_add_f32_e32 v186, v192, v147
	v_sub_f32_e32 v184, v184, v147
	v_mul_f32_e32 v192, 0xbfb8aa3b, v60
	v_exp_f32_e32 v225, v225
	v_mul_f32_e32 v159, v159, v206
	v_mul_f32_e32 v154, v203, v154
	v_mul_f32_e32 v203, 0xbfb8aa3b, v46
	v_mul_f32_e32 v206, 0x3fb8aa3b, v200
	v_mul_f32_e32 v200, 0xbfb8aa3b, v200
	v_add_f32_e32 v146, v146, v195
	v_exp_f32_e32 v192, v192
	v_mul_f32_e32 v195, 0x3fb8aa3b, v184
	v_mul_f32_e32 v184, 0xbfb8aa3b, v184
	v_exp_f32_e32 v203, v203
	v_exp_f32_e32 v200, v200
	v_exp_f32_e32 v184, v184
	v_mul_f32_e32 v161, v5, v161
	v_mul_f32_e32 v161, v161, v225
	v_sub_f32_e32 v204, 1.0, v204
	v_sub_f32_e32 v225, 1.0, v205
	v_add_f32_e32 v205, v208, v155
	v_sub_f32_e32 v183, 1.0, v183
	v_add_f32_e32 v192, 1.0, v192
	v_add_f32_e32 v203, 1.0, v203
	v_mul_f32_e32 v200, v204, v200
	v_sub_f32_e32 v204, v205, v155
	v_mul_f32_e32 v205, 0xbfb8aa3b, v30
	v_rcp_f32_e32 v192, v192
	v_mul_f32_e32 v183, v183, v184
	v_mul_f32_e32 v184, 0xbfb8aa3b, v44
	v_rcp_f32_e32 v203, v203
	v_exp_f32_e32 v205, v205
	v_exp_f32_e32 v195, v195
	v_exp_f32_e32 v184, v184
	v_exp_f32_e32 v206, v206
	v_mul_f32_e32 v192, v60, v192
	v_sub_f32_e32 v151, v151, v147
	v_mul_f32_e32 v203, v46, v203
	v_add_f32_e32 v205, 1.0, v205
	v_mul_f32_e32 v192, v192, v195
	v_add_f32_e32 v184, 1.0, v184
	v_mul_f32_e32 v195, 0x3fb8aa3b, v151
	v_mul_f32_e32 v151, 0xbfb8aa3b, v151
	v_mul_f32_e32 v203, v203, v206
	v_rcp_f32_e32 v205, v205
	v_mul_f32_e32 v206, 0x3fb8aa3b, v204
	v_rcp_f32_e32 v184, v184
	v_exp_f32_e32 v151, v151
	v_exp_f32_e32 v206, v206
	v_exp_f32_e32 v195, v195
	v_sub_f32_e32 v185, 1.0, v185
	v_mul_f32_e32 v205, v30, v205
	v_mul_f32_e32 v184, v44, v184
	v_mul_f32_e32 v151, v185, v151
	v_sub_f32_e32 v185, v186, v147
	v_mul_f32_e32 v205, v205, v206
	v_sub_f32_e32 v206, v207, v155
	v_mul_f32_e32 v155, 0xbfb8aa3b, v14
	v_mul_f32_e32 v184, v184, v195
	v_mul_f32_e32 v195, 0x3fb8aa3b, v185
	v_mul_f32_e32 v185, 0xbfb8aa3b, v185
	v_exp_f32_e32 v155, v155
	v_exp_f32_e32 v185, v185
	v_sub_f32_e32 v190, 1.0, v190
	v_sub_f32_e32 v146, v146, v147
	v_add_f32_e32 v155, 1.0, v155
	v_add_f32_e32 v157, v201, v157
	v_add_f32_e32 v201, v202, v153
	v_add_f32_e32 v202, v152, v156
	v_mul_f32_e32 v156, 0xbfb8aa3b, v63
	v_mul_f32_e32 v185, v190, v185
	v_mul_f32_e32 v190, 0x3fb8aa3b, v146
	v_mul_f32_e32 v146, 0xbfb8aa3b, v146
	v_rcp_f32_e32 v155, v155
	v_mul_f32_e32 v207, 0x3fb8aa3b, v206
	v_exp_f32_e32 v156, v156
	v_exp_f32_e32 v146, v146
	v_exp_f32_e32 v207, v207
	v_sub_f32_e32 v182, 1.0, v182
	v_add_f32_e32 v144, v144, v148
	v_sub_f32_e32 v148, v191, v145
	v_mul_f32_e32 v155, v14, v155
	v_sub_f32_e32 v152, v199, v153
	v_add_f32_e32 v156, 1.0, v156
	v_mul_f32_e32 v182, v182, v146
	v_sub_f32_e32 v146, 1.0, v187
	v_sub_f32_e32 v187, 1.0, v189
	v_mul_f32_e32 v189, 0xbfb8aa3b, v61
	v_mul_f32_e32 v191, 0x3fb8aa3b, v148
	v_mul_f32_e32 v148, 0xbfb8aa3b, v148
	v_mul_f32_e32 v155, v155, v207
	v_sub_f32_e32 v207, 1.0, v158
	v_rcp_f32_e32 v156, v156
	v_mul_f32_e32 v158, 0x3fb8aa3b, v152
	v_exp_f32_e32 v189, v189
	v_exp_f32_e32 v148, v148
	v_exp_f32_e32 v158, v158
	v_mul_f32_e32 v147, 0xbfb8aa3b, v12
	v_add_f32_e32 v149, v193, v149
	v_mul_f32_e32 v156, v63, v156
	v_exp_f32_e32 v147, v147
	v_add_f32_e32 v189, 1.0, v189
	v_mul_f32_e32 v148, v146, v148
	v_sub_f32_e32 v146, v149, v145
	v_mul_f32_e32 v149, 0xbfb8aa3b, v45
	v_mul_f32_e32 v156, v156, v158
	v_mul_f32_e32 v158, 0xbfb8aa3b, v47
	v_rcp_f32_e32 v189, v189
	v_exp_f32_e32 v149, v149
	v_mul_f32_e32 v152, 0xbfb8aa3b, v152
	v_exp_f32_e32 v158, v158
	v_exp_f32_e32 v191, v191
	v_exp_f32_e32 v152, v152
	v_add_f32_e32 v147, 1.0, v147
	v_rcp_f32_e32 v147, v147
	v_mul_f32_e32 v189, v61, v189
	v_add_f32_e32 v149, 1.0, v149
	v_sub_f32_e32 v196, 1.0, v196
	v_sub_f32_e32 v157, v157, v153
	v_add_f32_e32 v158, 1.0, v158
	v_exp_f32_e32 v190, v190
	v_mul_f32_e32 v189, v189, v191
	v_rcp_f32_e32 v149, v149
	v_mul_f32_e32 v191, 0x3fb8aa3b, v146
	v_mul_f32_e32 v146, 0xbfb8aa3b, v146
	v_mul_f32_e32 v152, v196, v152
	v_rcp_f32_e32 v158, v158
	v_mul_f32_e32 v196, 0x3fb8aa3b, v157
	v_exp_f32_e32 v191, v191
	v_exp_f32_e32 v146, v146
	v_exp_f32_e32 v196, v196
; __device__ __forceinline__ unsigned pk2(float lo, float hi) { return __builtin_bit_cast(unsigned, __builtin_convertvector((f32x2){lo, hi}, bf16x2_t)); }
; __device__ __forceinline__ float fexp(float x) { return __builtin_amdgcn_exp2f(x * 1.44269504089f); }
; __device__ __forceinline__ float fsigmoid(float x) { return __builtin_amdgcn_rcpf(1.0f + fexp(-x)); }
;     __device__ __forceinline__ void operator()(f32x4 (&acc)[2][2][4][2], const pg8::Unit& u, int wr, int wc, int fr, int fq) const {
;     ...
;                         for (int m = 0; m < 4; ++m) { const float x = cc[m] - cmid; const float qv = acc[ai][0][m][n][j];
;                             acc[ai][0][m][n][j] = qv * fsigmoid(qv) * fexp(x); acc[ai][1][m][n][j] *= fexp(-x); }
;                         if (fr == 0) { float* sp = (float*)(ws + WS_SCL) + cb * 384 + c8 + 4 * n + j; sp[0] = fexp(cmid); sp[128] = fexp(clast); sp[256] = fexp(clast - cmid); }
;                         asm volatile("" ::: "memory");
;                     }
;                 bf16_t* qp = (bf16_t*)(ws + WS_QI) + cb * 8192 + fr * 128 + c8; bf16_t* kp = (bf16_t*)(ws + WS_KI) + cb * 8192 + fr * 128 + c8;
; #pragma unroll
;                 for (int m = 0; m < 4; ++m) {
;                     const f32x4 a0 = acc[ai][0][m][0], a1 = acc[ai][0][m][1], b0 = acc[ai][1][m][0], b1 = acc[ai][1][m][1];
;                     *(u32x4*)(qp + m * 2048) = (u32x4){pk2(a0[0], a0[1]), pk2(a0[2], a0[3]), pk2(a1[0], a1[1]), pk2(a1[2], a1[3])};
;                     *(u32x4*)(kp + m * 2048) = (u32x4){pk2(b0[0], b0[1]), pk2(b0[2], b0[3]), pk2(b1[0], b1[1]), pk2(b1[2], b1[3])};
;                 }
	v_mul_f32_e32 v157, 0xbfb8aa3b, v157
	v_exp_f32_e32 v157, v157
	v_mul_f32_e32 v147, v12, v147
	v_mul_f32_e32 v190, v147, v190
	v_sub_f32_e32 v147, 1.0, v188
	v_add_f32_e32 v188, v194, v145
	v_mul_f32_e32 v149, v45, v149
	v_mul_f32_e32 v158, v47, v158
	v_mul_f32_e32 v149, v149, v191
	v_mul_f32_e32 v191, v147, v146
	v_sub_f32_e32 v146, v188, v145
	v_sub_f32_e32 v144, v144, v145
	v_mul_f32_e32 v145, 0xbfb8aa3b, v13
	v_sub_f32_e32 v197, 1.0, v197
	v_mul_f32_e32 v158, v158, v196
	v_sub_f32_e32 v196, v201, v153
	v_mul_f32_e32 v147, 0xbfb8aa3b, v29
	v_mul_f32_e32 v188, 0x3fb8aa3b, v146
	v_mul_f32_e32 v146, 0xbfb8aa3b, v146
	v_exp_f32_e32 v145, v145
	v_mul_f32_e32 v157, v197, v157
	v_mul_f32_e32 v197, 0xbfb8aa3b, v31
	v_mul_f32_e32 v199, 0x3fb8aa3b, v196
	v_mul_f32_e32 v196, 0xbfb8aa3b, v196
	v_exp_f32_e32 v147, v147
	v_exp_f32_e32 v146, v146
	v_exp_f32_e32 v197, v197
	v_exp_f32_e32 v196, v196
	v_mul_f32_e32 v186, 0xbfb8aa3b, v28
	v_add_f32_e32 v145, 1.0, v145
	v_sub_f32_e32 v198, 1.0, v198
	v_exp_f32_e32 v186, v186
	v_add_f32_e32 v147, 1.0, v147
	v_mul_f32_e32 v187, v187, v146
	v_rcp_f32_e32 v145, v145
	v_mul_f32_e32 v146, 0x3fb8aa3b, v144
	v_mul_f32_e32 v144, 0xbfb8aa3b, v144
	s_lshl_b64 s[4:5], s[66:67], 14
	v_add_f32_e32 v197, 1.0, v197
	v_mul_f32_e32 v196, v198, v196
	v_sub_f32_e32 v198, v202, v153
	v_mul_f32_e32 v153, 0xbfb8aa3b, v15
	v_rcp_f32_e32 v147, v147
	v_exp_f32_e32 v146, v146
	v_exp_f32_e32 v144, v144
	s_add_u32 s26, s95, s4
	v_rcp_f32_e32 v197, v197
	v_exp_f32_e32 v153, v153
	v_exp_f32_e32 v188, v188
	s_addc_u32 s27, s96, s5
	v_exp_f32_e32 v199, v199
	s_add_u32 s4, s97, s4
	v_add_f32_e32 v186, 1.0, v186
	v_sub_f32_e32 v150, 1.0, v150
	v_mul_f32_e32 v145, v13, v145
	s_addc_u32 s5, s85, s5
	v_rcp_f32_e32 v186, v186
	v_mul_f32_e32 v147, v29, v147
	v_mul_f32_e32 v193, v145, v146
	v_mul_f32_e32 v194, v150, v144
	v_lshl_add_u64 v[144:145], s[26:27], 0, v[140:141]
	v_lshl_add_u64 v[140:141], s[4:5], 0, v[140:141]
	v_mul_f32_e32 v217, 0xbfb8aa3b, v217
	v_mul_f32_e32 v222, 0xbfb8aa3b, v222
	v_mul_f32_e32 v204, 0xbfb8aa3b, v204
	v_mul_f32_e32 v197, v31, v197
	v_add_f32_e32 v153, 1.0, v153
	v_exp_f32_e32 v195, v195
	v_mul_f32_e32 v188, v147, v188
	v_lshl_add_u64 v[144:145], v[144:145], 0, v[142:143]
	v_lshl_add_u64 v[146:147], v[140:141], 0, v[142:143]
	v_cvt_pk_bf16_f32 v140, v192, v189
	v_cvt_pk_bf16_f32 v141, v159, v156
	v_cvt_pk_bf16_f32 v142, v167, v165
	v_cvt_pk_bf16_f32 v143, v137, v171
	v_exp_f32_e32 v217, v217
	v_exp_f32_e32 v222, v222
	v_exp_f32_e32 v204, v204
	v_mul_f32_e32 v197, v197, v199
	v_rcp_f32_e32 v153, v153
	v_mul_f32_e32 v199, 0x3fb8aa3b, v198
	global_store_dwordx4 v[144:145], v[140:143], off nt
	v_exp_f32_e32 v199, v199
	v_mul_f32_e32 v172, 0xbfb8aa3b, v172
	v_cvt_pk_bf16_f32 v140, v183, v148
	v_cvt_pk_bf16_f32 v141, v154, v152
	v_cvt_pk_bf16_f32 v142, v162, v160
	v_cvt_pk_bf16_f32 v143, v135, v138
	v_add_co_u32_e32 v148, vcc, s79, v144
	global_store_dwordx4 v[146:147], v[140:143], off nt
	v_mul_f32_e32 v214, 0xbfb8aa3b, v214
	v_mul_f32_e32 v219, 0xbfb8aa3b, v219
	v_cvt_pk_bf16_f32 v140, v184, v149
	v_addc_co_u32_e32 v149, vcc, 0, v145, vcc
	v_mul_f32_e32 v224, 0xbfb8aa3b, v224
	v_mul_f32_e32 v206, 0xbfb8aa3b, v206
	v_mul_f32_e32 v198, 0xbfb8aa3b, v198
	v_mul_f32_e32 v186, v28, v186
	v_cvt_pk_bf16_f32 v141, v203, v158
	v_cvt_pk_bf16_f32 v142, v216, v221
	v_cvt_pk_bf16_f32 v143, v166, v211
	v_add_co_u32_e32 v150, vcc, s79, v146
	v_exp_f32_e32 v172, v172
	v_exp_f32_e32 v214, v214
	v_exp_f32_e32 v219, v219
	v_exp_f32_e32 v224, v224
	v_exp_f32_e32 v206, v206
	v_exp_f32_e32 v198, v198
	v_mul_f32_e32 v186, v186, v195
	global_store_dwordx4 v[148:149], v[140:143], off offset:-4096 nt
	v_mul_f32_e32 v217, v231, v217
	v_mul_f32_e32 v222, v228, v222
	v_cvt_pk_bf16_f32 v140, v151, v191
	v_cvt_pk_bf16_f32 v141, v200, v157
	v_cvt_pk_bf16_f32 v142, v215, v220
	v_cvt_pk_bf16_f32 v143, v164, v173
	v_addc_co_u32_e32 v151, vcc, 0, v147, vcc
	v_mul_f32_e32 v204, v225, v204
	v_mul_f32_e32 v153, v15, v153
	global_store_dwordx4 v[150:151], v[140:143], off offset:-4096 nt
	v_mul_f32_e32 v153, v153, v199
	v_add_co_u32_e32 v138, vcc, s62, v144
	v_cvt_pk_bf16_f32 v140, v186, v188
	v_cvt_pk_bf16_f32 v141, v205, v197
	v_cvt_pk_bf16_f32 v142, v218, v223
	v_cvt_pk_bf16_f32 v143, v170, v213
	global_store_dwordx4 v[148:149], v[140:143], off nt
	v_mul_f32_e32 v172, v236, v172
	v_mul_f32_e32 v214, v235, v214
	v_cvt_pk_bf16_f32 v140, v185, v187
	v_cvt_pk_bf16_f32 v141, v204, v196
	v_cvt_pk_bf16_f32 v142, v217, v222
	v_cvt_pk_bf16_f32 v143, v168, v212
	global_store_dwordx4 v[150:151], v[140:143], off nt
	v_mul_f32_e32 v219, v232, v219
	v_mul_f32_e32 v224, v229, v224
	v_cvt_pk_bf16_f32 v140, v190, v193
	v_cvt_pk_bf16_f32 v141, v155, v153
	v_cvt_pk_bf16_f32 v142, v163, v161
	v_cvt_pk_bf16_f32 v143, v169, v139
	v_addc_co_u32_e32 v139, vcc, 0, v145, vcc
	v_mul_f32_e32 v206, v226, v206
	v_mul_f32_e32 v198, v207, v198
	global_store_dwordx4 v[138:139], v[140:143], off nt
	v_cvt_pk_bf16_f32 v138, v182, v194
	v_cvt_pk_bf16_f32 v139, v206, v198
	v_add_co_u32_e32 v142, vcc, 0x3000, v146
	v_cvt_pk_bf16_f32 v140, v219, v224
	v_cvt_pk_bf16_f32 v141, v172, v214
	v_addc_co_u32_e32 v143, vcc, 0, v147, vcc
	global_store_dwordx4 v[142:143], v[138:141], off nt

; __device__ __forceinline__ unsigned pk2(float lo, float hi) { return __builtin_bit_cast(unsigned, __builtin_convertvector((f32x2){lo, hi}, bf16x2_t)); }
; __device__ __forceinline__ float fgelu(float x) { return x * fsigmoid(x * (1.5957691216f + 0.0713548163f * x * x)); }
;     __device__ __forceinline__ void operator()(f32x4 (&acc)[2][2][4][2], const pg8::Unit& u, int wr, int wc, int fr, int fq) const {
;     ...
;                     const int row = row0 + ai * 128 + m * 16;
;                     float s1 = 0.f, s2 = 0.f;
; #pragma unroll
;                     for (int bj = 0; bj < 2; ++bj) {
;                         float y[8];
; #pragma unroll
;                         for (int n = 0; n < 2; ++n)
; #pragma unroll
;                             for (int j = 0; j < 4; ++j) { const float v = fgelu(acc[ai][bj][m][n][j]); y[4 * n + j] = v; s1 += v; s2 += v * v; }
;                         *(u32x4*)(G + (size_t)row * BW + bj * 128) = (u32x4){pk2(y[0], y[1]), pk2(y[2], y[3]), pk2(y[4], y[5]), pk2(y[6], y[7])};
;                     }
;                     s1 += __shfl_xor(s1, 16); s1 += __shfl_xor(s1, 32);
;                     s2 += __shfl_xor(s2, 16); s2 += __shfl_xor(s2, 32);
;                     if (fq == 0) *(f32x2*)(lns + ((size_t)row * 32 + (tile - 16) * 4 + wc) * 2) = (f32x2){s1, s2};
.LBB0_179:
	s_andn2_b64 vcc, exec, s[66:67]
	s_cbranch_vccnz .LBB0_197
	v_mul_f32_e32 v142, 0x3d922279, v124
	v_mul_f32_e32 v143, 0x3d922279, v125
	v_fmaak_f32 v142, v124, v142, 0x3fcc422a
	v_fmaak_f32 v143, v125, v143, 0x3fcc422a
	v_mul_f32_e32 v142, v124, v142
	v_mul_f32_e32 v143, v125, v143
	v_mul_f32_e32 v142, 0xbfb8aa3b, v142
	v_mul_f32_e32 v143, 0xbfb8aa3b, v143
	v_mul_f32_e32 v148, 0x3d922279, v126
	v_mul_f32_e32 v149, 0x3d922279, v127
	v_exp_f32_e32 v142, v142
	v_exp_f32_e32 v143, v143
	v_fmaak_f32 v148, v126, v148, 0x3fcc422a
	v_fmaak_f32 v149, v127, v149, 0x3fcc422a
	v_mul_f32_e32 v150, 0x3d922279, v116
	v_mul_f32_e32 v151, 0x3d922279, v117
	v_mul_f32_e32 v148, v126, v148
	v_mul_f32_e32 v149, v127, v149
	v_fmaak_f32 v150, v116, v150, 0x3fcc422a
	v_fmaak_f32 v151, v117, v151, 0x3fcc422a
	v_mul_f32_e32 v148, 0xbfb8aa3b, v148
	v_mul_f32_e32 v149, 0xbfb8aa3b, v149
	v_mul_f32_e32 v150, v116, v150
	v_mul_f32_e32 v151, v117, v151
	v_exp_f32_e32 v148, v148
	v_exp_f32_e32 v149, v149
	v_mul_f32_e32 v150, 0xbfb8aa3b, v150
	v_mul_f32_e32 v151, 0xbfb8aa3b, v151
	v_add_f32_e32 v142, 1.0, v142
	v_add_f32_e32 v143, 1.0, v143
	v_exp_f32_e32 v150, v150
	v_exp_f32_e32 v151, v151
	v_rcp_f32_e32 v142, v142
	v_rcp_f32_e32 v143, v143
	v_add_f32_e32 v148, 1.0, v148
	v_add_f32_e32 v149, 1.0, v149
	v_rcp_f32_e32 v148, v148
	v_rcp_f32_e32 v149, v149
	v_add_f32_e32 v150, 1.0, v150
	v_add_f32_e32 v151, 1.0, v151
	v_pk_mul_f32 v[142:143], v[124:125], v[142:143]
	v_rcp_f32_e32 v150, v150
	v_rcp_f32_e32 v151, v151
	v_add_f32_e32 v144, 0, v142
	v_add_f32_e32 v147, v143, v144
	v_mul_f32_e32 v144, v143, v143
	v_pk_fma_f32 v[144:145], v[142:143], v[142:143], v[144:145] op_sel_hi:[1,1,0]
	v_pk_mul_f32 v[148:149], v[126:127], v[148:149]
	v_pk_mul_f32 v[150:151], v[116:117], v[150:151]
	v_pk_fma_f32 v[144:145], v[148:149], v[148:149], v[144:145]
	v_mul_f32_e32 v154, v149, v149
	v_mov_b32_e32 v152, v150
	v_mov_b32_e32 v153, v149
	v_pk_add_f32 v[144:145], v[154:155], v[144:145] op_sel_hi:[0,1]
	v_pk_fma_f32 v[144:145], v[152:153], v[152:153], v[144:145]
	v_mul_f32_e32 v152, 0x3d922279, v118
	v_mul_f32_e32 v153, 0x3d922279, v119
	v_fmaak_f32 v152, v118, v152, 0x3fcc422a
	v_fmaak_f32 v153, v119, v153, 0x3fcc422a
	s_add_i32 s3, s64, -16
	v_mul_f32_e32 v152, v118, v152
	v_mul_f32_e32 v153, v119, v153
	s_lshl_b32 s4, s3, 9
	v_mul_f32_e32 v152, 0xbfb8aa3b, v152
	v_mul_f32_e32 v153, 0xbfb8aa3b, v153
	s_add_u32 s4, s86, s4
	v_exp_f32_e32 v152, v152
	v_exp_f32_e32 v153, v153
	s_addc_u32 s5, s87, 0
	v_ashrrev_i32_e32 v137, 31, v136
	v_lshl_add_u64 v[138:139], v[136:137], 1, s[4:5]
	v_and_b32_e32 v137, 64, v180
	v_xor_b32_e32 v135, 16, v180
	v_add_u32_e32 v137, 64, v137
	v_cmp_lt_i32_e32 vcc, v135, v137
	v_add_f32_e32 v152, 1.0, v152
	v_add_f32_e32 v153, 1.0, v153
	v_cndmask_b32_e32 v135, v180, v135, vcc
	v_rcp_f32_e32 v152, v152
	v_rcp_f32_e32 v153, v153
	v_lshlrev_b32_e32 v146, 2, v135
	v_xor_b32_e32 v135, 32, v180
	v_cmp_lt_i32_e32 vcc, v135, v137
	v_pk_mul_f32 v[152:153], v[118:119], v[152:153]
	v_mul_f32_e32 v156, v151, v151
	v_cndmask_b32_e32 v135, v180, v135, vcc
	v_lshlrev_b32_e32 v137, 2, v135
	v_ashrrev_i32_e32 v135, 31, v134
	v_lshlrev_b64 v[140:141], 12, v[134:135]
	v_mov_b32_e32 v154, v152
	v_mov_b32_e32 v155, v151
	v_pk_add_f32 v[144:145], v[156:157], v[144:145] op_sel_hi:[0,1]
	v_lshl_add_u64 v[140:141], v[138:139], 0, v[140:141]
	v_pk_fma_f32 v[154:155], v[154:155], v[154:155], v[144:145]
	v_cvt_pk_bf16_f32 v142, v142, v143
	v_cvt_pk_bf16_f32 v143, v148, v149
	v_cvt_pk_bf16_f32 v144, v150, v151
	v_cvt_pk_bf16_f32 v145, v152, v153
	global_store_dwordx4 v[140:141], v[142:145], off nt
	v_add_f32_e32 v147, v148, v147
	v_add_f32_e32 v147, v149, v147
	v_mul_f32_e32 v142, 0x3d922279, v120
	v_mul_f32_e32 v143, 0x3d922279, v121
	v_fmaak_f32 v142, v120, v142, 0x3fcc422a
	v_fmaak_f32 v143, v121, v143, 0x3fcc422a
	v_mul_f32_e32 v142, v120, v142
	v_mul_f32_e32 v143, v121, v143
	v_mul_f32_e32 v142, 0xbfb8aa3b, v142
	v_mul_f32_e32 v143, 0xbfb8aa3b, v143
	v_exp_f32_e32 v142, v142
	v_exp_f32_e32 v143, v143
	v_add_f32_e32 v147, v150, v147
	v_add_f32_e32 v147, v151, v147
	v_add_f32_e32 v142, 1.0, v142
	v_add_f32_e32 v143, 1.0, v143
	v_rcp_f32_e32 v142, v142
	v_rcp_f32_e32 v143, v143
	v_add_f32_e32 v147, v152, v147
	v_add_f32_e32 v147, v153, v147
	s_lshl_b32 s3, s3, 2
	v_pk_mul_f32 v[142:143], v[120:121], v[142:143]
	v_cmp_eq_u32_e32 vcc, 0, v181
	v_pk_mov_b32 v[144:145], v[152:153], v[142:143] op_sel:[1,0]
	v_mul_f32_e32 v148, v142, v142
	v_pk_fma_f32 v[144:145], v[144:145], v[144:145], v[154:155]
	v_mul_f32_e32 v152, v143, v143
	v_pk_add_f32 v[144:145], v[144:145], v[148:149] op_sel_hi:[1,0]
	v_mul_f32_e32 v148, 0x3d922279, v122
	v_mul_f32_e32 v149, 0x3d922279, v123
	v_fmaak_f32 v148, v122, v148, 0x3fcc422a
	v_fmaak_f32 v149, v123, v149, 0x3fcc422a
	v_mul_f32_e32 v148, v122, v148
	v_mul_f32_e32 v149, v123, v149
	v_mul_f32_e32 v148, 0xbfb8aa3b, v148
	v_mul_f32_e32 v149, 0xbfb8aa3b, v149
	v_exp_f32_e32 v148, v148
	v_exp_f32_e32 v149, v149
	v_mov_b32_e32 v151, v143
	v_pk_add_f32 v[144:145], v[152:153], v[144:145] op_sel_hi:[0,1]
	v_add_f32_e32 v148, 1.0, v148
	v_add_f32_e32 v149, 1.0, v149
	v_rcp_f32_e32 v148, v148
	v_rcp_f32_e32 v149, v149
	v_add_f32_e32 v147, v147, v142
	v_add_f32_e32 v147, v143, v147
	v_cvt_pk_bf16_f32 v142, v142, v143
	v_pk_mul_f32 v[148:149], v[122:123], v[148:149]
	s_or_b32 s14, s3, s82
	v_mov_b32_e32 v150, v148
	v_pk_fma_f32 v[144:145], v[150:151], v[150:151], v[144:145]
	v_mul_f32_e32 v150, 0x3d922279, v112
	v_mul_f32_e32 v151, 0x3d922279, v113
	v_fmaak_f32 v150, v112, v150, 0x3fcc422a
	v_fmaak_f32 v151, v113, v151, 0x3fcc422a
	v_mul_f32_e32 v150, v112, v150
; __device__ __forceinline__ unsigned pk2(float lo, float hi) { return __builtin_bit_cast(unsigned, __builtin_convertvector((f32x2){lo, hi}, bf16x2_t)); }
; __device__ __forceinline__ float fgelu(float x) { return x * fsigmoid(x * (1.5957691216f + 0.0713548163f * x * x)); }
;     __device__ __forceinline__ void operator()(f32x4 (&acc)[2][2][4][2], const pg8::Unit& u, int wr, int wc, int fr, int fq) const {
;     ...
;                     const int row = row0 + ai * 128 + m * 16;
;                     float s1 = 0.f, s2 = 0.f;
; #pragma unroll
;                     for (int bj = 0; bj < 2; ++bj) {
;                         float y[8];
; #pragma unroll
;                         for (int n = 0; n < 2; ++n)
; #pragma unroll
;                             for (int j = 0; j < 4; ++j) { const float v = fgelu(acc[ai][bj][m][n][j]); y[4 * n + j] = v; s1 += v; s2 += v * v; }
;                         *(u32x4*)(G + (size_t)row * BW + bj * 128) = (u32x4){pk2(y[0], y[1]), pk2(y[2], y[3]), pk2(y[4], y[5]), pk2(y[6], y[7])};
;                     }
;                     s1 += __shfl_xor(s1, 16); s1 += __shfl_xor(s1, 32);
;                     s2 += __shfl_xor(s2, 16); s2 += __shfl_xor(s2, 32);
;                     if (fq == 0) *(f32x2*)(lns + ((size_t)row * 32 + (tile - 16) * 4 + wc) * 2) = (f32x2){s1, s2};
	v_mul_f32_e32 v151, v113, v151
	v_mul_f32_e32 v150, 0xbfb8aa3b, v150
	v_mul_f32_e32 v151, 0xbfb8aa3b, v151
	v_exp_f32_e32 v150, v150
	v_exp_f32_e32 v151, v151
	v_mul_f32_e32 v154, v149, v149
	v_mov_b32_e32 v153, v149
	v_add_f32_e32 v150, 1.0, v150
	v_add_f32_e32 v151, 1.0, v151
	v_rcp_f32_e32 v150, v150
	v_rcp_f32_e32 v151, v151
	v_pk_add_f32 v[144:145], v[154:155], v[144:145] op_sel_hi:[0,1]
	v_add_f32_e32 v147, v148, v147
	v_add_f32_e32 v147, v149, v147
	v_pk_mul_f32 v[150:151], v[112:113], v[150:151]
	v_cvt_pk_bf16_f32 v143, v148, v149
	v_mov_b32_e32 v152, v150
	v_pk_fma_f32 v[152:153], v[152:153], v[152:153], v[144:145]
	v_mul_f32_e32 v144, 0x3d922279, v114
	v_fmaak_f32 v144, v114, v144, 0x3fcc422a
	v_mul_f32_e32 v144, v114, v144
	v_mul_f32_e32 v144, 0xbfb8aa3b, v144
	v_exp_f32_e32 v144, v144
	v_add_f32_e32 v147, v150, v147
	v_mul_f32_e32 v158, v151, v151
	v_add_f32_e32 v154, v151, v147
	v_add_f32_e32 v144, 1.0, v144
	v_rcp_f32_e32 v156, v144
	v_mul_f32_e32 v144, 0x3d922279, v115
	v_fmaak_f32 v144, v115, v144, 0x3fcc422a
	v_mul_f32_e32 v144, v115, v144
	v_mul_f32_e32 v144, 0xbfb8aa3b, v144
	v_exp_f32_e32 v144, v144
	v_pk_add_f32 v[152:153], v[158:159], v[152:153] op_sel_hi:[0,1]
	v_add_f32_e32 v144, 1.0, v144
	v_rcp_f32_e32 v157, v144
	v_cvt_pk_bf16_f32 v144, v150, v151
	v_pk_mul_f32 v[148:149], v[114:115], v[156:157]
	s_nop 0
	v_mov_b32_e32 v150, v148
	v_mov_b32_e32 v155, v149
	v_pk_fma_f32 v[150:151], v[150:151], v[150:151], v[152:153]
	v_pk_fma_f32 v[152:153], v[114:115], v[156:157], v[154:155]
	v_pk_mul_f32 v[154:155], v[148:149], v[148:149]
	v_pk_mov_b32 v[150:151], v[148:149], v[150:151] op_sel:[1,0]
	v_mov_b32_e32 v153, v155
	v_pk_add_f32 v[150:151], v[152:153], v[150:151]
	v_cvt_pk_bf16_f32 v145, v148, v149
	global_store_dwordx4 v[140:141], v[142:145], off offset:256 nt
	ds_bpermute_b32 v140, v146, v150
	ds_bpermute_b32 v141, v146, v151
	s_waitcnt lgkmcnt(0)
	v_pk_add_f32 v[140:141], v[150:151], v[140:141]
	ds_bpermute_b32 v142, v137, v140
	ds_bpermute_b32 v143, v137, v141
	s_and_saveexec_b64 s[4:5], vcc
	s_cbranch_execz .LBB0_182
	s_waitcnt lgkmcnt(0)
	v_pk_add_f32 v[140:141], v[140:141], v[142:143]
	v_lshlrev_b64 v[142:143], 8, v[134:135]
	v_lshl_add_u64 v[142:143], s[40:41], 0, v[142:143]
	v_lshl_add_u64 v[142:143], s[14:15], 3, v[142:143]
	global_store_dwordx2 v[142:143], v[140:141], off
.LBB0_182:
	s_or_b64 exec, exec, s[4:5]
	v_mul_f32_e32 v147, 0x3d922279, v110
	v_fmaak_f32 v147, v110, v147, 0x3fcc422a
	v_mul_f32_e32 v147, v110, v147
	v_mul_f32_e32 v147, 0xbfb8aa3b, v147
	v_exp_f32_e32 v147, v147
	v_mul_f32_e32 v135, 0x3d922279, v108
	v_fmaak_f32 v135, v108, v135, 0x3fcc422a
	v_mul_f32_e32 v135, v108, v135
	v_add_f32_e32 v147, 1.0, v147
	v_rcp_f32_e32 v150, v147
	v_mul_f32_e32 v147, 0x3d922279, v111
	v_fmaak_f32 v147, v111, v147, 0x3fcc422a
	v_mul_f32_e32 v147, v111, v147
	v_mul_f32_e32 v147, 0xbfb8aa3b, v147
	v_exp_f32_e32 v147, v147
	v_mul_f32_e32 v135, 0xbfb8aa3b, v135
	v_exp_f32_e32 v135, v135
	v_add_u32_e32 v140, 16, v134
	v_add_f32_e32 v147, 1.0, v147
	v_rcp_f32_e32 v151, v147
	v_mul_f32_e32 v147, 0x3d922279, v100
	v_fmaak_f32 v147, v100, v147, 0x3fcc422a
	v_mul_f32_e32 v147, v100, v147
	v_mul_f32_e32 v147, 0xbfb8aa3b, v147
	v_exp_f32_e32 v147, v147
	v_add_f32_e32 v135, 1.0, v135
	v_rcp_f32_e32 v144, v135
	v_mul_f32_e32 v135, 0x3d922279, v109
	v_add_f32_e32 v147, 1.0, v147
	v_rcp_f32_e32 v152, v147
	v_mul_f32_e32 v147, 0x3d922279, v101
	v_fmaak_f32 v135, v109, v135, 0x3fcc422a
	v_fmaak_f32 v147, v101, v147, 0x3fcc422a
	v_mul_f32_e32 v135, v109, v135
	v_mul_f32_e32 v147, v101, v147
	v_mul_f32_e32 v135, 0xbfb8aa3b, v135
	v_mul_f32_e32 v147, 0xbfb8aa3b, v147
	v_exp_f32_e32 v135, v135
	v_exp_f32_e32 v147, v147
	v_pk_mul_f32 v[150:151], v[110:111], v[150:151]
	v_ashrrev_i32_e32 v141, 31, v140
	v_add_f32_e32 v135, 1.0, v135
	v_add_f32_e32 v147, 1.0, v147
	v_rcp_f32_e32 v145, v135
	v_rcp_f32_e32 v153, v147
	v_mul_f32_e32 v147, 0x3d922279, v102
	v_fmaak_f32 v147, v102, v147, 0x3fcc422a
	v_mul_f32_e32 v147, v102, v147
	v_mul_f32_e32 v147, 0xbfb8aa3b, v147
	v_pk_mul_f32 v[144:145], v[108:109], v[144:145]
	v_exp_f32_e32 v147, v147
	v_mul_f32_e32 v148, v145, v145
	v_pk_fma_f32 v[148:149], v[144:145], v[144:145], v[148:149] op_sel_hi:[1,1,0]
	v_pk_mul_f32 v[152:153], v[100:101], v[152:153]
	v_pk_fma_f32 v[148:149], v[150:151], v[150:151], v[148:149]
	v_mul_f32_e32 v156, v151, v151
	v_mov_b32_e32 v154, v152
	v_mov_b32_e32 v155, v151
	v_pk_add_f32 v[148:149], v[156:157], v[148:149] op_sel_hi:[0,1]
	v_add_f32_e32 v147, 1.0, v147
	v_pk_fma_f32 v[148:149], v[154:155], v[154:155], v[148:149]
	v_rcp_f32_e32 v154, v147
	v_mul_f32_e32 v147, 0x3d922279, v103
	v_fmaak_f32 v147, v103, v147, 0x3fcc422a
	v_mul_f32_e32 v147, v103, v147
	v_mul_f32_e32 v147, 0xbfb8aa3b, v147
	v_exp_f32_e32 v147, v147
	v_mul_f32_e32 v158, v153, v153
	v_add_f32_e32 v135, 0, v144
	v_mov_b32_e32 v157, v153
	v_add_f32_e32 v147, 1.0, v147
	v_rcp_f32_e32 v155, v147
	v_pk_add_f32 v[148:149], v[158:159], v[148:149] op_sel_hi:[0,1]
	v_add_f32_e32 v135, v145, v135
	v_mul_f32_e32 v147, 0x3d922279, v106
	v_pk_mul_f32 v[154:155], v[102:103], v[154:155]
	v_fmaak_f32 v147, v106, v147, 0x3fcc422a
	v_mov_b32_e32 v156, v154
	v_pk_fma_f32 v[156:157], v[156:157], v[156:157], v[148:149]
	v_cvt_pk_bf16_f32 v148, v144, v145
	v_mul_f32_e32 v144, 0x3d922279, v104
	v_mul_f32_e32 v145, 0x3d922279, v105
	v_fmaak_f32 v144, v104, v144, 0x3fcc422a
	v_fmaak_f32 v145, v105, v145, 0x3fcc422a
	v_mul_f32_e32 v144, v104, v144
	v_mul_f32_e32 v145, v105, v145
	v_mul_f32_e32 v144, 0xbfb8aa3b, v144
	v_mul_f32_e32 v145, 0xbfb8aa3b, v145
	v_exp_f32_e32 v144, v144
	v_exp_f32_e32 v145, v145
	v_mul_f32_e32 v147, v106, v147
	v_mul_f32_e32 v147, 0xbfb8aa3b, v147
	v_add_f32_e32 v144, 1.0, v144
	v_add_f32_e32 v145, 1.0, v145
	v_rcp_f32_e32 v144, v144
	v_rcp_f32_e32 v145, v145
	v_exp_f32_e32 v147, v147
	s_waitcnt lgkmcnt(0)
; __device__ __forceinline__ unsigned pk2(float lo, float hi) { return __builtin_bit_cast(unsigned, __builtin_convertvector((f32x2){lo, hi}, bf16x2_t)); }
; __device__ __forceinline__ float fgelu(float x) { return x * fsigmoid(x * (1.5957691216f + 0.0713548163f * x * x)); }
;     __device__ __forceinline__ void operator()(f32x4 (&acc)[2][2][4][2], const pg8::Unit& u, int wr, int wc, int fr, int fq) const {
;     ...
;                     const int row = row0 + ai * 128 + m * 16;
;                     float s1 = 0.f, s2 = 0.f;
; #pragma unroll
;                     for (int bj = 0; bj < 2; ++bj) {
;                         float y[8];
; #pragma unroll
;                         for (int n = 0; n < 2; ++n)
; #pragma unroll
;                             for (int j = 0; j < 4; ++j) { const float v = fgelu(acc[ai][bj][m][n][j]); y[4 * n + j] = v; s1 += v; s2 += v * v; }
;                         *(u32x4*)(G + (size_t)row * BW + bj * 128) = (u32x4){pk2(y[0], y[1]), pk2(y[2], y[3]), pk2(y[4], y[5]), pk2(y[6], y[7])};
;                     }
;                     s1 += __shfl_xor(s1, 16); s1 += __shfl_xor(s1, 32);
;                     s2 += __shfl_xor(s2, 16); s2 += __shfl_xor(s2, 32);
;                     if (fq == 0) *(f32x2*)(lns + ((size_t)row * 32 + (tile - 16) * 4 + wc) * 2) = (f32x2){s1, s2};
	v_lshlrev_b64 v[142:143], 12, v[140:141]
	v_add_f32_e32 v135, v150, v135
	v_lshl_add_u64 v[142:143], v[138:139], 0, v[142:143]
	v_add_f32_e32 v135, v151, v135
	v_cvt_pk_bf16_f32 v149, v150, v151
	v_cvt_pk_bf16_f32 v150, v152, v153
	v_cvt_pk_bf16_f32 v151, v154, v155
	v_pk_mul_f32 v[144:145], v[104:105], v[144:145]
	global_store_dwordx4 v[142:143], v[148:151], off nt
	v_add_f32_e32 v147, 1.0, v147
	v_add_f32_e32 v135, v152, v135
	v_pk_mov_b32 v[148:149], v[154:155], v[144:145] op_sel:[1,0]
	v_mul_f32_e32 v150, v144, v144
	v_pk_fma_f32 v[148:149], v[148:149], v[148:149], v[156:157]
	v_add_f32_e32 v135, v153, v135
	v_pk_add_f32 v[148:149], v[148:149], v[150:151] op_sel_hi:[1,0]
	v_rcp_f32_e32 v150, v147
	v_mul_f32_e32 v147, 0x3d922279, v107
	v_fmaak_f32 v147, v107, v147, 0x3fcc422a
	v_mul_f32_e32 v147, v107, v147
	v_mul_f32_e32 v147, 0xbfb8aa3b, v147
	v_exp_f32_e32 v147, v147
	v_add_f32_e32 v135, v154, v135
	v_mul_f32_e32 v154, v145, v145
	v_mov_b32_e32 v153, v145
	v_add_f32_e32 v147, 1.0, v147
	v_rcp_f32_e32 v151, v147
	v_mul_f32_e32 v147, 0x3d922279, v96
	v_fmaak_f32 v147, v96, v147, 0x3fcc422a
	v_mul_f32_e32 v147, v96, v147
	v_mul_f32_e32 v147, 0xbfb8aa3b, v147
	v_exp_f32_e32 v147, v147
	v_pk_mul_f32 v[150:151], v[106:107], v[150:151]
	v_pk_add_f32 v[148:149], v[154:155], v[148:149] op_sel_hi:[0,1]
	v_mov_b32_e32 v152, v150
	v_add_f32_e32 v147, 1.0, v147
	v_pk_fma_f32 v[148:149], v[152:153], v[152:153], v[148:149]
	v_rcp_f32_e32 v152, v147
	v_mul_f32_e32 v147, 0x3d922279, v97
	v_fmaak_f32 v147, v97, v147, 0x3fcc422a
	v_mul_f32_e32 v147, v97, v147
	v_mul_f32_e32 v147, 0xbfb8aa3b, v147
	v_exp_f32_e32 v147, v147
	v_add_f32_e32 v135, v155, v135
	v_add_f32_e32 v135, v135, v144
	v_add_f32_e32 v135, v145, v135
	v_add_f32_e32 v147, 1.0, v147
	v_rcp_f32_e32 v153, v147
	v_add_f32_e32 v135, v150, v135
	v_add_f32_e32 v135, v151, v135
	v_mul_f32_e32 v156, v151, v151
	v_pk_mul_f32 v[152:153], v[96:97], v[152:153]
	v_pk_add_f32 v[148:149], v[156:157], v[148:149] op_sel_hi:[0,1]
	v_add_f32_e32 v135, v152, v135
	v_add_f32_e32 v156, v153, v135
	v_mul_f32_e32 v135, 0x3d922279, v98
	v_fmaak_f32 v135, v98, v135, 0x3fcc422a
	v_mul_f32_e32 v135, v98, v135
	v_mul_f32_e32 v135, 0xbfb8aa3b, v135
	v_exp_f32_e32 v135, v135
	v_mov_b32_e32 v154, v152
	v_mov_b32_e32 v155, v151
	v_pk_fma_f32 v[154:155], v[154:155], v[154:155], v[148:149]
	v_add_f32_e32 v135, 1.0, v135
	v_rcp_f32_e32 v158, v135
	v_mul_f32_e32 v135, 0x3d922279, v99
	v_fmaak_f32 v135, v99, v135, 0x3fcc422a
	v_mul_f32_e32 v135, v99, v135
	v_mul_f32_e32 v135, 0xbfb8aa3b, v135
	v_exp_f32_e32 v135, v135
	v_cvt_pk_bf16_f32 v148, v144, v145
	v_mul_f32_e32 v160, v153, v153
	v_cvt_pk_bf16_f32 v149, v150, v151
	v_add_f32_e32 v135, 1.0, v135
	v_rcp_f32_e32 v159, v135
	v_cvt_pk_bf16_f32 v150, v152, v153
	v_pk_add_f32 v[154:155], v[160:161], v[154:155] op_sel_hi:[0,1]
	v_pk_mul_f32 v[144:145], v[98:99], v[158:159]
	s_nop 0
	v_mov_b32_e32 v152, v144
	v_mov_b32_e32 v157, v145
	v_pk_fma_f32 v[152:153], v[152:153], v[152:153], v[154:155]
	v_pk_fma_f32 v[154:155], v[98:99], v[158:159], v[156:157]
	v_pk_mul_f32 v[156:157], v[144:145], v[144:145]
	v_pk_mov_b32 v[152:153], v[144:145], v[152:153] op_sel:[1,0]
	v_mov_b32_e32 v155, v157
	v_pk_add_f32 v[152:153], v[154:155], v[152:153]
	v_cvt_pk_bf16_f32 v151, v144, v145
	global_store_dwordx4 v[142:143], v[148:151], off offset:256 nt
	ds_bpermute_b32 v142, v146, v152
	ds_bpermute_b32 v143, v146, v153
	s_waitcnt lgkmcnt(0)
	v_pk_add_f32 v[142:143], v[152:153], v[142:143]
	ds_bpermute_b32 v144, v137, v142
	ds_bpermute_b32 v145, v137, v143
	s_and_saveexec_b64 s[4:5], vcc
	s_cbranch_execz .LBB0_184
	v_lshlrev_b64 v[140:141], 8, v[140:141]
	v_lshl_add_u64 v[140:141], s[40:41], 0, v[140:141]
	s_waitcnt lgkmcnt(0)
	v_pk_add_f32 v[142:143], v[142:143], v[144:145]
	v_lshl_add_u64 v[140:141], s[14:15], 3, v[140:141]
	global_store_dwordx2 v[140:141], v[142:143], off
.LBB0_184:
	s_or_b64 exec, exec, s[4:5]
	v_mul_f32_e32 v147, 0x3d922279, v94
	v_fmaak_f32 v147, v94, v147, 0x3fcc422a
	v_mul_f32_e32 v147, v94, v147
	v_mul_f32_e32 v147, 0xbfb8aa3b, v147
	v_exp_f32_e32 v147, v147
	v_mul_f32_e32 v135, 0x3d922279, v92
	v_fmaak_f32 v135, v92, v135, 0x3fcc422a
	v_mul_f32_e32 v135, v92, v135
	v_add_f32_e32 v147, 1.0, v147
	v_rcp_f32_e32 v150, v147
	v_mul_f32_e32 v147, 0x3d922279, v95
	v_fmaak_f32 v147, v95, v147, 0x3fcc422a
	v_mul_f32_e32 v147, v95, v147
	v_mul_f32_e32 v147, 0xbfb8aa3b, v147
	v_exp_f32_e32 v147, v147
	v_mul_f32_e32 v135, 0xbfb8aa3b, v135
	v_exp_f32_e32 v135, v135
	v_add_u32_e32 v140, 32, v134
	v_add_f32_e32 v147, 1.0, v147
	v_rcp_f32_e32 v151, v147
	v_mul_f32_e32 v147, 0x3d922279, v84
	v_fmaak_f32 v147, v84, v147, 0x3fcc422a
	v_mul_f32_e32 v147, v84, v147
	v_mul_f32_e32 v147, 0xbfb8aa3b, v147
	v_exp_f32_e32 v147, v147
	v_add_f32_e32 v135, 1.0, v135
	s_waitcnt lgkmcnt(0)
; __device__ __forceinline__ unsigned pk2(float lo, float hi) { return __builtin_bit_cast(unsigned, __builtin_convertvector((f32x2){lo, hi}, bf16x2_t)); }
; __device__ __forceinline__ float fgelu(float x) { return x * fsigmoid(x * (1.5957691216f + 0.0713548163f * x * x)); }
;     __device__ __forceinline__ void operator()(f32x4 (&acc)[2][2][4][2], const pg8::Unit& u, int wr, int wc, int fr, int fq) const {
;     ...
;                     const int row = row0 + ai * 128 + m * 16;
;                     float s1 = 0.f, s2 = 0.f;
; #pragma unroll
;                     for (int bj = 0; bj < 2; ++bj) {
;                         float y[8];
; #pragma unroll
;                         for (int n = 0; n < 2; ++n)
; #pragma unroll
;                             for (int j = 0; j < 4; ++j) { const float v = fgelu(acc[ai][bj][m][n][j]); y[4 * n + j] = v; s1 += v; s2 += v * v; }
;                         *(u32x4*)(G + (size_t)row * BW + bj * 128) = (u32x4){pk2(y[0], y[1]), pk2(y[2], y[3]), pk2(y[4], y[5]), pk2(y[6], y[7])};
;                     }
;                     s1 += __shfl_xor(s1, 16); s1 += __shfl_xor(s1, 32);
;                     s2 += __shfl_xor(s2, 16); s2 += __shfl_xor(s2, 32);
;                     if (fq == 0) *(f32x2*)(lns + ((size_t)row * 32 + (tile - 16) * 4 + wc) * 2) = (f32x2){s1, s2};
	v_rcp_f32_e32 v144, v135
	v_mul_f32_e32 v135, 0x3d922279, v93
	v_add_f32_e32 v147, 1.0, v147
	v_rcp_f32_e32 v152, v147
	v_mul_f32_e32 v147, 0x3d922279, v85
	v_fmaak_f32 v135, v93, v135, 0x3fcc422a
	v_fmaak_f32 v147, v85, v147, 0x3fcc422a
	v_mul_f32_e32 v135, v93, v135
	v_mul_f32_e32 v147, v85, v147
	v_mul_f32_e32 v135, 0xbfb8aa3b, v135
	v_mul_f32_e32 v147, 0xbfb8aa3b, v147
	v_exp_f32_e32 v135, v135
	v_exp_f32_e32 v147, v147
	v_pk_mul_f32 v[150:151], v[94:95], v[150:151]
	v_ashrrev_i32_e32 v141, 31, v140
	v_add_f32_e32 v135, 1.0, v135
	v_add_f32_e32 v147, 1.0, v147
	v_rcp_f32_e32 v145, v135
	v_rcp_f32_e32 v153, v147
	v_mul_f32_e32 v147, 0x3d922279, v86
	v_fmaak_f32 v147, v86, v147, 0x3fcc422a
	v_mul_f32_e32 v147, v86, v147
	v_mul_f32_e32 v147, 0xbfb8aa3b, v147
	v_pk_mul_f32 v[144:145], v[92:93], v[144:145]
	v_exp_f32_e32 v147, v147
	v_mul_f32_e32 v148, v145, v145
	v_pk_fma_f32 v[148:149], v[144:145], v[144:145], v[148:149] op_sel_hi:[1,1,0]
	v_pk_mul_f32 v[152:153], v[84:85], v[152:153]
	v_pk_fma_f32 v[148:149], v[150:151], v[150:151], v[148:149]
	v_mul_f32_e32 v156, v151, v151
	v_mov_b32_e32 v154, v152
	v_mov_b32_e32 v155, v151
	v_pk_add_f32 v[148:149], v[156:157], v[148:149] op_sel_hi:[0,1]
	v_add_f32_e32 v147, 1.0, v147
	v_pk_fma_f32 v[148:149], v[154:155], v[154:155], v[148:149]
	v_rcp_f32_e32 v154, v147
	v_mul_f32_e32 v147, 0x3d922279, v87
	v_fmaak_f32 v147, v87, v147, 0x3fcc422a
	v_mul_f32_e32 v147, v87, v147
	v_mul_f32_e32 v147, 0xbfb8aa3b, v147
	v_exp_f32_e32 v147, v147
	v_mul_f32_e32 v158, v153, v153
	v_add_f32_e32 v135, 0, v144
	v_mov_b32_e32 v157, v153
	v_add_f32_e32 v147, 1.0, v147
	v_rcp_f32_e32 v155, v147
	v_pk_add_f32 v[148:149], v[158:159], v[148:149] op_sel_hi:[0,1]
	v_add_f32_e32 v135, v145, v135
	v_mul_f32_e32 v147, 0x3d922279, v90
	v_pk_mul_f32 v[154:155], v[86:87], v[154:155]
	v_fmaak_f32 v147, v90, v147, 0x3fcc422a
	v_mov_b32_e32 v156, v154
	v_pk_fma_f32 v[156:157], v[156:157], v[156:157], v[148:149]
	v_cvt_pk_bf16_f32 v148, v144, v145
	v_mul_f32_e32 v144, 0x3d922279, v88
	v_mul_f32_e32 v145, 0x3d922279, v89
	v_fmaak_f32 v144, v88, v144, 0x3fcc422a
	v_fmaak_f32 v145, v89, v145, 0x3fcc422a
	v_mul_f32_e32 v144, v88, v144
	v_mul_f32_e32 v145, v89, v145
	v_mul_f32_e32 v144, 0xbfb8aa3b, v144
	v_mul_f32_e32 v145, 0xbfb8aa3b, v145
	v_exp_f32_e32 v144, v144
	v_exp_f32_e32 v145, v145
	v_mul_f32_e32 v147, v90, v147
	v_mul_f32_e32 v147, 0xbfb8aa3b, v147
	v_add_f32_e32 v144, 1.0, v144
	v_add_f32_e32 v145, 1.0, v145
	v_rcp_f32_e32 v144, v144
	v_rcp_f32_e32 v145, v145
	v_exp_f32_e32 v147, v147
	v_lshlrev_b64 v[142:143], 12, v[140:141]
	v_add_f32_e32 v135, v150, v135
	v_lshl_add_u64 v[142:143], v[138:139], 0, v[142:143]
	v_add_f32_e32 v135, v151, v135
	v_cvt_pk_bf16_f32 v149, v150, v151
	v_cvt_pk_bf16_f32 v150, v152, v153
	v_cvt_pk_bf16_f32 v151, v154, v155
	v_pk_mul_f32 v[144:145], v[88:89], v[144:145]
	global_store_dwordx4 v[142:143], v[148:151], off nt
	v_add_f32_e32 v147, 1.0, v147
	v_add_f32_e32 v135, v152, v135
	v_pk_mov_b32 v[148:149], v[154:155], v[144:145] op_sel:[1,0]
	v_mul_f32_e32 v150, v144, v144
	v_pk_fma_f32 v[148:149], v[148:149], v[148:149], v[156:157]
	v_add_f32_e32 v135, v153, v135
	v_pk_add_f32 v[148:149], v[148:149], v[150:151] op_sel_hi:[1,0]
	v_rcp_f32_e32 v150, v147
	v_mul_f32_e32 v147, 0x3d922279, v91
	v_fmaak_f32 v147, v91, v147, 0x3fcc422a
	v_mul_f32_e32 v147, v91, v147
	v_mul_f32_e32 v147, 0xbfb8aa3b, v147
	v_exp_f32_e32 v147, v147
	v_add_f32_e32 v135, v154, v135
	v_mul_f32_e32 v154, v145, v145
	v_mov_b32_e32 v153, v145
	v_add_f32_e32 v147, 1.0, v147
	v_rcp_f32_e32 v151, v147
	v_mul_f32_e32 v147, 0x3d922279, v80
	v_fmaak_f32 v147, v80, v147, 0x3fcc422a
	v_mul_f32_e32 v147, v80, v147
	v_mul_f32_e32 v147, 0xbfb8aa3b, v147
	v_exp_f32_e32 v147, v147
	v_pk_mul_f32 v[150:151], v[90:91], v[150:151]
	v_pk_add_f32 v[148:149], v[154:155], v[148:149] op_sel_hi:[0,1]
	v_mov_b32_e32 v152, v150
	v_add_f32_e32 v147, 1.0, v147
	v_pk_fma_f32 v[148:149], v[152:153], v[152:153], v[148:149]
	v_rcp_f32_e32 v152, v147
	v_mul_f32_e32 v147, 0x3d922279, v81
	v_fmaak_f32 v147, v81, v147, 0x3fcc422a
	v_mul_f32_e32 v147, v81, v147
	v_mul_f32_e32 v147, 0xbfb8aa3b, v147
	v_exp_f32_e32 v147, v147
	v_add_f32_e32 v135, v155, v135
	v_add_f32_e32 v135, v135, v144
	v_add_f32_e32 v135, v145, v135
	v_add_f32_e32 v147, 1.0, v147
	v_rcp_f32_e32 v153, v147
	v_add_f32_e32 v135, v150, v135
	v_add_f32_e32 v135, v151, v135
	v_mul_f32_e32 v156, v151, v151
	v_pk_mul_f32 v[152:153], v[80:81], v[152:153]
	v_pk_add_f32 v[148:149], v[156:157], v[148:149] op_sel_hi:[0,1]
	v_add_f32_e32 v135, v152, v135
	v_add_f32_e32 v156, v153, v135
	v_mul_f32_e32 v135, 0x3d922279, v82
	v_fmaak_f32 v135, v82, v135, 0x3fcc422a
	v_mul_f32_e32 v135, v82, v135
	v_mul_f32_e32 v135, 0xbfb8aa3b, v135
	v_exp_f32_e32 v135, v135
	v_mov_b32_e32 v154, v152
	v_mov_b32_e32 v155, v151
	v_pk_fma_f32 v[154:155], v[154:155], v[154:155], v[148:149]
	v_add_f32_e32 v135, 1.0, v135
	v_rcp_f32_e32 v158, v135
	v_mul_f32_e32 v135, 0x3d922279, v83
	v_fmaak_f32 v135, v83, v135, 0x3fcc422a
	v_mul_f32_e32 v135, v83, v135
	v_mul_f32_e32 v135, 0xbfb8aa3b, v135
	v_exp_f32_e32 v135, v135
	v_cvt_pk_bf16_f32 v148, v144, v145
	v_mul_f32_e32 v160, v153, v153
	v_cvt_pk_bf16_f32 v149, v150, v151
	v_add_f32_e32 v135, 1.0, v135
	v_rcp_f32_e32 v159, v135
	v_cvt_pk_bf16_f32 v150, v152, v153
	v_pk_add_f32 v[154:155], v[160:161], v[154:155] op_sel_hi:[0,1]
	v_pk_mul_f32 v[144:145], v[82:83], v[158:159]
	s_nop 0
	v_mov_b32_e32 v152, v144
	v_mov_b32_e32 v157, v145
	v_pk_fma_f32 v[152:153], v[152:153], v[152:153], v[154:155]
	v_pk_fma_f32 v[154:155], v[82:83], v[158:159], v[156:157]
	v_pk_mul_f32 v[156:157], v[144:145], v[144:145]
	v_pk_mov_b32 v[152:153], v[144:145], v[152:153] op_sel:[1,0]
	v_mov_b32_e32 v155, v157
	v_pk_add_f32 v[152:153], v[154:155], v[152:153]
	v_cvt_pk_bf16_f32 v151, v144, v145
	global_store_dwordx4 v[142:143], v[148:151], off offset:256 nt
	ds_bpermute_b32 v142, v146, v152
	ds_bpermute_b32 v143, v146, v153
	s_waitcnt lgkmcnt(0)
	v_pk_add_f32 v[142:143], v[152:153], v[142:143]
	ds_bpermute_b32 v144, v137, v142
	ds_bpermute_b32 v145, v137, v143
	s_and_saveexec_b64 s[4:5], vcc
	s_cbranch_execz .LBB0_186
	v_lshlrev_b64 v[140:141], 8, v[140:141]
	v_lshl_add_u64 v[140:141], s[40:41], 0, v[140:141]
	s_waitcnt lgkmcnt(0)
	v_pk_add_f32 v[142:143], v[142:143], v[144:145]
	v_lshl_add_u64 v[140:141], s[14:15], 3, v[140:141]
	global_store_dwordx2 v[140:141], v[142:143], off
; __device__ __forceinline__ unsigned pk2(float lo, float hi) { return __builtin_bit_cast(unsigned, __builtin_convertvector((f32x2){lo, hi}, bf16x2_t)); }
; __device__ __forceinline__ float fgelu(float x) { return x * fsigmoid(x * (1.5957691216f + 0.0713548163f * x * x)); }
;     __device__ __forceinline__ void operator()(f32x4 (&acc)[2][2][4][2], const pg8::Unit& u, int wr, int wc, int fr, int fq) const {
;     ...
;                     const int row = row0 + ai * 128 + m * 16;
;                     float s1 = 0.f, s2 = 0.f;
; #pragma unroll
;                     for (int bj = 0; bj < 2; ++bj) {
;                         float y[8];
; #pragma unroll
;                         for (int n = 0; n < 2; ++n)
; #pragma unroll
;                             for (int j = 0; j < 4; ++j) { const float v = fgelu(acc[ai][bj][m][n][j]); y[4 * n + j] = v; s1 += v; s2 += v * v; }
;                         *(u32x4*)(G + (size_t)row * BW + bj * 128) = (u32x4){pk2(y[0], y[1]), pk2(y[2], y[3]), pk2(y[4], y[5]), pk2(y[6], y[7])};
;                     }
;                     s1 += __shfl_xor(s1, 16); s1 += __shfl_xor(s1, 32);
;                     s2 += __shfl_xor(s2, 16); s2 += __shfl_xor(s2, 32);
;                     if (fq == 0) *(f32x2*)(lns + ((size_t)row * 32 + (tile - 16) * 4 + wc) * 2) = (f32x2){s1, s2};
.LBB0_186:
	s_or_b64 exec, exec, s[4:5]
	v_mul_f32_e32 v147, 0x3d922279, v78
	v_fmaak_f32 v147, v78, v147, 0x3fcc422a
	v_mul_f32_e32 v147, v78, v147
	v_mul_f32_e32 v147, 0xbfb8aa3b, v147
	v_exp_f32_e32 v147, v147
	v_mul_f32_e32 v135, 0x3d922279, v76
	v_fmaak_f32 v135, v76, v135, 0x3fcc422a
	v_mul_f32_e32 v135, v76, v135
	v_add_f32_e32 v147, 1.0, v147
	v_rcp_f32_e32 v150, v147
	v_mul_f32_e32 v147, 0x3d922279, v79
	v_fmaak_f32 v147, v79, v147, 0x3fcc422a
	v_mul_f32_e32 v147, v79, v147
	v_mul_f32_e32 v147, 0xbfb8aa3b, v147
	v_exp_f32_e32 v147, v147
	v_mul_f32_e32 v135, 0xbfb8aa3b, v135
	v_exp_f32_e32 v135, v135
	v_add_u32_e32 v140, 48, v134
	v_add_f32_e32 v147, 1.0, v147
	v_rcp_f32_e32 v151, v147
	v_mul_f32_e32 v147, 0x3d922279, v68
	v_fmaak_f32 v147, v68, v147, 0x3fcc422a
	v_mul_f32_e32 v147, v68, v147
	v_mul_f32_e32 v147, 0xbfb8aa3b, v147
	v_exp_f32_e32 v147, v147
	v_add_f32_e32 v135, 1.0, v135
	s_waitcnt lgkmcnt(0)
	v_rcp_f32_e32 v144, v135
	v_mul_f32_e32 v135, 0x3d922279, v77
	v_add_f32_e32 v147, 1.0, v147
	v_rcp_f32_e32 v152, v147
	v_mul_f32_e32 v147, 0x3d922279, v69
	v_fmaak_f32 v135, v77, v135, 0x3fcc422a
	v_fmaak_f32 v147, v69, v147, 0x3fcc422a
	v_mul_f32_e32 v135, v77, v135
	v_mul_f32_e32 v147, v69, v147
	v_mul_f32_e32 v135, 0xbfb8aa3b, v135
	v_mul_f32_e32 v147, 0xbfb8aa3b, v147
	v_exp_f32_e32 v135, v135
	v_exp_f32_e32 v147, v147
	v_pk_mul_f32 v[150:151], v[78:79], v[150:151]
	v_ashrrev_i32_e32 v141, 31, v140
	v_add_f32_e32 v135, 1.0, v135
	v_add_f32_e32 v147, 1.0, v147
	v_rcp_f32_e32 v145, v135
	v_rcp_f32_e32 v153, v147
	v_mul_f32_e32 v147, 0x3d922279, v70
	v_fmaak_f32 v147, v70, v147, 0x3fcc422a
	v_mul_f32_e32 v147, v70, v147
	v_mul_f32_e32 v147, 0xbfb8aa3b, v147
	v_pk_mul_f32 v[144:145], v[76:77], v[144:145]
	v_exp_f32_e32 v147, v147
	v_mul_f32_e32 v148, v145, v145
	v_pk_fma_f32 v[148:149], v[144:145], v[144:145], v[148:149] op_sel_hi:[1,1,0]
	v_pk_mul_f32 v[152:153], v[68:69], v[152:153]
	v_pk_fma_f32 v[148:149], v[150:151], v[150:151], v[148:149]
	v_mul_f32_e32 v156, v151, v151
	v_mov_b32_e32 v154, v152
	v_mov_b32_e32 v155, v151
	v_pk_add_f32 v[148:149], v[156:157], v[148:149] op_sel_hi:[0,1]
	v_add_f32_e32 v147, 1.0, v147
	v_pk_fma_f32 v[148:149], v[154:155], v[154:155], v[148:149]
	v_rcp_f32_e32 v154, v147
	v_mul_f32_e32 v147, 0x3d922279, v71
	v_fmaak_f32 v147, v71, v147, 0x3fcc422a
	v_mul_f32_e32 v147, v71, v147
	v_mul_f32_e32 v147, 0xbfb8aa3b, v147
	v_exp_f32_e32 v147, v147
	v_mul_f32_e32 v158, v153, v153
	v_add_f32_e32 v135, 0, v144
	v_mov_b32_e32 v157, v153
	v_add_f32_e32 v147, 1.0, v147
	v_rcp_f32_e32 v155, v147
	v_pk_add_f32 v[148:149], v[158:159], v[148:149] op_sel_hi:[0,1]
	v_add_f32_e32 v135, v145, v135
	v_mul_f32_e32 v147, 0x3d922279, v74
	v_pk_mul_f32 v[154:155], v[70:71], v[154:155]
	v_fmaak_f32 v147, v74, v147, 0x3fcc422a
	v_mov_b32_e32 v156, v154
	v_pk_fma_f32 v[156:157], v[156:157], v[156:157], v[148:149]
	v_cvt_pk_bf16_f32 v148, v144, v145
	v_mul_f32_e32 v144, 0x3d922279, v72
	v_mul_f32_e32 v145, 0x3d922279, v73
	v_fmaak_f32 v144, v72, v144, 0x3fcc422a
	v_fmaak_f32 v145, v73, v145, 0x3fcc422a
	v_mul_f32_e32 v144, v72, v144
	v_mul_f32_e32 v145, v73, v145
	v_mul_f32_e32 v144, 0xbfb8aa3b, v144
	v_mul_f32_e32 v145, 0xbfb8aa3b, v145
	v_exp_f32_e32 v144, v144
	v_exp_f32_e32 v145, v145
	v_mul_f32_e32 v147, v74, v147
	v_mul_f32_e32 v147, 0xbfb8aa3b, v147
	v_add_f32_e32 v144, 1.0, v144
	v_add_f32_e32 v145, 1.0, v145
	v_rcp_f32_e32 v144, v144
	v_rcp_f32_e32 v145, v145
	v_exp_f32_e32 v147, v147
	v_lshlrev_b64 v[142:143], 12, v[140:141]
	v_add_f32_e32 v135, v150, v135
	v_lshl_add_u64 v[142:143], v[138:139], 0, v[142:143]
	v_add_f32_e32 v135, v151, v135
	v_cvt_pk_bf16_f32 v149, v150, v151
	v_cvt_pk_bf16_f32 v150, v152, v153
	v_cvt_pk_bf16_f32 v151, v154, v155
	v_pk_mul_f32 v[144:145], v[72:73], v[144:145]
	global_store_dwordx4 v[142:143], v[148:151], off nt
	v_add_f32_e32 v147, 1.0, v147
	v_add_f32_e32 v135, v152, v135
	v_pk_mov_b32 v[148:149], v[154:155], v[144:145] op_sel:[1,0]
	v_mul_f32_e32 v150, v144, v144
	v_pk_fma_f32 v[148:149], v[148:149], v[148:149], v[156:157]
	v_add_f32_e32 v135, v153, v135
	v_pk_add_f32 v[148:149], v[148:149], v[150:151] op_sel_hi:[1,0]
	v_rcp_f32_e32 v150, v147
	v_mul_f32_e32 v147, 0x3d922279, v75
	v_fmaak_f32 v147, v75, v147, 0x3fcc422a
	v_mul_f32_e32 v147, v75, v147
	v_mul_f32_e32 v147, 0xbfb8aa3b, v147
	v_exp_f32_e32 v147, v147
	v_add_f32_e32 v135, v154, v135
	v_mul_f32_e32 v154, v145, v145
	v_mov_b32_e32 v153, v145
	v_add_f32_e32 v147, 1.0, v147
	v_rcp_f32_e32 v151, v147
	v_mul_f32_e32 v147, 0x3d922279, v64
	v_fmaak_f32 v147, v64, v147, 0x3fcc422a
	v_mul_f32_e32 v147, v64, v147
	v_mul_f32_e32 v147, 0xbfb8aa3b, v147
	v_exp_f32_e32 v147, v147
	v_pk_mul_f32 v[150:151], v[74:75], v[150:151]
	v_pk_add_f32 v[148:149], v[154:155], v[148:149] op_sel_hi:[0,1]
	v_mov_b32_e32 v152, v150
	v_add_f32_e32 v147, 1.0, v147
	v_pk_fma_f32 v[148:149], v[152:153], v[152:153], v[148:149]
	v_rcp_f32_e32 v152, v147
	v_mul_f32_e32 v147, 0x3d922279, v65
	v_fmaak_f32 v147, v65, v147, 0x3fcc422a
	v_mul_f32_e32 v147, v65, v147
	v_mul_f32_e32 v147, 0xbfb8aa3b, v147
	v_exp_f32_e32 v147, v147
	v_add_f32_e32 v135, v155, v135
	v_add_f32_e32 v135, v135, v144
	v_add_f32_e32 v135, v145, v135
	v_add_f32_e32 v147, 1.0, v147
	v_rcp_f32_e32 v153, v147
	v_add_f32_e32 v135, v150, v135
	v_add_f32_e32 v135, v151, v135
	v_mul_f32_e32 v156, v151, v151
	v_pk_mul_f32 v[152:153], v[64:65], v[152:153]
	v_pk_add_f32 v[148:149], v[156:157], v[148:149] op_sel_hi:[0,1]
	v_add_f32_e32 v135, v152, v135
	v_add_f32_e32 v156, v153, v135
	v_mul_f32_e32 v135, 0x3d922279, v66
	v_fmaak_f32 v135, v66, v135, 0x3fcc422a
	v_mul_f32_e32 v135, v66, v135
	v_mul_f32_e32 v135, 0xbfb8aa3b, v135
	v_exp_f32_e32 v135, v135
	v_mov_b32_e32 v154, v152
	v_mov_b32_e32 v155, v151
	v_pk_fma_f32 v[154:155], v[154:155], v[154:155], v[148:149]
	v_add_f32_e32 v135, 1.0, v135
	v_rcp_f32_e32 v158, v135
	v_mul_f32_e32 v135, 0x3d922279, v67
	v_fmaak_f32 v135, v67, v135, 0x3fcc422a
	v_mul_f32_e32 v135, v67, v135
	v_mul_f32_e32 v135, 0xbfb8aa3b, v135
	v_exp_f32_e32 v135, v135
	v_cvt_pk_bf16_f32 v148, v144, v145
	v_mul_f32_e32 v160, v153, v153
	v_cvt_pk_bf16_f32 v149, v150, v151
	v_add_f32_e32 v135, 1.0, v135
	v_rcp_f32_e32 v159, v135
	v_cvt_pk_bf16_f32 v150, v152, v153
	v_pk_add_f32 v[154:155], v[160:161], v[154:155] op_sel_hi:[0,1]
	v_pk_mul_f32 v[144:145], v[66:67], v[158:159]
	s_nop 0
	v_mov_b32_e32 v152, v144
	v_mov_b32_e32 v157, v145
	v_pk_fma_f32 v[152:153], v[152:153], v[152:153], v[154:155]
	v_pk_fma_f32 v[154:155], v[66:67], v[158:159], v[156:157]
	v_pk_mul_f32 v[156:157], v[144:145], v[144:145]
	v_pk_mov_b32 v[152:153], v[144:145], v[152:153] op_sel:[1,0]
	v_mov_b32_e32 v155, v157
	v_pk_add_f32 v[152:153], v[154:155], v[152:153]
	v_cvt_pk_bf16_f32 v151, v144, v145
	global_store_dwordx4 v[142:143], v[148:151], off offset:256 nt
	ds_bpermute_b32 v142, v146, v152
	ds_bpermute_b32 v143, v146, v153
	s_waitcnt lgkmcnt(0)
; __device__ __forceinline__ unsigned pk2(float lo, float hi) { return __builtin_bit_cast(unsigned, __builtin_convertvector((f32x2){lo, hi}, bf16x2_t)); }
; __device__ __forceinline__ float fgelu(float x) { return x * fsigmoid(x * (1.5957691216f + 0.0713548163f * x * x)); }
;     __device__ __forceinline__ void operator()(f32x4 (&acc)[2][2][4][2], const pg8::Unit& u, int wr, int wc, int fr, int fq) const {
;     ...
;                     const int row = row0 + ai * 128 + m * 16;
;                     float s1 = 0.f, s2 = 0.f;
; #pragma unroll
;                     for (int bj = 0; bj < 2; ++bj) {
;                         float y[8];
; #pragma unroll
;                         for (int n = 0; n < 2; ++n)
; #pragma unroll
;                             for (int j = 0; j < 4; ++j) { const float v = fgelu(acc[ai][bj][m][n][j]); y[4 * n + j] = v; s1 += v; s2 += v * v; }
;                         *(u32x4*)(G + (size_t)row * BW + bj * 128) = (u32x4){pk2(y[0], y[1]), pk2(y[2], y[3]), pk2(y[4], y[5]), pk2(y[6], y[7])};
;                     }
;                     s1 += __shfl_xor(s1, 16); s1 += __shfl_xor(s1, 32);
;                     s2 += __shfl_xor(s2, 16); s2 += __shfl_xor(s2, 32);
;                     if (fq == 0) *(f32x2*)(lns + ((size_t)row * 32 + (tile - 16) * 4 + wc) * 2) = (f32x2){s1, s2};
	v_pk_add_f32 v[142:143], v[152:153], v[142:143]
	ds_bpermute_b32 v144, v137, v142
	ds_bpermute_b32 v145, v137, v143
	s_and_saveexec_b64 s[4:5], vcc
	s_cbranch_execz .LBB0_188
	v_lshlrev_b64 v[140:141], 8, v[140:141]
	v_lshl_add_u64 v[140:141], s[40:41], 0, v[140:141]
	s_waitcnt lgkmcnt(0)
	v_pk_add_f32 v[142:143], v[142:143], v[144:145]
	v_lshl_add_u64 v[140:141], s[14:15], 3, v[140:141]
	global_store_dwordx2 v[140:141], v[142:143], off
.LBB0_188:
	s_or_b64 exec, exec, s[4:5]
	v_mul_f32_e32 v147, 0x3d922279, v62
	v_fmaak_f32 v147, v62, v147, 0x3fcc422a
	v_mul_f32_e32 v147, v62, v147
	v_mul_f32_e32 v147, 0xbfb8aa3b, v147
	v_exp_f32_e32 v147, v147
	v_mul_f32_e32 v135, 0x3d922279, v60
	v_fmaak_f32 v135, v60, v135, 0x3fcc422a
	v_mul_f32_e32 v135, v60, v135
	v_add_f32_e32 v147, 1.0, v147
	v_rcp_f32_e32 v150, v147
	v_mul_f32_e32 v147, 0x3d922279, v63
	v_fmaak_f32 v147, v63, v147, 0x3fcc422a
	v_mul_f32_e32 v147, v63, v147
	v_mul_f32_e32 v147, 0xbfb8aa3b, v147
	v_exp_f32_e32 v147, v147
	v_mul_f32_e32 v135, 0xbfb8aa3b, v135
	v_exp_f32_e32 v135, v135
	v_add_u32_e32 v140, 0x80, v134
	v_add_f32_e32 v147, 1.0, v147
	v_rcp_f32_e32 v151, v147
	v_mul_f32_e32 v147, 0x3d922279, v52
	v_fmaak_f32 v147, v52, v147, 0x3fcc422a
	v_mul_f32_e32 v147, v52, v147
	v_mul_f32_e32 v147, 0xbfb8aa3b, v147
	v_exp_f32_e32 v147, v147
	v_add_f32_e32 v135, 1.0, v135
	s_waitcnt lgkmcnt(0)
	v_rcp_f32_e32 v144, v135
	v_mul_f32_e32 v135, 0x3d922279, v61
	v_add_f32_e32 v147, 1.0, v147
	v_rcp_f32_e32 v152, v147
	v_mul_f32_e32 v147, 0x3d922279, v53
	v_fmaak_f32 v135, v61, v135, 0x3fcc422a
	v_fmaak_f32 v147, v53, v147, 0x3fcc422a
	v_mul_f32_e32 v135, v61, v135
	v_mul_f32_e32 v147, v53, v147
	v_mul_f32_e32 v135, 0xbfb8aa3b, v135
	v_mul_f32_e32 v147, 0xbfb8aa3b, v147
	v_exp_f32_e32 v135, v135
	v_exp_f32_e32 v147, v147
	v_pk_mul_f32 v[150:151], v[62:63], v[150:151]
	v_ashrrev_i32_e32 v141, 31, v140
	v_add_f32_e32 v135, 1.0, v135
	v_add_f32_e32 v147, 1.0, v147
	v_rcp_f32_e32 v145, v135
	v_rcp_f32_e32 v153, v147
	v_mul_f32_e32 v147, 0x3d922279, v54
	v_fmaak_f32 v147, v54, v147, 0x3fcc422a
	v_mul_f32_e32 v147, v54, v147
	v_mul_f32_e32 v147, 0xbfb8aa3b, v147
	v_pk_mul_f32 v[144:145], v[60:61], v[144:145]
	v_exp_f32_e32 v147, v147
	v_mul_f32_e32 v148, v145, v145
	v_pk_fma_f32 v[148:149], v[144:145], v[144:145], v[148:149] op_sel_hi:[1,1,0]
	v_pk_mul_f32 v[152:153], v[52:53], v[152:153]
	v_pk_fma_f32 v[148:149], v[150:151], v[150:151], v[148:149]
	v_mul_f32_e32 v156, v151, v151
	v_mov_b32_e32 v154, v152
	v_mov_b32_e32 v155, v151
	v_pk_add_f32 v[148:149], v[156:157], v[148:149] op_sel_hi:[0,1]
	v_add_f32_e32 v147, 1.0, v147
	v_pk_fma_f32 v[148:149], v[154:155], v[154:155], v[148:149]
	v_rcp_f32_e32 v154, v147
	v_mul_f32_e32 v147, 0x3d922279, v55
	v_fmaak_f32 v147, v55, v147, 0x3fcc422a
	v_mul_f32_e32 v147, v55, v147
	v_mul_f32_e32 v147, 0xbfb8aa3b, v147
	v_exp_f32_e32 v147, v147
	v_mul_f32_e32 v158, v153, v153
	v_add_f32_e32 v135, 0, v144
	v_mov_b32_e32 v157, v153
	v_add_f32_e32 v147, 1.0, v147
	v_rcp_f32_e32 v155, v147
	v_pk_add_f32 v[148:149], v[158:159], v[148:149] op_sel_hi:[0,1]
	v_add_f32_e32 v135, v145, v135
	v_mul_f32_e32 v147, 0x3d922279, v58
	v_pk_mul_f32 v[154:155], v[54:55], v[154:155]
	v_fmaak_f32 v147, v58, v147, 0x3fcc422a
	v_mov_b32_e32 v156, v154
	v_pk_fma_f32 v[156:157], v[156:157], v[156:157], v[148:149]
	v_cvt_pk_bf16_f32 v148, v144, v145
	v_mul_f32_e32 v144, 0x3d922279, v56
	v_mul_f32_e32 v145, 0x3d922279, v57
	v_fmaak_f32 v144, v56, v144, 0x3fcc422a
	v_fmaak_f32 v145, v57, v145, 0x3fcc422a
	v_mul_f32_e32 v144, v56, v144
	v_mul_f32_e32 v145, v57, v145
	v_mul_f32_e32 v144, 0xbfb8aa3b, v144
	v_mul_f32_e32 v145, 0xbfb8aa3b, v145
	v_exp_f32_e32 v144, v144
	v_exp_f32_e32 v145, v145
	v_mul_f32_e32 v147, v58, v147
	v_mul_f32_e32 v147, 0xbfb8aa3b, v147
	v_add_f32_e32 v144, 1.0, v144
	v_add_f32_e32 v145, 1.0, v145
	v_rcp_f32_e32 v144, v144
	v_rcp_f32_e32 v145, v145
	v_exp_f32_e32 v147, v147
	v_lshlrev_b64 v[142:143], 12, v[140:141]
	v_add_f32_e32 v135, v150, v135
	v_lshl_add_u64 v[142:143], v[138:139], 0, v[142:143]
	v_add_f32_e32 v135, v151, v135
	v_cvt_pk_bf16_f32 v149, v150, v151
	v_cvt_pk_bf16_f32 v150, v152, v153
	v_cvt_pk_bf16_f32 v151, v154, v155
	v_pk_mul_f32 v[144:145], v[56:57], v[144:145]
	global_store_dwordx4 v[142:143], v[148:151], off nt
	v_add_f32_e32 v147, 1.0, v147
	v_add_f32_e32 v135, v152, v135
	v_pk_mov_b32 v[148:149], v[154:155], v[144:145] op_sel:[1,0]
	v_mul_f32_e32 v150, v144, v144
	v_pk_fma_f32 v[148:149], v[148:149], v[148:149], v[156:157]
	v_add_f32_e32 v135, v153, v135
	v_pk_add_f32 v[148:149], v[148:149], v[150:151] op_sel_hi:[1,0]
	v_rcp_f32_e32 v150, v147
	v_mul_f32_e32 v147, 0x3d922279, v59
	v_fmaak_f32 v147, v59, v147, 0x3fcc422a
	v_mul_f32_e32 v147, v59, v147
	v_mul_f32_e32 v147, 0xbfb8aa3b, v147
	v_exp_f32_e32 v147, v147
	v_add_f32_e32 v135, v154, v135
	v_mul_f32_e32 v154, v145, v145
	v_mov_b32_e32 v153, v145
	v_add_f32_e32 v147, 1.0, v147
	v_rcp_f32_e32 v151, v147
	v_mul_f32_e32 v147, 0x3d922279, v48
	v_fmaak_f32 v147, v48, v147, 0x3fcc422a
	v_mul_f32_e32 v147, v48, v147
	v_mul_f32_e32 v147, 0xbfb8aa3b, v147
	v_exp_f32_e32 v147, v147
	v_pk_mul_f32 v[150:151], v[58:59], v[150:151]
	v_pk_add_f32 v[148:149], v[154:155], v[148:149] op_sel_hi:[0,1]
	v_mov_b32_e32 v152, v150
	v_add_f32_e32 v147, 1.0, v147
	v_pk_fma_f32 v[148:149], v[152:153], v[152:153], v[148:149]
	v_rcp_f32_e32 v152, v147
	v_mul_f32_e32 v147, 0x3d922279, v49
	v_fmaak_f32 v147, v49, v147, 0x3fcc422a
	v_mul_f32_e32 v147, v49, v147
	v_mul_f32_e32 v147, 0xbfb8aa3b, v147
	v_exp_f32_e32 v147, v147
	v_add_f32_e32 v135, v155, v135
	v_add_f32_e32 v135, v135, v144
	v_add_f32_e32 v135, v145, v135
; __device__ __forceinline__ unsigned pk2(float lo, float hi) { return __builtin_bit_cast(unsigned, __builtin_convertvector((f32x2){lo, hi}, bf16x2_t)); }
; __device__ __forceinline__ float fgelu(float x) { return x * fsigmoid(x * (1.5957691216f + 0.0713548163f * x * x)); }
;     __device__ __forceinline__ void operator()(f32x4 (&acc)[2][2][4][2], const pg8::Unit& u, int wr, int wc, int fr, int fq) const {
;     ...
;                     const int row = row0 + ai * 128 + m * 16;
;                     float s1 = 0.f, s2 = 0.f;
; #pragma unroll
;                     for (int bj = 0; bj < 2; ++bj) {
;                         float y[8];
; #pragma unroll
;                         for (int n = 0; n < 2; ++n)
; #pragma unroll
;                             for (int j = 0; j < 4; ++j) { const float v = fgelu(acc[ai][bj][m][n][j]); y[4 * n + j] = v; s1 += v; s2 += v * v; }
;                         *(u32x4*)(G + (size_t)row * BW + bj * 128) = (u32x4){pk2(y[0], y[1]), pk2(y[2], y[3]), pk2(y[4], y[5]), pk2(y[6], y[7])};
;                     }
;                     s1 += __shfl_xor(s1, 16); s1 += __shfl_xor(s1, 32);
;                     s2 += __shfl_xor(s2, 16); s2 += __shfl_xor(s2, 32);
;                     if (fq == 0) *(f32x2*)(lns + ((size_t)row * 32 + (tile - 16) * 4 + wc) * 2) = (f32x2){s1, s2};
	v_add_f32_e32 v147, 1.0, v147
	v_rcp_f32_e32 v153, v147
	v_add_f32_e32 v135, v150, v135
	v_add_f32_e32 v135, v151, v135
	v_mul_f32_e32 v156, v151, v151
	v_pk_mul_f32 v[152:153], v[48:49], v[152:153]
	v_pk_add_f32 v[148:149], v[156:157], v[148:149] op_sel_hi:[0,1]
	v_add_f32_e32 v135, v152, v135
	v_add_f32_e32 v156, v153, v135
	v_mul_f32_e32 v135, 0x3d922279, v50
	v_fmaak_f32 v135, v50, v135, 0x3fcc422a
	v_mul_f32_e32 v135, v50, v135
	v_mul_f32_e32 v135, 0xbfb8aa3b, v135
	v_exp_f32_e32 v135, v135
	v_mov_b32_e32 v154, v152
	v_mov_b32_e32 v155, v151
	v_pk_fma_f32 v[154:155], v[154:155], v[154:155], v[148:149]
	v_add_f32_e32 v135, 1.0, v135
	v_rcp_f32_e32 v158, v135
	v_mul_f32_e32 v135, 0x3d922279, v51
	v_fmaak_f32 v135, v51, v135, 0x3fcc422a
	v_mul_f32_e32 v135, v51, v135
	v_mul_f32_e32 v135, 0xbfb8aa3b, v135
	v_exp_f32_e32 v135, v135
	v_cvt_pk_bf16_f32 v148, v144, v145
	v_mul_f32_e32 v160, v153, v153
	v_cvt_pk_bf16_f32 v149, v150, v151
	v_add_f32_e32 v135, 1.0, v135
	v_rcp_f32_e32 v159, v135
	v_cvt_pk_bf16_f32 v150, v152, v153
	v_pk_add_f32 v[154:155], v[160:161], v[154:155] op_sel_hi:[0,1]
	v_pk_mul_f32 v[144:145], v[50:51], v[158:159]
	s_nop 0
	v_mov_b32_e32 v152, v144
	v_mov_b32_e32 v157, v145
	v_pk_fma_f32 v[152:153], v[152:153], v[152:153], v[154:155]
	v_pk_fma_f32 v[154:155], v[50:51], v[158:159], v[156:157]
	v_pk_mul_f32 v[156:157], v[144:145], v[144:145]
	v_pk_mov_b32 v[152:153], v[144:145], v[152:153] op_sel:[1,0]
	v_mov_b32_e32 v155, v157
	v_pk_add_f32 v[152:153], v[154:155], v[152:153]
	v_cvt_pk_bf16_f32 v151, v144, v145
	global_store_dwordx4 v[142:143], v[148:151], off offset:256 nt
	ds_bpermute_b32 v142, v146, v152
	ds_bpermute_b32 v143, v146, v153
	s_waitcnt lgkmcnt(0)
	v_pk_add_f32 v[142:143], v[152:153], v[142:143]
	ds_bpermute_b32 v144, v137, v142
	ds_bpermute_b32 v145, v137, v143
	s_and_saveexec_b64 s[4:5], vcc
	s_cbranch_execz .LBB0_190
	v_lshlrev_b64 v[140:141], 8, v[140:141]
	v_lshl_add_u64 v[140:141], s[40:41], 0, v[140:141]
	s_waitcnt lgkmcnt(0)
	v_pk_add_f32 v[142:143], v[142:143], v[144:145]
	v_lshl_add_u64 v[140:141], s[14:15], 3, v[140:141]
	global_store_dwordx2 v[140:141], v[142:143], off
.LBB0_190:
	s_or_b64 exec, exec, s[4:5]
	v_mul_f32_e32 v147, 0x3d922279, v46
	v_fmaak_f32 v147, v46, v147, 0x3fcc422a
	v_mul_f32_e32 v147, v46, v147
	v_mul_f32_e32 v147, 0xbfb8aa3b, v147
	v_exp_f32_e32 v147, v147
	v_mul_f32_e32 v135, 0x3d922279, v44
	v_fmaak_f32 v135, v44, v135, 0x3fcc422a
	v_mul_f32_e32 v135, v44, v135
	v_add_f32_e32 v147, 1.0, v147
	v_rcp_f32_e32 v150, v147
	v_mul_f32_e32 v147, 0x3d922279, v47
	v_fmaak_f32 v147, v47, v147, 0x3fcc422a
	v_mul_f32_e32 v147, v47, v147
	v_mul_f32_e32 v147, 0xbfb8aa3b, v147
	v_exp_f32_e32 v147, v147
	v_mul_f32_e32 v135, 0xbfb8aa3b, v135
	v_exp_f32_e32 v135, v135
	v_add_u32_e32 v140, 0x90, v134
	v_add_f32_e32 v147, 1.0, v147
	v_rcp_f32_e32 v151, v147
	v_mul_f32_e32 v147, 0x3d922279, v36
	v_fmaak_f32 v147, v36, v147, 0x3fcc422a
	v_mul_f32_e32 v147, v36, v147
	v_mul_f32_e32 v147, 0xbfb8aa3b, v147
	v_exp_f32_e32 v147, v147
	v_add_f32_e32 v135, 1.0, v135
	s_waitcnt lgkmcnt(0)
	v_rcp_f32_e32 v144, v135
	v_mul_f32_e32 v135, 0x3d922279, v45
	v_add_f32_e32 v147, 1.0, v147
	v_rcp_f32_e32 v152, v147
	v_mul_f32_e32 v147, 0x3d922279, v37
	v_fmaak_f32 v135, v45, v135, 0x3fcc422a
	v_fmaak_f32 v147, v37, v147, 0x3fcc422a
	v_mul_f32_e32 v135, v45, v135
	v_mul_f32_e32 v147, v37, v147
	v_mul_f32_e32 v135, 0xbfb8aa3b, v135
	v_mul_f32_e32 v147, 0xbfb8aa3b, v147
	v_exp_f32_e32 v135, v135
	v_exp_f32_e32 v147, v147
	v_pk_mul_f32 v[150:151], v[46:47], v[150:151]
	v_ashrrev_i32_e32 v141, 31, v140
	v_add_f32_e32 v135, 1.0, v135
	v_add_f32_e32 v147, 1.0, v147
	v_rcp_f32_e32 v145, v135
	v_rcp_f32_e32 v153, v147
	v_mul_f32_e32 v147, 0x3d922279, v38
	v_fmaak_f32 v147, v38, v147, 0x3fcc422a
	v_mul_f32_e32 v147, v38, v147
	v_mul_f32_e32 v147, 0xbfb8aa3b, v147
	v_pk_mul_f32 v[144:145], v[44:45], v[144:145]
	v_exp_f32_e32 v147, v147
	v_mul_f32_e32 v148, v145, v145
	v_pk_fma_f32 v[148:149], v[144:145], v[144:145], v[148:149] op_sel_hi:[1,1,0]
	v_pk_mul_f32 v[152:153], v[36:37], v[152:153]
	v_pk_fma_f32 v[148:149], v[150:151], v[150:151], v[148:149]
	v_mul_f32_e32 v156, v151, v151
	v_mov_b32_e32 v154, v152
	v_mov_b32_e32 v155, v151
	v_pk_add_f32 v[148:149], v[156:157], v[148:149] op_sel_hi:[0,1]
	v_add_f32_e32 v147, 1.0, v147
	v_pk_fma_f32 v[148:149], v[154:155], v[154:155], v[148:149]
	v_rcp_f32_e32 v154, v147
	v_mul_f32_e32 v147, 0x3d922279, v39
	v_fmaak_f32 v147, v39, v147, 0x3fcc422a
	v_mul_f32_e32 v147, v39, v147
	v_mul_f32_e32 v147, 0xbfb8aa3b, v147
	v_exp_f32_e32 v147, v147
	v_mul_f32_e32 v158, v153, v153
	v_add_f32_e32 v135, 0, v144
	v_mov_b32_e32 v157, v153
	v_add_f32_e32 v147, 1.0, v147
	v_rcp_f32_e32 v155, v147
	v_pk_add_f32 v[148:149], v[158:159], v[148:149] op_sel_hi:[0,1]
	v_add_f32_e32 v135, v145, v135
	v_mul_f32_e32 v147, 0x3d922279, v42
	v_pk_mul_f32 v[154:155], v[38:39], v[154:155]
	v_fmaak_f32 v147, v42, v147, 0x3fcc422a
	v_mov_b32_e32 v156, v154
	v_pk_fma_f32 v[156:157], v[156:157], v[156:157], v[148:149]
	v_cvt_pk_bf16_f32 v148, v144, v145
	v_mul_f32_e32 v144, 0x3d922279, v40
	v_mul_f32_e32 v145, 0x3d922279, v41
	v_fmaak_f32 v144, v40, v144, 0x3fcc422a
	v_fmaak_f32 v145, v41, v145, 0x3fcc422a
	v_mul_f32_e32 v144, v40, v144
	v_mul_f32_e32 v145, v41, v145
	v_mul_f32_e32 v144, 0xbfb8aa3b, v144
	v_mul_f32_e32 v145, 0xbfb8aa3b, v145
	v_exp_f32_e32 v144, v144
	v_exp_f32_e32 v145, v145
	v_mul_f32_e32 v147, v42, v147
	v_mul_f32_e32 v147, 0xbfb8aa3b, v147
	v_add_f32_e32 v144, 1.0, v144
	v_add_f32_e32 v145, 1.0, v145
	v_rcp_f32_e32 v144, v144
	v_rcp_f32_e32 v145, v145
	v_exp_f32_e32 v147, v147
; __device__ __forceinline__ unsigned pk2(float lo, float hi) { return __builtin_bit_cast(unsigned, __builtin_convertvector((f32x2){lo, hi}, bf16x2_t)); }
; __device__ __forceinline__ float fgelu(float x) { return x * fsigmoid(x * (1.5957691216f + 0.0713548163f * x * x)); }
;     __device__ __forceinline__ void operator()(f32x4 (&acc)[2][2][4][2], const pg8::Unit& u, int wr, int wc, int fr, int fq) const {
;     ...
;                     const int row = row0 + ai * 128 + m * 16;
;                     float s1 = 0.f, s2 = 0.f;
; #pragma unroll
;                     for (int bj = 0; bj < 2; ++bj) {
;                         float y[8];
; #pragma unroll
;                         for (int n = 0; n < 2; ++n)
; #pragma unroll
;                             for (int j = 0; j < 4; ++j) { const float v = fgelu(acc[ai][bj][m][n][j]); y[4 * n + j] = v; s1 += v; s2 += v * v; }
;                         *(u32x4*)(G + (size_t)row * BW + bj * 128) = (u32x4){pk2(y[0], y[1]), pk2(y[2], y[3]), pk2(y[4], y[5]), pk2(y[6], y[7])};
;                     }
;                     s1 += __shfl_xor(s1, 16); s1 += __shfl_xor(s1, 32);
;                     s2 += __shfl_xor(s2, 16); s2 += __shfl_xor(s2, 32);
;                     if (fq == 0) *(f32x2*)(lns + ((size_t)row * 32 + (tile - 16) * 4 + wc) * 2) = (f32x2){s1, s2};
	v_lshlrev_b64 v[142:143], 12, v[140:141]
	v_add_f32_e32 v135, v150, v135
	v_lshl_add_u64 v[142:143], v[138:139], 0, v[142:143]
	v_add_f32_e32 v135, v151, v135
	v_cvt_pk_bf16_f32 v149, v150, v151
	v_cvt_pk_bf16_f32 v150, v152, v153
	v_cvt_pk_bf16_f32 v151, v154, v155
	v_pk_mul_f32 v[144:145], v[40:41], v[144:145]
	global_store_dwordx4 v[142:143], v[148:151], off nt
	v_add_f32_e32 v147, 1.0, v147
	v_add_f32_e32 v135, v152, v135
	v_pk_mov_b32 v[148:149], v[154:155], v[144:145] op_sel:[1,0]
	v_mul_f32_e32 v150, v144, v144
	v_pk_fma_f32 v[148:149], v[148:149], v[148:149], v[156:157]
	v_add_f32_e32 v135, v153, v135
	v_pk_add_f32 v[148:149], v[148:149], v[150:151] op_sel_hi:[1,0]
	v_rcp_f32_e32 v150, v147
	v_mul_f32_e32 v147, 0x3d922279, v43
	v_fmaak_f32 v147, v43, v147, 0x3fcc422a
	v_mul_f32_e32 v147, v43, v147
	v_mul_f32_e32 v147, 0xbfb8aa3b, v147
	v_exp_f32_e32 v147, v147
	v_add_f32_e32 v135, v154, v135
	v_mul_f32_e32 v154, v145, v145
	v_mov_b32_e32 v153, v145
	v_add_f32_e32 v147, 1.0, v147
	v_rcp_f32_e32 v151, v147
	v_mul_f32_e32 v147, 0x3d922279, v32
	v_fmaak_f32 v147, v32, v147, 0x3fcc422a
	v_mul_f32_e32 v147, v32, v147
	v_mul_f32_e32 v147, 0xbfb8aa3b, v147
	v_exp_f32_e32 v147, v147
	v_pk_mul_f32 v[150:151], v[42:43], v[150:151]
	v_pk_add_f32 v[148:149], v[154:155], v[148:149] op_sel_hi:[0,1]
	v_mov_b32_e32 v152, v150
	v_add_f32_e32 v147, 1.0, v147
	v_pk_fma_f32 v[148:149], v[152:153], v[152:153], v[148:149]
	v_rcp_f32_e32 v152, v147
	v_mul_f32_e32 v147, 0x3d922279, v33
	v_fmaak_f32 v147, v33, v147, 0x3fcc422a
	v_mul_f32_e32 v147, v33, v147
	v_mul_f32_e32 v147, 0xbfb8aa3b, v147
	v_exp_f32_e32 v147, v147
	v_add_f32_e32 v135, v155, v135
	v_add_f32_e32 v135, v135, v144
	v_add_f32_e32 v135, v145, v135
	v_add_f32_e32 v147, 1.0, v147
	v_rcp_f32_e32 v153, v147
	v_add_f32_e32 v135, v150, v135
	v_add_f32_e32 v135, v151, v135
	v_mul_f32_e32 v156, v151, v151
	v_pk_mul_f32 v[152:153], v[32:33], v[152:153]
	v_pk_add_f32 v[148:149], v[156:157], v[148:149] op_sel_hi:[0,1]
	v_add_f32_e32 v135, v152, v135
	v_add_f32_e32 v156, v153, v135
	v_mul_f32_e32 v135, 0x3d922279, v34
	v_fmaak_f32 v135, v34, v135, 0x3fcc422a
	v_mul_f32_e32 v135, v34, v135
	v_mul_f32_e32 v135, 0xbfb8aa3b, v135
	v_exp_f32_e32 v135, v135
	v_mov_b32_e32 v154, v152
	v_mov_b32_e32 v155, v151
	v_pk_fma_f32 v[154:155], v[154:155], v[154:155], v[148:149]
	v_add_f32_e32 v135, 1.0, v135
	v_rcp_f32_e32 v158, v135
	v_mul_f32_e32 v135, 0x3d922279, v35
	v_fmaak_f32 v135, v35, v135, 0x3fcc422a
	v_mul_f32_e32 v135, v35, v135
	v_mul_f32_e32 v135, 0xbfb8aa3b, v135
	v_exp_f32_e32 v135, v135
	v_cvt_pk_bf16_f32 v148, v144, v145
	v_mul_f32_e32 v160, v153, v153
	v_cvt_pk_bf16_f32 v149, v150, v151
	v_add_f32_e32 v135, 1.0, v135
	v_rcp_f32_e32 v159, v135
	v_cvt_pk_bf16_f32 v150, v152, v153
	v_pk_add_f32 v[154:155], v[160:161], v[154:155] op_sel_hi:[0,1]
	v_pk_mul_f32 v[144:145], v[34:35], v[158:159]
	s_nop 0
	v_mov_b32_e32 v152, v144
	v_mov_b32_e32 v157, v145
	v_pk_fma_f32 v[152:153], v[152:153], v[152:153], v[154:155]
	v_pk_fma_f32 v[154:155], v[34:35], v[158:159], v[156:157]
	v_pk_mul_f32 v[156:157], v[144:145], v[144:145]
	v_pk_mov_b32 v[152:153], v[144:145], v[152:153] op_sel:[1,0]
	v_mov_b32_e32 v155, v157
	v_pk_add_f32 v[152:153], v[154:155], v[152:153]
	v_cvt_pk_bf16_f32 v151, v144, v145
	global_store_dwordx4 v[142:143], v[148:151], off offset:256 nt
	ds_bpermute_b32 v142, v146, v152
	ds_bpermute_b32 v143, v146, v153
	s_waitcnt lgkmcnt(0)
	v_pk_add_f32 v[142:143], v[152:153], v[142:143]
	ds_bpermute_b32 v144, v137, v142
	ds_bpermute_b32 v145, v137, v143
	s_and_saveexec_b64 s[4:5], vcc
	s_cbranch_execz .LBB0_192
	v_lshlrev_b64 v[140:141], 8, v[140:141]
	v_lshl_add_u64 v[140:141], s[40:41], 0, v[140:141]
	s_waitcnt lgkmcnt(0)
	v_pk_add_f32 v[142:143], v[142:143], v[144:145]
	v_lshl_add_u64 v[140:141], s[14:15], 3, v[140:141]
	global_store_dwordx2 v[140:141], v[142:143], off
.LBB0_192:
	s_or_b64 exec, exec, s[4:5]
	v_mul_f32_e32 v147, 0x3d922279, v30
	v_fmaak_f32 v147, v30, v147, 0x3fcc422a
	v_mul_f32_e32 v147, v30, v147
	v_mul_f32_e32 v147, 0xbfb8aa3b, v147
	v_exp_f32_e32 v147, v147
	v_mul_f32_e32 v135, 0x3d922279, v28
	v_fmaak_f32 v135, v28, v135, 0x3fcc422a
	v_mul_f32_e32 v135, v28, v135
	v_add_f32_e32 v147, 1.0, v147
	v_rcp_f32_e32 v150, v147
	v_mul_f32_e32 v147, 0x3d922279, v31
	v_fmaak_f32 v147, v31, v147, 0x3fcc422a
	v_mul_f32_e32 v147, v31, v147
	v_mul_f32_e32 v147, 0xbfb8aa3b, v147
	v_exp_f32_e32 v147, v147
	v_mul_f32_e32 v135, 0xbfb8aa3b, v135
	v_exp_f32_e32 v135, v135
	v_add_u32_e32 v140, 0xa0, v134
	v_add_f32_e32 v147, 1.0, v147
	v_rcp_f32_e32 v151, v147
	v_mul_f32_e32 v147, 0x3d922279, v20
	v_fmaak_f32 v147, v20, v147, 0x3fcc422a
	v_mul_f32_e32 v147, v20, v147
	v_mul_f32_e32 v147, 0xbfb8aa3b, v147
	v_exp_f32_e32 v147, v147
	v_add_f32_e32 v135, 1.0, v135
	s_waitcnt lgkmcnt(0)
; __device__ __forceinline__ unsigned pk2(float lo, float hi) { return __builtin_bit_cast(unsigned, __builtin_convertvector((f32x2){lo, hi}, bf16x2_t)); }
; __device__ __forceinline__ float fgelu(float x) { return x * fsigmoid(x * (1.5957691216f + 0.0713548163f * x * x)); }
;     __device__ __forceinline__ void operator()(f32x4 (&acc)[2][2][4][2], const pg8::Unit& u, int wr, int wc, int fr, int fq) const {
;     ...
;                     const int row = row0 + ai * 128 + m * 16;
;                     float s1 = 0.f, s2 = 0.f;
; #pragma unroll
;                     for (int bj = 0; bj < 2; ++bj) {
;                         float y[8];
; #pragma unroll
;                         for (int n = 0; n < 2; ++n)
; #pragma unroll
;                             for (int j = 0; j < 4; ++j) { const float v = fgelu(acc[ai][bj][m][n][j]); y[4 * n + j] = v; s1 += v; s2 += v * v; }
;                         *(u32x4*)(G + (size_t)row * BW + bj * 128) = (u32x4){pk2(y[0], y[1]), pk2(y[2], y[3]), pk2(y[4], y[5]), pk2(y[6], y[7])};
;                     }
;                     s1 += __shfl_xor(s1, 16); s1 += __shfl_xor(s1, 32);
;                     s2 += __shfl_xor(s2, 16); s2 += __shfl_xor(s2, 32);
;                     if (fq == 0) *(f32x2*)(lns + ((size_t)row * 32 + (tile - 16) * 4 + wc) * 2) = (f32x2){s1, s2};
	v_rcp_f32_e32 v144, v135
	v_mul_f32_e32 v135, 0x3d922279, v29
	v_add_f32_e32 v147, 1.0, v147
	v_rcp_f32_e32 v152, v147
	v_mul_f32_e32 v147, 0x3d922279, v21
	v_fmaak_f32 v135, v29, v135, 0x3fcc422a
	v_fmaak_f32 v147, v21, v147, 0x3fcc422a
	v_mul_f32_e32 v135, v29, v135
	v_mul_f32_e32 v147, v21, v147
	v_mul_f32_e32 v135, 0xbfb8aa3b, v135
	v_mul_f32_e32 v147, 0xbfb8aa3b, v147
	v_exp_f32_e32 v135, v135
	v_exp_f32_e32 v147, v147
	v_pk_mul_f32 v[150:151], v[30:31], v[150:151]
	v_ashrrev_i32_e32 v141, 31, v140
	v_add_f32_e32 v135, 1.0, v135
	v_add_f32_e32 v147, 1.0, v147
	v_rcp_f32_e32 v145, v135
	v_rcp_f32_e32 v153, v147
	v_mul_f32_e32 v147, 0x3d922279, v22
	v_fmaak_f32 v147, v22, v147, 0x3fcc422a
	v_mul_f32_e32 v147, v22, v147
	v_mul_f32_e32 v147, 0xbfb8aa3b, v147
	v_pk_mul_f32 v[144:145], v[28:29], v[144:145]
	v_exp_f32_e32 v147, v147
	v_mul_f32_e32 v148, v145, v145
	v_pk_fma_f32 v[148:149], v[144:145], v[144:145], v[148:149] op_sel_hi:[1,1,0]
	v_pk_mul_f32 v[152:153], v[20:21], v[152:153]
	v_pk_fma_f32 v[148:149], v[150:151], v[150:151], v[148:149]
	v_mul_f32_e32 v156, v151, v151
	v_mov_b32_e32 v154, v152
	v_mov_b32_e32 v155, v151
	v_pk_add_f32 v[148:149], v[156:157], v[148:149] op_sel_hi:[0,1]
	v_add_f32_e32 v147, 1.0, v147
	v_pk_fma_f32 v[148:149], v[154:155], v[154:155], v[148:149]
	v_rcp_f32_e32 v154, v147
	v_mul_f32_e32 v147, 0x3d922279, v23
	v_fmaak_f32 v147, v23, v147, 0x3fcc422a
	v_mul_f32_e32 v147, v23, v147
	v_mul_f32_e32 v147, 0xbfb8aa3b, v147
	v_exp_f32_e32 v147, v147
	v_mul_f32_e32 v158, v153, v153
	v_add_f32_e32 v135, 0, v144
	v_mov_b32_e32 v157, v153
	v_add_f32_e32 v147, 1.0, v147
	v_rcp_f32_e32 v155, v147
	v_pk_add_f32 v[148:149], v[158:159], v[148:149] op_sel_hi:[0,1]
	v_add_f32_e32 v135, v145, v135
	v_mul_f32_e32 v147, 0x3d922279, v26
	v_pk_mul_f32 v[154:155], v[22:23], v[154:155]
	v_fmaak_f32 v147, v26, v147, 0x3fcc422a
	v_mov_b32_e32 v156, v154
	v_pk_fma_f32 v[156:157], v[156:157], v[156:157], v[148:149]
	v_cvt_pk_bf16_f32 v148, v144, v145
	v_mul_f32_e32 v144, 0x3d922279, v24
	v_mul_f32_e32 v145, 0x3d922279, v25
	v_fmaak_f32 v144, v24, v144, 0x3fcc422a
	v_fmaak_f32 v145, v25, v145, 0x3fcc422a
	v_mul_f32_e32 v144, v24, v144
	v_mul_f32_e32 v145, v25, v145
	v_mul_f32_e32 v144, 0xbfb8aa3b, v144
	v_mul_f32_e32 v145, 0xbfb8aa3b, v145
	v_exp_f32_e32 v144, v144
	v_exp_f32_e32 v145, v145
	v_mul_f32_e32 v147, v26, v147
	v_mul_f32_e32 v147, 0xbfb8aa3b, v147
	v_add_f32_e32 v144, 1.0, v144
	v_add_f32_e32 v145, 1.0, v145
	v_rcp_f32_e32 v144, v144
	v_rcp_f32_e32 v145, v145
	v_exp_f32_e32 v147, v147
	v_lshlrev_b64 v[142:143], 12, v[140:141]
	v_add_f32_e32 v135, v150, v135
	v_lshl_add_u64 v[142:143], v[138:139], 0, v[142:143]
	v_add_f32_e32 v135, v151, v135
	v_cvt_pk_bf16_f32 v149, v150, v151
	v_cvt_pk_bf16_f32 v150, v152, v153
	v_cvt_pk_bf16_f32 v151, v154, v155
	v_pk_mul_f32 v[144:145], v[24:25], v[144:145]
	global_store_dwordx4 v[142:143], v[148:151], off nt
	v_add_f32_e32 v147, 1.0, v147
	v_add_f32_e32 v135, v152, v135
	v_pk_mov_b32 v[148:149], v[154:155], v[144:145] op_sel:[1,0]
	v_mul_f32_e32 v150, v144, v144
	v_pk_fma_f32 v[148:149], v[148:149], v[148:149], v[156:157]
	v_add_f32_e32 v135, v153, v135
	v_pk_add_f32 v[148:149], v[148:149], v[150:151] op_sel_hi:[1,0]
	v_rcp_f32_e32 v150, v147
	v_mul_f32_e32 v147, 0x3d922279, v27
	v_fmaak_f32 v147, v27, v147, 0x3fcc422a
	v_mul_f32_e32 v147, v27, v147
	v_mul_f32_e32 v147, 0xbfb8aa3b, v147
	v_exp_f32_e32 v147, v147
	v_add_f32_e32 v135, v154, v135
	v_mul_f32_e32 v154, v145, v145
	v_mov_b32_e32 v153, v145
	v_add_f32_e32 v147, 1.0, v147
	v_rcp_f32_e32 v151, v147
	v_mul_f32_e32 v147, 0x3d922279, v16
	v_fmaak_f32 v147, v16, v147, 0x3fcc422a
	v_mul_f32_e32 v147, v16, v147
	v_mul_f32_e32 v147, 0xbfb8aa3b, v147
	v_exp_f32_e32 v147, v147
	v_pk_mul_f32 v[150:151], v[26:27], v[150:151]
	v_pk_add_f32 v[148:149], v[154:155], v[148:149] op_sel_hi:[0,1]
	v_mov_b32_e32 v152, v150
	v_add_f32_e32 v147, 1.0, v147
	v_pk_fma_f32 v[148:149], v[152:153], v[152:153], v[148:149]
	v_rcp_f32_e32 v152, v147
	v_mul_f32_e32 v147, 0x3d922279, v17
	v_fmaak_f32 v147, v17, v147, 0x3fcc422a
	v_mul_f32_e32 v147, v17, v147
	v_mul_f32_e32 v147, 0xbfb8aa3b, v147
	v_exp_f32_e32 v147, v147
	v_add_f32_e32 v135, v155, v135
	v_add_f32_e32 v135, v135, v144
	v_add_f32_e32 v135, v145, v135
	v_add_f32_e32 v147, 1.0, v147
	v_rcp_f32_e32 v153, v147
	v_add_f32_e32 v135, v150, v135
	v_add_f32_e32 v135, v151, v135
	v_mul_f32_e32 v156, v151, v151
	v_pk_mul_f32 v[152:153], v[16:17], v[152:153]
	v_pk_add_f32 v[148:149], v[156:157], v[148:149] op_sel_hi:[0,1]
	v_add_f32_e32 v135, v152, v135
	v_add_f32_e32 v156, v153, v135
	v_mul_f32_e32 v135, 0x3d922279, v18
	v_fmaak_f32 v135, v18, v135, 0x3fcc422a
	v_mul_f32_e32 v135, v18, v135
	v_mul_f32_e32 v135, 0xbfb8aa3b, v135
	v_exp_f32_e32 v135, v135
	v_mov_b32_e32 v154, v152
	v_mov_b32_e32 v155, v151
	v_pk_fma_f32 v[154:155], v[154:155], v[154:155], v[148:149]
	v_add_f32_e32 v135, 1.0, v135
	v_rcp_f32_e32 v158, v135
	v_mul_f32_e32 v135, 0x3d922279, v19
	v_fmaak_f32 v135, v19, v135, 0x3fcc422a
	v_mul_f32_e32 v135, v19, v135
	v_mul_f32_e32 v135, 0xbfb8aa3b, v135
	v_exp_f32_e32 v135, v135
	v_cvt_pk_bf16_f32 v148, v144, v145
	v_mul_f32_e32 v160, v153, v153
	v_cvt_pk_bf16_f32 v149, v150, v151
	v_add_f32_e32 v135, 1.0, v135
	v_rcp_f32_e32 v159, v135
	v_cvt_pk_bf16_f32 v150, v152, v153
	v_pk_add_f32 v[154:155], v[160:161], v[154:155] op_sel_hi:[0,1]
	v_pk_mul_f32 v[144:145], v[18:19], v[158:159]
	s_nop 0
	v_mov_b32_e32 v152, v144
	v_mov_b32_e32 v157, v145
	v_pk_fma_f32 v[152:153], v[152:153], v[152:153], v[154:155]
	v_pk_fma_f32 v[154:155], v[18:19], v[158:159], v[156:157]
	v_pk_mul_f32 v[156:157], v[144:145], v[144:145]
	v_pk_mov_b32 v[152:153], v[144:145], v[152:153] op_sel:[1,0]
	v_mov_b32_e32 v155, v157
	v_pk_add_f32 v[152:153], v[154:155], v[152:153]
	v_cvt_pk_bf16_f32 v151, v144, v145
	global_store_dwordx4 v[142:143], v[148:151], off offset:256 nt
	ds_bpermute_b32 v142, v146, v152
	ds_bpermute_b32 v143, v146, v153
	s_waitcnt lgkmcnt(0)
	v_pk_add_f32 v[142:143], v[152:153], v[142:143]
	ds_bpermute_b32 v144, v137, v142
	ds_bpermute_b32 v145, v137, v143
	s_and_saveexec_b64 s[4:5], vcc
	s_cbranch_execz .LBB0_194
	v_lshlrev_b64 v[140:141], 8, v[140:141]
	v_lshl_add_u64 v[140:141], s[40:41], 0, v[140:141]
	s_waitcnt lgkmcnt(0)
	v_pk_add_f32 v[142:143], v[142:143], v[144:145]
	v_lshl_add_u64 v[140:141], s[14:15], 3, v[140:141]
	global_store_dwordx2 v[140:141], v[142:143], off
; __device__ __forceinline__ unsigned pk2(float lo, float hi) { return __builtin_bit_cast(unsigned, __builtin_convertvector((f32x2){lo, hi}, bf16x2_t)); }
; __device__ __forceinline__ float fgelu(float x) { return x * fsigmoid(x * (1.5957691216f + 0.0713548163f * x * x)); }
;     __device__ __forceinline__ void operator()(f32x4 (&acc)[2][2][4][2], const pg8::Unit& u, int wr, int wc, int fr, int fq) const {
;     ...
;                     const int row = row0 + ai * 128 + m * 16;
;                     float s1 = 0.f, s2 = 0.f;
; #pragma unroll
;                     for (int bj = 0; bj < 2; ++bj) {
;                         float y[8];
; #pragma unroll
;                         for (int n = 0; n < 2; ++n)
; #pragma unroll
;                             for (int j = 0; j < 4; ++j) { const float v = fgelu(acc[ai][bj][m][n][j]); y[4 * n + j] = v; s1 += v; s2 += v * v; }
;                         *(u32x4*)(G + (size_t)row * BW + bj * 128) = (u32x4){pk2(y[0], y[1]), pk2(y[2], y[3]), pk2(y[4], y[5]), pk2(y[6], y[7])};
;                     }
;                     s1 += __shfl_xor(s1, 16); s1 += __shfl_xor(s1, 32);
;                     s2 += __shfl_xor(s2, 16); s2 += __shfl_xor(s2, 32);
;                     if (fq == 0) *(f32x2*)(lns + ((size_t)row * 32 + (tile - 16) * 4 + wc) * 2) = (f32x2){s1, s2};
.LBB0_194:
	s_or_b64 exec, exec, s[4:5]
	v_mul_f32_e32 v147, 0x3d922279, v14
	v_fmaak_f32 v147, v14, v147, 0x3fcc422a
	v_mul_f32_e32 v147, v14, v147
	v_mul_f32_e32 v147, 0xbfb8aa3b, v147
	v_exp_f32_e32 v147, v147
	v_mul_f32_e32 v135, 0x3d922279, v12
	v_fmaak_f32 v135, v12, v135, 0x3fcc422a
	v_mul_f32_e32 v135, v12, v135
	v_add_f32_e32 v147, 1.0, v147
	v_rcp_f32_e32 v148, v147
	v_mul_f32_e32 v147, 0x3d922279, v15
	v_fmaak_f32 v147, v15, v147, 0x3fcc422a
	v_mul_f32_e32 v147, v15, v147
	v_mul_f32_e32 v147, 0xbfb8aa3b, v147
	v_exp_f32_e32 v147, v147
	v_mul_f32_e32 v135, 0xbfb8aa3b, v135
	v_exp_f32_e32 v135, v135
	v_add_u32_e32 v140, 0xb0, v134
	v_add_f32_e32 v147, 1.0, v147
	v_rcp_f32_e32 v149, v147
	v_mul_f32_e32 v147, 0x3d922279, v4
	v_fmaak_f32 v147, v4, v147, 0x3fcc422a
	v_mul_f32_e32 v147, v4, v147
	v_mul_f32_e32 v147, 0xbfb8aa3b, v147
	v_exp_f32_e32 v147, v147
	v_ashrrev_i32_e32 v141, 31, v140
	v_lshlrev_b64 v[142:143], 12, v[140:141]
	v_add_f32_e32 v135, 1.0, v135
	v_add_f32_e32 v147, 1.0, v147
	v_lshl_add_u64 v[138:139], v[138:139], 0, v[142:143]
	v_rcp_f32_e32 v142, v135
	v_mul_f32_e32 v135, 0x3d922279, v13
	v_rcp_f32_e32 v150, v147
	v_mul_f32_e32 v147, 0x3d922279, v5
	v_fmaak_f32 v135, v13, v135, 0x3fcc422a
	v_fmaak_f32 v147, v5, v147, 0x3fcc422a
	v_mul_f32_e32 v135, v13, v135
	v_mul_f32_e32 v147, v5, v147
	v_mul_f32_e32 v135, 0xbfb8aa3b, v135
	v_mul_f32_e32 v147, 0xbfb8aa3b, v147
	v_exp_f32_e32 v135, v135
	v_exp_f32_e32 v147, v147
	v_pk_mul_f32 v[148:149], v[14:15], v[148:149]
	v_add_f32_e32 v135, 1.0, v135
	v_add_f32_e32 v147, 1.0, v147
	v_rcp_f32_e32 v143, v135
	v_rcp_f32_e32 v151, v147
	v_mul_f32_e32 v147, 0x3d922279, v6
	v_fmaak_f32 v147, v6, v147, 0x3fcc422a
	v_mul_f32_e32 v147, v6, v147
	v_mul_f32_e32 v147, 0xbfb8aa3b, v147
	v_pk_mul_f32 v[142:143], v[12:13], v[142:143]
	v_exp_f32_e32 v147, v147
	s_waitcnt lgkmcnt(0)
	v_mul_f32_e32 v144, v143, v143
	v_pk_fma_f32 v[144:145], v[142:143], v[142:143], v[144:145] op_sel_hi:[1,1,0]
	v_pk_mul_f32 v[150:151], v[4:5], v[150:151]
	v_pk_fma_f32 v[144:145], v[148:149], v[148:149], v[144:145]
	v_mul_f32_e32 v154, v149, v149
	v_mov_b32_e32 v152, v150
	v_mov_b32_e32 v153, v149
	v_pk_add_f32 v[144:145], v[154:155], v[144:145] op_sel_hi:[0,1]
	v_add_f32_e32 v147, 1.0, v147
	v_pk_fma_f32 v[144:145], v[152:153], v[152:153], v[144:145]
	v_rcp_f32_e32 v152, v147
	v_mul_f32_e32 v147, 0x3d922279, v7
	v_fmaak_f32 v147, v7, v147, 0x3fcc422a
	v_mul_f32_e32 v147, v7, v147
	v_mul_f32_e32 v147, 0xbfb8aa3b, v147
	v_exp_f32_e32 v147, v147
	v_mul_f32_e32 v156, v151, v151
	v_add_f32_e32 v135, 0, v142
	v_mov_b32_e32 v155, v151
	v_add_f32_e32 v147, 1.0, v147
	v_rcp_f32_e32 v153, v147
	v_pk_add_f32 v[144:145], v[156:157], v[144:145] op_sel_hi:[0,1]
	v_add_f32_e32 v135, v143, v135
	v_cvt_pk_bf16_f32 v142, v142, v143
	v_pk_mul_f32 v[152:153], v[6:7], v[152:153]
	v_cvt_pk_bf16_f32 v143, v148, v149
	v_mov_b32_e32 v154, v152
	v_pk_fma_f32 v[154:155], v[154:155], v[154:155], v[144:145]
	v_cvt_pk_bf16_f32 v144, v150, v151
	v_cvt_pk_bf16_f32 v145, v152, v153
	global_store_dwordx4 v[138:139], v[142:145], off nt
	v_mul_f32_e32 v147, 0x3d922279, v10
	v_fmaak_f32 v147, v10, v147, 0x3fcc422a
	v_mul_f32_e32 v142, 0x3d922279, v8
	v_mul_f32_e32 v143, 0x3d922279, v9
	v_fmaak_f32 v142, v8, v142, 0x3fcc422a
	v_fmaak_f32 v143, v9, v143, 0x3fcc422a
	v_mul_f32_e32 v142, v8, v142
	v_mul_f32_e32 v143, v9, v143
	v_mul_f32_e32 v142, 0xbfb8aa3b, v142
	v_mul_f32_e32 v143, 0xbfb8aa3b, v143
	v_exp_f32_e32 v142, v142
	v_exp_f32_e32 v143, v143
	v_mul_f32_e32 v147, v10, v147
	v_mul_f32_e32 v147, 0xbfb8aa3b, v147
	v_add_f32_e32 v142, 1.0, v142
	v_add_f32_e32 v143, 1.0, v143
	v_rcp_f32_e32 v142, v142
	v_rcp_f32_e32 v143, v143
	v_exp_f32_e32 v147, v147
	v_add_f32_e32 v135, v148, v135
	v_add_f32_e32 v135, v149, v135
	v_pk_mul_f32 v[142:143], v[8:9], v[142:143]
	v_add_f32_e32 v147, 1.0, v147
	v_pk_mov_b32 v[144:145], v[152:153], v[142:143] op_sel:[1,0]
	v_mul_f32_e32 v148, v142, v142
	v_pk_fma_f32 v[144:145], v[144:145], v[144:145], v[154:155]
	v_add_f32_e32 v135, v150, v135
	v_pk_add_f32 v[144:145], v[144:145], v[148:149] op_sel_hi:[1,0]
	v_rcp_f32_e32 v148, v147
	v_mul_f32_e32 v147, 0x3d922279, v11
	v_fmaak_f32 v147, v11, v147, 0x3fcc422a
	v_mul_f32_e32 v147, v11, v147
	v_mul_f32_e32 v147, 0xbfb8aa3b, v147
	v_exp_f32_e32 v147, v147
	v_add_f32_e32 v135, v151, v135
	v_add_f32_e32 v135, v152, v135
	v_mul_f32_e32 v152, v143, v143
	v_add_f32_e32 v147, 1.0, v147
	v_rcp_f32_e32 v149, v147
	v_mul_f32_e32 v147, 0x3d922279, v0
	v_fmaak_f32 v147, v0, v147, 0x3fcc422a
	v_mul_f32_e32 v147, v0, v147
	v_mul_f32_e32 v147, 0xbfb8aa3b, v147
	v_exp_f32_e32 v147, v147
	v_pk_mul_f32 v[148:149], v[10:11], v[148:149]
	v_mov_b32_e32 v151, v143
	v_mov_b32_e32 v150, v148
	v_pk_add_f32 v[144:145], v[152:153], v[144:145] op_sel_hi:[0,1]
	v_add_f32_e32 v147, 1.0, v147
	v_pk_fma_f32 v[144:145], v[150:151], v[150:151], v[144:145]
	v_rcp_f32_e32 v150, v147
	v_mul_f32_e32 v147, 0x3d922279, v1
	v_fmaak_f32 v147, v1, v147, 0x3fcc422a
	v_mul_f32_e32 v147, v1, v147
	v_mul_f32_e32 v147, 0xbfb8aa3b, v147
	v_exp_f32_e32 v147, v147
	v_add_f32_e32 v135, v153, v135
	v_add_f32_e32 v135, v135, v142
	v_add_f32_e32 v135, v143, v135
	v_add_f32_e32 v147, 1.0, v147
	v_rcp_f32_e32 v151, v147
	v_add_f32_e32 v135, v148, v135
	v_add_f32_e32 v135, v149, v135
	v_mul_f32_e32 v154, v149, v149
	v_pk_mul_f32 v[150:151], v[0:1], v[150:151]
	v_pk_add_f32 v[144:145], v[154:155], v[144:145] op_sel_hi:[0,1]
	v_add_f32_e32 v135, v150, v135
	v_add_f32_e32 v154, v151, v135
	v_mul_f32_e32 v135, 0x3d922279, v2
	v_fmaak_f32 v135, v2, v135, 0x3fcc422a
	v_mul_f32_e32 v135, v2, v135
	v_mul_f32_e32 v135, 0xbfb8aa3b, v135
	v_exp_f32_e32 v135, v135
	v_mov_b32_e32 v152, v150
	v_mov_b32_e32 v153, v149
	v_pk_fma_f32 v[152:153], v[152:153], v[152:153], v[144:145]
	v_add_f32_e32 v135, 1.0, v135
	v_rcp_f32_e32 v156, v135
	v_mul_f32_e32 v135, 0x3d922279, v3
	v_fmaak_f32 v135, v3, v135, 0x3fcc422a
	v_mul_f32_e32 v135, v3, v135
	v_mul_f32_e32 v135, 0xbfb8aa3b, v135
	v_exp_f32_e32 v135, v135
	v_cvt_pk_bf16_f32 v142, v142, v143
	v_cvt_pk_bf16_f32 v143, v148, v149
	v_mul_f32_e32 v158, v151, v151
	v_add_f32_e32 v135, 1.0, v135
	v_rcp_f32_e32 v157, v135
	v_cvt_pk_bf16_f32 v144, v150, v151
	v_pk_add_f32 v[152:153], v[158:159], v[152:153] op_sel_hi:[0,1]
	v_pk_mul_f32 v[148:149], v[2:3], v[156:157]
	s_nop 0
	v_mov_b32_e32 v150, v148
	v_mov_b32_e32 v155, v149
	v_pk_fma_f32 v[150:151], v[150:151], v[150:151], v[152:153]
	v_pk_fma_f32 v[152:153], v[2:3], v[156:157], v[154:155]
	v_pk_mul_f32 v[154:155], v[148:149], v[148:149]
	v_pk_mov_b32 v[150:151], v[148:149], v[150:151] op_sel:[1,0]
	v_mov_b32_e32 v153, v155
	v_pk_add_f32 v[150:151], v[152:153], v[150:151]
	v_cvt_pk_bf16_f32 v145, v148, v149
	global_store_dwordx4 v[138:139], v[142:145], off offset:256 nt
	ds_bpermute_b32 v138, v146, v150
	ds_bpermute_b32 v139, v146, v151
	s_waitcnt lgkmcnt(0)
	v_pk_add_f32 v[138:139], v[150:151], v[138:139]
	ds_bpermute_b32 v142, v137, v138
	ds_bpermute_b32 v143, v137, v139
	s_and_saveexec_b64 s[4:5], vcc
	s_cbranch_execz .LBB0_196
;     __device__ __forceinline__ void operator()(f32x4 (&acc)[2][2][4][2], const pg8::Unit& u, int wr, int wc, int fr, int fq) const {
;     ...
;                     s1 += __shfl_xor(s1, 16); s1 += __shfl_xor(s1, 32);
;                     s2 += __shfl_xor(s2, 16); s2 += __shfl_xor(s2, 32);
;                     if (fq == 0) *(f32x2*)(lns + ((size_t)row * 32 + (tile - 16) * 4 + wc) * 2) = (f32x2){s1, s2};
	v_lshlrev_b64 v[140:141], 8, v[140:141]
	v_lshl_add_u64 v[140:141], s[40:41], 0, v[140:141]
	s_waitcnt lgkmcnt(0)
	v_pk_add_f32 v[138:139], v[138:139], v[142:143]
	v_lshl_add_u64 v[140:141], s[14:15], 3, v[140:141]
	global_store_dwordx2 v[140:141], v[138:139], off

; __device__ __forceinline__ unsigned pk2(float lo, float hi) { return __builtin_bit_cast(unsigned, __builtin_convertvector((f32x2){lo, hi}, bf16x2_t)); }
; __device__ __forceinline__ float fsigmoid(float x) { return __builtin_amdgcn_rcpf(1.0f + fexp(-x)); }
; __device__ __forceinline__ float fgelu(float x) { return x * fsigmoid(x * (1.5957691216f + 0.0713548163f * x * x)); }
;     __device__ __forceinline__ void operator()(f32x4 (&acc)[2][2][4][2], const pg8::Unit& u, int wr, int wc, int fr, int fq) const {
;     ...
;         if (tile < 16) {
;             bf16_t* G = (bf16_t*)(ws + WS_GUZ) + tile * 128 + c8;
; #pragma unroll
;             for (int ai = 0; ai < 2; ++ai)
; #pragma unroll
;                 for (int m = 0; m < 4; ++m) {
;                     float y[8];
; #pragma unroll
;                     for (int n = 0; n < 2; ++n)
; #pragma unroll
;                         for (int j = 0; j < 4; ++j) { const float uu = acc[ai][0][m][n][j], zz = acc[ai][1][m][n][j]; y[4 * n + j] = fgelu(uu) * zz * fsigmoid(zz); }
;                     *(u32x4*)(G + (size_t)(row0 + ai * 128 + m * 16) * BW) = (u32x4){pk2(y[0], y[1]), pk2(y[2], y[3]), pk2(y[4], y[5]), pk2(y[6], y[7])};
.LBB0_198:
	s_andn2_b64 vcc, exec, s[66:67]
	s_cbranch_vccnz .LBB0_200
	v_mul_f32_e32 v135, 0x3d922279, v124
	v_fmaak_f32 v135, v124, v135, 0x3fcc422a
	v_mul_f32_e32 v135, v124, v135
	v_mul_f32_e32 v139, 0x3d922279, v125
	v_mul_f32_e32 v135, 0xbfb8aa3b, v135
	v_fmaak_f32 v139, v125, v139, 0x3fcc422a
	v_exp_f32_e32 v135, v135
	v_mul_f32_e32 v139, v125, v139
	v_mul_f32_e32 v139, 0xbfb8aa3b, v139
	v_exp_f32_e32 v139, v139
	v_add_f32_e32 v135, 1.0, v135
	v_rcp_f32_e32 v138, v135
	v_mul_f32_e32 v135, 0xbfb8aa3b, v120
	v_exp_f32_e32 v135, v135
	v_mul_f32_e32 v140, 0xbfb8aa3b, v121
	v_add_f32_e32 v139, 1.0, v139
	v_exp_f32_e32 v141, v140
	v_rcp_f32_e32 v139, v139
	v_add_f32_e32 v135, 1.0, v135
	v_rcp_f32_e32 v140, v135
	v_add_f32_e32 v135, 1.0, v141
	v_pk_mul_f32 v[124:125], v[124:125], v[138:139]
	v_rcp_f32_e32 v141, v135
	v_pk_mul_f32 v[120:121], v[124:125], v[120:121]
	v_mul_f32_e32 v124, 0x3d922279, v126
	v_mul_f32_e32 v135, 0x3d922279, v127
	v_fmaak_f32 v124, v126, v124, 0x3fcc422a
	v_fmaak_f32 v135, v127, v135, 0x3fcc422a
	v_mul_f32_e32 v124, v126, v124
	v_mul_f32_e32 v125, 0xbfb8aa3b, v122
	v_mul_f32_e32 v135, v127, v135
	v_mul_f32_e32 v124, 0xbfb8aa3b, v124
	v_exp_f32_e32 v125, v125
	v_mul_f32_e32 v135, 0xbfb8aa3b, v135
	v_exp_f32_e32 v124, v124
	v_exp_f32_e32 v135, v135
	v_add_f32_e32 v125, 1.0, v125
	v_mul_f32_e32 v138, 0xbfb8aa3b, v123
	v_add_f32_e32 v124, 1.0, v124
	v_exp_f32_e32 v139, v138
	v_rcp_f32_e32 v138, v125
	v_add_f32_e32 v125, 1.0, v135
	v_rcp_f32_e32 v124, v124
	v_rcp_f32_e32 v125, v125
	v_add_f32_e32 v135, 1.0, v139
	v_rcp_f32_e32 v139, v135
	v_mul_f32_e32 v135, 0x3d922279, v116
	v_pk_mul_f32 v[124:125], v[126:127], v[124:125]
	v_mul_f32_e32 v126, 0x3d922279, v117
	v_fmaak_f32 v135, v116, v135, 0x3fcc422a
	v_fmaak_f32 v126, v117, v126, 0x3fcc422a
	v_mul_f32_e32 v135, v116, v135
	v_pk_mul_f32 v[122:123], v[124:125], v[122:123]
	v_mul_f32_e32 v125, 0xbfb8aa3b, v112
	v_mul_f32_e32 v126, v117, v126
	v_mul_f32_e32 v135, 0xbfb8aa3b, v135
	v_exp_f32_e32 v125, v125
	v_mul_f32_e32 v126, 0xbfb8aa3b, v126
	v_exp_f32_e32 v135, v135
	v_exp_f32_e32 v126, v126
	v_add_f32_e32 v127, 1.0, v125
	v_mul_f32_e32 v125, 0xbfb8aa3b, v113
	v_add_f32_e32 v124, 1.0, v135
	v_exp_f32_e32 v135, v125
	v_add_f32_e32 v125, 1.0, v126
	v_rcp_f32_e32 v124, v124
	v_rcp_f32_e32 v125, v125
	v_rcp_f32_e32 v126, v127
	v_add_f32_e32 v127, 1.0, v135
	v_rcp_f32_e32 v127, v127
	v_pk_mul_f32 v[116:117], v[116:117], v[124:125]
	v_mul_f32_e32 v124, 0x3d922279, v118
	v_fmaak_f32 v124, v118, v124, 0x3fcc422a
	v_mul_f32_e32 v124, v118, v124
	v_mul_f32_e32 v124, 0xbfb8aa3b, v124
	v_exp_f32_e32 v124, v124
	v_mul_f32_e32 v125, 0xbfb8aa3b, v114
	v_exp_f32_e32 v125, v125
	v_pk_mul_f32 v[112:113], v[116:117], v[112:113]
	v_add_f32_e32 v116, 1.0, v124
	v_mul_f32_e32 v124, 0x3d922279, v119
	v_fmaak_f32 v124, v119, v124, 0x3fcc422a
	v_mul_f32_e32 v124, v119, v124
	v_mul_f32_e32 v124, 0xbfb8aa3b, v124
	v_add_f32_e32 v117, 1.0, v125
	v_exp_f32_e32 v125, v124
	v_mul_f32_e32 v124, 0xbfb8aa3b, v115
	v_exp_f32_e32 v135, v124
	v_rcp_f32_e32 v124, v117
	v_add_f32_e32 v117, 1.0, v125
	v_rcp_f32_e32 v116, v116
	v_rcp_f32_e32 v117, v117
	v_add_f32_e32 v125, 1.0, v135
	s_lshl_b32 s4, s64, 7
	v_rcp_f32_e32 v125, v125
	v_pk_mul_f32 v[112:113], v[112:113], v[126:127]
	v_pk_mul_f32 v[116:117], v[118:119], v[116:117]
	s_ashr_i32 s5, s4, 31
	v_pk_mul_f32 v[114:115], v[116:117], v[114:115]
	v_cvt_pk_bf16_f32 v116, v112, v113
	v_mul_f32_e32 v112, 0x3d922279, v108
	s_lshl_b64 s[4:5], s[4:5], 1
	v_fmaak_f32 v112, v108, v112, 0x3fcc422a
	s_add_u32 s4, s88, s4
	v_mul_f32_e32 v112, v108, v112
	s_addc_u32 s5, s89, s5
	v_ashrrev_i32_e32 v137, 31, v136
	v_pk_mul_f32 v[118:119], v[114:115], v[124:125]
	v_ashrrev_i32_e32 v135, 31, v134
	v_mul_f32_e32 v112, 0xbfb8aa3b, v112
	v_lshl_add_u64 v[136:137], v[136:137], 1, s[4:5]
	v_pk_mul_f32 v[120:121], v[120:121], v[140:141]
	v_pk_mul_f32 v[122:123], v[122:123], v[138:139]
	v_cvt_pk_bf16_f32 v117, v118, v119
	v_exp_f32_e32 v118, v112
	v_lshlrev_b64 v[112:113], 12, v[134:135]
	v_cvt_pk_bf16_f32 v114, v120, v121
	v_cvt_pk_bf16_f32 v115, v122, v123
	v_lshl_add_u64 v[112:113], v[136:137], 0, v[112:113]
	global_store_dwordx4 v[112:113], v[114:117], off nt
	s_mov_b32 s3, 0x10000
	s_nop 0
	v_mul_f32_e32 v116, 0x3d922279, v109
	v_fmaak_f32 v116, v109, v116, 0x3fcc422a
	v_mul_f32_e32 v115, 0xbfb8aa3b, v104
	v_mul_f32_e32 v116, v109, v116
	v_exp_f32_e32 v115, v115
	v_mul_f32_e32 v116, 0xbfb8aa3b, v116
	v_exp_f32_e32 v116, v116
	v_add_f32_e32 v114, 1.0, v118
	v_add_f32_e32 v117, 1.0, v115
	v_mul_f32_e32 v115, 0xbfb8aa3b, v105
	v_exp_f32_e32 v118, v115
	v_add_f32_e32 v115, 1.0, v116
	v_rcp_f32_e32 v114, v114
	v_rcp_f32_e32 v115, v115
	v_rcp_f32_e32 v116, v117
	v_add_f32_e32 v117, 1.0, v118
	v_rcp_f32_e32 v117, v117
	v_pk_mul_f32 v[108:109], v[108:109], v[114:115]
	v_mul_f32_e32 v114, 0x3d922279, v111
	v_pk_mul_f32 v[104:105], v[108:109], v[104:105]
	v_mul_f32_e32 v108, 0x3d922279, v110
	v_fmaak_f32 v108, v110, v108, 0x3fcc422a
	v_fmaak_f32 v114, v111, v114, 0x3fcc422a
	v_mul_f32_e32 v108, v110, v108
	v_mul_f32_e32 v109, 0xbfb8aa3b, v106
	v_mul_f32_e32 v114, v111, v114
	v_mul_f32_e32 v108, 0xbfb8aa3b, v108
	v_exp_f32_e32 v109, v109
	v_mul_f32_e32 v114, 0xbfb8aa3b, v114
	v_exp_f32_e32 v108, v108
	v_exp_f32_e32 v115, v114
	v_add_f32_e32 v109, 1.0, v109
	v_mul_f32_e32 v114, 0xbfb8aa3b, v107
	v_pk_mul_f32 v[104:105], v[104:105], v[116:117]
	v_add_f32_e32 v108, 1.0, v108
	v_exp_f32_e32 v116, v114
	v_rcp_f32_e32 v114, v109
	v_add_f32_e32 v109, 1.0, v115
	v_rcp_f32_e32 v108, v108
	v_rcp_f32_e32 v109, v109
	v_add_f32_e32 v115, 1.0, v116
	v_mul_f32_e32 v116, 0x3d922279, v100
; __device__ __forceinline__ unsigned pk2(float lo, float hi) { return __builtin_bit_cast(unsigned, __builtin_convertvector((f32x2){lo, hi}, bf16x2_t)); }
; __device__ __forceinline__ float fsigmoid(float x) { return __builtin_amdgcn_rcpf(1.0f + fexp(-x)); }
; __device__ __forceinline__ float fgelu(float x) { return x * fsigmoid(x * (1.5957691216f + 0.0713548163f * x * x)); }
;     __device__ __forceinline__ void operator()(f32x4 (&acc)[2][2][4][2], const pg8::Unit& u, int wr, int wc, int fr, int fq) const {
;     ...
;             for (int ai = 0; ai < 2; ++ai)
; #pragma unroll
;                 for (int m = 0; m < 4; ++m) {
;                     float y[8];
; #pragma unroll
;                     for (int n = 0; n < 2; ++n)
; #pragma unroll
;                         for (int j = 0; j < 4; ++j) { const float uu = acc[ai][0][m][n][j], zz = acc[ai][1][m][n][j]; y[4 * n + j] = fgelu(uu) * zz * fsigmoid(zz); }
;                     *(u32x4*)(G + (size_t)(row0 + ai * 128 + m * 16) * BW) = (u32x4){pk2(y[0], y[1]), pk2(y[2], y[3]), pk2(y[4], y[5]), pk2(y[6], y[7])};
	v_fmaak_f32 v116, v100, v116, 0x3fcc422a
	v_pk_mul_f32 v[108:109], v[110:111], v[108:109]
	v_mul_f32_e32 v110, 0x3d922279, v101
	v_fmaak_f32 v110, v101, v110, 0x3fcc422a
	v_mul_f32_e32 v116, v100, v116
	v_pk_mul_f32 v[106:107], v[108:109], v[106:107]
	v_mul_f32_e32 v109, 0xbfb8aa3b, v96
	v_mul_f32_e32 v110, v101, v110
	v_mul_f32_e32 v116, 0xbfb8aa3b, v116
	v_exp_f32_e32 v109, v109
	v_mul_f32_e32 v110, 0xbfb8aa3b, v110
	v_rcp_f32_e32 v115, v115
	v_exp_f32_e32 v116, v116
	v_exp_f32_e32 v110, v110
	v_add_f32_e32 v111, 1.0, v109
	v_mul_f32_e32 v109, 0xbfb8aa3b, v97
	v_pk_mul_f32 v[106:107], v[106:107], v[114:115]
	v_add_f32_e32 v108, 1.0, v116
	v_exp_f32_e32 v114, v109
	v_add_f32_e32 v109, 1.0, v110
	v_rcp_f32_e32 v108, v108
	v_rcp_f32_e32 v109, v109
	v_rcp_f32_e32 v110, v111
	v_add_f32_e32 v111, 1.0, v114
	v_rcp_f32_e32 v111, v111
	v_pk_mul_f32 v[100:101], v[100:101], v[108:109]
	v_mul_f32_e32 v108, 0x3d922279, v102
	v_fmaak_f32 v108, v102, v108, 0x3fcc422a
	v_mul_f32_e32 v108, v102, v108
	v_mul_f32_e32 v108, 0xbfb8aa3b, v108
	v_exp_f32_e32 v108, v108
	v_mul_f32_e32 v109, 0xbfb8aa3b, v98
	v_exp_f32_e32 v109, v109
	v_pk_mul_f32 v[96:97], v[100:101], v[96:97]
	v_add_f32_e32 v100, 1.0, v108
	v_mul_f32_e32 v108, 0x3d922279, v103
	v_fmaak_f32 v108, v103, v108, 0x3fcc422a
	v_mul_f32_e32 v108, v103, v108
	v_mul_f32_e32 v108, 0xbfb8aa3b, v108
	v_add_f32_e32 v101, 1.0, v109
	v_exp_f32_e32 v109, v108
	v_mul_f32_e32 v108, 0xbfb8aa3b, v99
	v_exp_f32_e32 v114, v108
	v_rcp_f32_e32 v108, v101
	v_add_f32_e32 v101, 1.0, v109
	v_rcp_f32_e32 v100, v100
	v_rcp_f32_e32 v101, v101
	v_add_f32_e32 v109, 1.0, v114
	v_rcp_f32_e32 v109, v109
	v_pk_mul_f32 v[110:111], v[96:97], v[110:111]
	v_pk_mul_f32 v[96:97], v[102:103], v[100:101]
	s_nop 0
	v_pk_mul_f32 v[96:97], v[96:97], v[98:99]
	v_cvt_pk_bf16_f32 v98, v110, v111
	v_pk_mul_f32 v[100:101], v[96:97], v[108:109]
	v_cvt_pk_bf16_f32 v96, v104, v105
	v_cvt_pk_bf16_f32 v99, v100, v101
	v_mul_f32_e32 v100, 0x3d922279, v92
	v_fmaak_f32 v100, v92, v100, 0x3fcc422a
	v_mul_f32_e32 v100, v92, v100
	v_mul_f32_e32 v100, 0xbfb8aa3b, v100
	v_exp_f32_e32 v102, v100
	v_add_co_u32_e32 v100, vcc, s3, v112
	v_cvt_pk_bf16_f32 v97, v106, v107
	s_nop 0
	v_addc_co_u32_e32 v101, vcc, 0, v113, vcc
	global_store_dwordx4 v[100:101], v[96:99], off nt
	s_mov_b32 s3, 0x30000
	s_nop 0
	v_mul_f32_e32 v98, 0x3d922279, v93
	v_fmaak_f32 v98, v93, v98, 0x3fcc422a
	v_mul_f32_e32 v97, 0xbfb8aa3b, v88
	v_mul_f32_e32 v98, v93, v98
	v_exp_f32_e32 v97, v97
	v_mul_f32_e32 v98, 0xbfb8aa3b, v98
	v_exp_f32_e32 v98, v98
	v_add_f32_e32 v96, 1.0, v102
	v_add_f32_e32 v99, 1.0, v97
	v_mul_f32_e32 v97, 0xbfb8aa3b, v89
	v_exp_f32_e32 v100, v97
	v_add_f32_e32 v97, 1.0, v98
	v_rcp_f32_e32 v96, v96
	v_rcp_f32_e32 v97, v97
	v_rcp_f32_e32 v98, v99
	v_add_f32_e32 v99, 1.0, v100
	v_rcp_f32_e32 v99, v99
	v_pk_mul_f32 v[92:93], v[92:93], v[96:97]
	v_mul_f32_e32 v96, 0x3d922279, v95
	v_pk_mul_f32 v[88:89], v[92:93], v[88:89]
	v_mul_f32_e32 v92, 0x3d922279, v94
	v_fmaak_f32 v92, v94, v92, 0x3fcc422a
	v_fmaak_f32 v96, v95, v96, 0x3fcc422a
	v_mul_f32_e32 v92, v94, v92
	v_mul_f32_e32 v93, 0xbfb8aa3b, v90
	v_mul_f32_e32 v96, v95, v96
	v_mul_f32_e32 v92, 0xbfb8aa3b, v92
	v_exp_f32_e32 v93, v93
	v_mul_f32_e32 v96, 0xbfb8aa3b, v96
	v_exp_f32_e32 v92, v92
	v_exp_f32_e32 v97, v96
	v_add_f32_e32 v93, 1.0, v93
	v_mul_f32_e32 v96, 0xbfb8aa3b, v91
	v_pk_mul_f32 v[88:89], v[88:89], v[98:99]
	v_add_f32_e32 v92, 1.0, v92
	v_exp_f32_e32 v98, v96
	v_rcp_f32_e32 v96, v93
	v_add_f32_e32 v93, 1.0, v97
	v_rcp_f32_e32 v92, v92
	v_rcp_f32_e32 v93, v93
	v_add_f32_e32 v97, 1.0, v98
	v_mul_f32_e32 v98, 0x3d922279, v84
	v_fmaak_f32 v98, v84, v98, 0x3fcc422a
	v_pk_mul_f32 v[92:93], v[94:95], v[92:93]
	v_mul_f32_e32 v94, 0x3d922279, v85
	v_fmaak_f32 v94, v85, v94, 0x3fcc422a
	v_mul_f32_e32 v98, v84, v98
	v_pk_mul_f32 v[90:91], v[92:93], v[90:91]
	v_mul_f32_e32 v93, 0xbfb8aa3b, v80
	v_mul_f32_e32 v94, v85, v94
	v_mul_f32_e32 v98, 0xbfb8aa3b, v98
	v_exp_f32_e32 v93, v93
	v_mul_f32_e32 v94, 0xbfb8aa3b, v94
	v_rcp_f32_e32 v97, v97
	v_exp_f32_e32 v98, v98
	v_exp_f32_e32 v94, v94
	v_add_f32_e32 v95, 1.0, v93
	v_mul_f32_e32 v93, 0xbfb8aa3b, v81
	v_pk_mul_f32 v[90:91], v[90:91], v[96:97]
	v_add_f32_e32 v92, 1.0, v98
	v_exp_f32_e32 v96, v93
	v_add_f32_e32 v93, 1.0, v94
	v_rcp_f32_e32 v92, v92
	v_rcp_f32_e32 v93, v93
	v_rcp_f32_e32 v94, v95
	v_add_f32_e32 v95, 1.0, v96
	v_rcp_f32_e32 v95, v95
	v_pk_mul_f32 v[84:85], v[84:85], v[92:93]
	v_mul_f32_e32 v92, 0x3d922279, v86
	v_fmaak_f32 v92, v86, v92, 0x3fcc422a
	v_mul_f32_e32 v92, v86, v92
	v_mul_f32_e32 v92, 0xbfb8aa3b, v92
	v_exp_f32_e32 v92, v92
	v_mul_f32_e32 v93, 0xbfb8aa3b, v82
	v_exp_f32_e32 v93, v93
	v_pk_mul_f32 v[80:81], v[84:85], v[80:81]
	v_add_f32_e32 v84, 1.0, v92
	v_mul_f32_e32 v92, 0x3d922279, v87
	v_fmaak_f32 v92, v87, v92, 0x3fcc422a
	v_mul_f32_e32 v92, v87, v92
	v_mul_f32_e32 v92, 0xbfb8aa3b, v92
	v_add_f32_e32 v85, 1.0, v93
	v_exp_f32_e32 v93, v92
	v_mul_f32_e32 v92, 0xbfb8aa3b, v83
	v_exp_f32_e32 v96, v92
	v_rcp_f32_e32 v92, v85
	v_add_f32_e32 v85, 1.0, v93
	v_rcp_f32_e32 v84, v84
	v_rcp_f32_e32 v85, v85
	v_add_f32_e32 v93, 1.0, v96
	v_rcp_f32_e32 v93, v93
	v_pk_mul_f32 v[94:95], v[80:81], v[94:95]
	v_pk_mul_f32 v[80:81], v[86:87], v[84:85]
	s_nop 0
	v_pk_mul_f32 v[80:81], v[80:81], v[82:83]
	v_cvt_pk_bf16_f32 v82, v94, v95
	v_pk_mul_f32 v[84:85], v[80:81], v[92:93]
	v_cvt_pk_bf16_f32 v80, v88, v89
	v_cvt_pk_bf16_f32 v83, v84, v85
	v_mul_f32_e32 v84, 0x3d922279, v76
	v_fmaak_f32 v84, v76, v84, 0x3fcc422a
	v_mul_f32_e32 v84, v76, v84
	v_mul_f32_e32 v84, 0xbfb8aa3b, v84
	v_exp_f32_e32 v86, v84
	v_add_co_u32_e32 v84, vcc, s94, v112
; __device__ __forceinline__ unsigned pk2(float lo, float hi) { return __builtin_bit_cast(unsigned, __builtin_convertvector((f32x2){lo, hi}, bf16x2_t)); }
; __device__ __forceinline__ float fsigmoid(float x) { return __builtin_amdgcn_rcpf(1.0f + fexp(-x)); }
; __device__ __forceinline__ float fgelu(float x) { return x * fsigmoid(x * (1.5957691216f + 0.0713548163f * x * x)); }
;     __device__ __forceinline__ void operator()(f32x4 (&acc)[2][2][4][2], const pg8::Unit& u, int wr, int wc, int fr, int fq) const {
;     ...
;             for (int ai = 0; ai < 2; ++ai)
; #pragma unroll
;                 for (int m = 0; m < 4; ++m) {
;                     float y[8];
; #pragma unroll
;                     for (int n = 0; n < 2; ++n)
; #pragma unroll
;                         for (int j = 0; j < 4; ++j) { const float uu = acc[ai][0][m][n][j], zz = acc[ai][1][m][n][j]; y[4 * n + j] = fgelu(uu) * zz * fsigmoid(zz); }
;                     *(u32x4*)(G + (size_t)(row0 + ai * 128 + m * 16) * BW) = (u32x4){pk2(y[0], y[1]), pk2(y[2], y[3]), pk2(y[4], y[5]), pk2(y[6], y[7])};
	v_cvt_pk_bf16_f32 v81, v90, v91
	s_nop 0
	v_addc_co_u32_e32 v85, vcc, 0, v113, vcc
	global_store_dwordx4 v[84:85], v[80:83], off nt
	s_nop 1
	v_mul_f32_e32 v82, 0x3d922279, v77
	v_fmaak_f32 v82, v77, v82, 0x3fcc422a
	v_mul_f32_e32 v81, 0xbfb8aa3b, v72
	v_mul_f32_e32 v82, v77, v82
	v_exp_f32_e32 v81, v81
	v_mul_f32_e32 v82, 0xbfb8aa3b, v82
	v_exp_f32_e32 v82, v82
	v_add_f32_e32 v80, 1.0, v86
	v_add_f32_e32 v83, 1.0, v81
	v_mul_f32_e32 v81, 0xbfb8aa3b, v73
	v_exp_f32_e32 v84, v81
	v_add_f32_e32 v81, 1.0, v82
	v_rcp_f32_e32 v80, v80
	v_rcp_f32_e32 v81, v81
	v_rcp_f32_e32 v82, v83
	v_add_f32_e32 v83, 1.0, v84
	v_rcp_f32_e32 v83, v83
	v_pk_mul_f32 v[76:77], v[76:77], v[80:81]
	v_mul_f32_e32 v80, 0x3d922279, v79
	v_pk_mul_f32 v[72:73], v[76:77], v[72:73]
	v_mul_f32_e32 v76, 0x3d922279, v78
	v_fmaak_f32 v76, v78, v76, 0x3fcc422a
	v_fmaak_f32 v80, v79, v80, 0x3fcc422a
	v_mul_f32_e32 v76, v78, v76
	v_mul_f32_e32 v77, 0xbfb8aa3b, v74
	v_mul_f32_e32 v80, v79, v80
	v_mul_f32_e32 v76, 0xbfb8aa3b, v76
	v_exp_f32_e32 v77, v77
	v_mul_f32_e32 v80, 0xbfb8aa3b, v80
	v_exp_f32_e32 v76, v76
	v_exp_f32_e32 v81, v80
	v_add_f32_e32 v77, 1.0, v77
	v_mul_f32_e32 v80, 0xbfb8aa3b, v75
	v_pk_mul_f32 v[72:73], v[72:73], v[82:83]
	v_add_f32_e32 v76, 1.0, v76
	v_exp_f32_e32 v82, v80
	v_rcp_f32_e32 v80, v77
	v_add_f32_e32 v77, 1.0, v81
	v_rcp_f32_e32 v76, v76
	v_rcp_f32_e32 v77, v77
	v_add_f32_e32 v81, 1.0, v82
	v_mul_f32_e32 v82, 0x3d922279, v68
	v_fmaak_f32 v82, v68, v82, 0x3fcc422a
	v_pk_mul_f32 v[76:77], v[78:79], v[76:77]
	v_mul_f32_e32 v78, 0x3d922279, v69
	v_fmaak_f32 v78, v69, v78, 0x3fcc422a
	v_mul_f32_e32 v82, v68, v82
	v_pk_mul_f32 v[74:75], v[76:77], v[74:75]
	v_mul_f32_e32 v77, 0xbfb8aa3b, v64
	v_mul_f32_e32 v78, v69, v78
	v_mul_f32_e32 v82, 0xbfb8aa3b, v82
	v_exp_f32_e32 v77, v77
	v_mul_f32_e32 v78, 0xbfb8aa3b, v78
	v_rcp_f32_e32 v81, v81
	v_exp_f32_e32 v82, v82
	v_exp_f32_e32 v78, v78
	v_add_f32_e32 v79, 1.0, v77
	v_mul_f32_e32 v77, 0xbfb8aa3b, v65
	v_pk_mul_f32 v[74:75], v[74:75], v[80:81]
	v_add_f32_e32 v76, 1.0, v82
	v_exp_f32_e32 v80, v77
	v_add_f32_e32 v77, 1.0, v78
	v_rcp_f32_e32 v76, v76
	v_rcp_f32_e32 v77, v77
	v_rcp_f32_e32 v78, v79
	v_add_f32_e32 v79, 1.0, v80
	v_rcp_f32_e32 v79, v79
	v_pk_mul_f32 v[68:69], v[68:69], v[76:77]
	v_mul_f32_e32 v76, 0x3d922279, v70
	v_fmaak_f32 v76, v70, v76, 0x3fcc422a
	v_mul_f32_e32 v76, v70, v76
	v_mul_f32_e32 v76, 0xbfb8aa3b, v76
	v_exp_f32_e32 v76, v76
	v_mul_f32_e32 v77, 0xbfb8aa3b, v66
	v_exp_f32_e32 v77, v77
	v_pk_mul_f32 v[64:65], v[68:69], v[64:65]
	v_add_f32_e32 v68, 1.0, v76
	v_mul_f32_e32 v76, 0x3d922279, v71
	v_fmaak_f32 v76, v71, v76, 0x3fcc422a
	v_mul_f32_e32 v76, v71, v76
	v_mul_f32_e32 v76, 0xbfb8aa3b, v76
	v_add_f32_e32 v69, 1.0, v77
	v_exp_f32_e32 v77, v76
	v_mul_f32_e32 v76, 0xbfb8aa3b, v67
	v_exp_f32_e32 v80, v76
	v_rcp_f32_e32 v76, v69
	v_add_f32_e32 v69, 1.0, v77
	v_rcp_f32_e32 v68, v68
	v_rcp_f32_e32 v69, v69
	v_add_f32_e32 v77, 1.0, v80
	v_rcp_f32_e32 v77, v77
	v_pk_mul_f32 v[78:79], v[64:65], v[78:79]
	v_pk_mul_f32 v[64:65], v[70:71], v[68:69]
	s_nop 0
	v_pk_mul_f32 v[64:65], v[64:65], v[66:67]
	v_cvt_pk_bf16_f32 v66, v78, v79
	v_pk_mul_f32 v[68:69], v[64:65], v[76:77]
	v_cvt_pk_bf16_f32 v64, v72, v73
	v_cvt_pk_bf16_f32 v67, v68, v69
	v_mul_f32_e32 v68, 0x3d922279, v60
	v_fmaak_f32 v68, v60, v68, 0x3fcc422a
	v_mul_f32_e32 v68, v60, v68
	v_mul_f32_e32 v68, 0xbfb8aa3b, v68
	v_exp_f32_e32 v70, v68
	v_add_co_u32_e32 v68, vcc, s3, v112
	v_cvt_pk_bf16_f32 v65, v74, v75
	s_nop 0
	v_addc_co_u32_e32 v69, vcc, 0, v113, vcc
	global_store_dwordx4 v[68:69], v[64:67], off nt
	s_mov_b32 s3, 0x80000
	s_nop 0
	v_mul_f32_e32 v66, 0x3d922279, v61
	v_fmaak_f32 v66, v61, v66, 0x3fcc422a
	v_mul_f32_e32 v65, 0xbfb8aa3b, v56
	v_mul_f32_e32 v66, v61, v66
	v_exp_f32_e32 v65, v65
	v_mul_f32_e32 v66, 0xbfb8aa3b, v66
	v_exp_f32_e32 v66, v66
	v_add_f32_e32 v64, 1.0, v70
	v_add_f32_e32 v67, 1.0, v65
	v_mul_f32_e32 v65, 0xbfb8aa3b, v57
	v_exp_f32_e32 v68, v65
	v_add_f32_e32 v65, 1.0, v66
	v_rcp_f32_e32 v64, v64
	v_rcp_f32_e32 v65, v65
	v_rcp_f32_e32 v66, v67
	v_add_f32_e32 v67, 1.0, v68
	v_rcp_f32_e32 v67, v67
	v_pk_mul_f32 v[60:61], v[60:61], v[64:65]
	v_mul_f32_e32 v64, 0x3d922279, v63
	v_pk_mul_f32 v[56:57], v[60:61], v[56:57]
	v_mul_f32_e32 v60, 0x3d922279, v62
	v_fmaak_f32 v60, v62, v60, 0x3fcc422a
	v_fmaak_f32 v64, v63, v64, 0x3fcc422a
	v_mul_f32_e32 v60, v62, v60
	v_mul_f32_e32 v61, 0xbfb8aa3b, v58
	v_mul_f32_e32 v64, v63, v64
	v_mul_f32_e32 v60, 0xbfb8aa3b, v60
	v_exp_f32_e32 v61, v61
	v_mul_f32_e32 v64, 0xbfb8aa3b, v64
	v_exp_f32_e32 v60, v60
	v_exp_f32_e32 v65, v64
	v_add_f32_e32 v61, 1.0, v61
	v_mul_f32_e32 v64, 0xbfb8aa3b, v59
	v_pk_mul_f32 v[56:57], v[56:57], v[66:67]
	v_add_f32_e32 v60, 1.0, v60
	v_exp_f32_e32 v66, v64
	v_rcp_f32_e32 v64, v61
	v_add_f32_e32 v61, 1.0, v65
	v_rcp_f32_e32 v60, v60
	v_rcp_f32_e32 v61, v61
	v_add_f32_e32 v65, 1.0, v66
	v_mul_f32_e32 v66, 0x3d922279, v52
	v_fmaak_f32 v66, v52, v66, 0x3fcc422a
	v_pk_mul_f32 v[60:61], v[62:63], v[60:61]
	v_mul_f32_e32 v62, 0x3d922279, v53
	v_fmaak_f32 v62, v53, v62, 0x3fcc422a
	v_mul_f32_e32 v66, v52, v66
	v_pk_mul_f32 v[58:59], v[60:61], v[58:59]
	v_mul_f32_e32 v61, 0xbfb8aa3b, v48
	v_mul_f32_e32 v62, v53, v62
	v_mul_f32_e32 v66, 0xbfb8aa3b, v66
	v_exp_f32_e32 v61, v61
	v_mul_f32_e32 v62, 0xbfb8aa3b, v62
	v_rcp_f32_e32 v65, v65
	v_exp_f32_e32 v66, v66
	v_exp_f32_e32 v62, v62
	v_add_f32_e32 v63, 1.0, v61
	v_mul_f32_e32 v61, 0xbfb8aa3b, v49
	v_pk_mul_f32 v[58:59], v[58:59], v[64:65]
	v_add_f32_e32 v60, 1.0, v66
	v_exp_f32_e32 v64, v61
	v_add_f32_e32 v61, 1.0, v62
	v_rcp_f32_e32 v60, v60
	v_rcp_f32_e32 v61, v61
	v_rcp_f32_e32 v62, v63
; __device__ __forceinline__ unsigned pk2(float lo, float hi) { return __builtin_bit_cast(unsigned, __builtin_convertvector((f32x2){lo, hi}, bf16x2_t)); }
; __device__ __forceinline__ float fsigmoid(float x) { return __builtin_amdgcn_rcpf(1.0f + fexp(-x)); }
; __device__ __forceinline__ float fgelu(float x) { return x * fsigmoid(x * (1.5957691216f + 0.0713548163f * x * x)); }
;     __device__ __forceinline__ void operator()(f32x4 (&acc)[2][2][4][2], const pg8::Unit& u, int wr, int wc, int fr, int fq) const {
;     ...
;             for (int ai = 0; ai < 2; ++ai)
; #pragma unroll
;                 for (int m = 0; m < 4; ++m) {
;                     float y[8];
; #pragma unroll
;                     for (int n = 0; n < 2; ++n)
; #pragma unroll
;                         for (int j = 0; j < 4; ++j) { const float uu = acc[ai][0][m][n][j], zz = acc[ai][1][m][n][j]; y[4 * n + j] = fgelu(uu) * zz * fsigmoid(zz); }
;                     *(u32x4*)(G + (size_t)(row0 + ai * 128 + m * 16) * BW) = (u32x4){pk2(y[0], y[1]), pk2(y[2], y[3]), pk2(y[4], y[5]), pk2(y[6], y[7])};
	v_add_f32_e32 v63, 1.0, v64
	v_rcp_f32_e32 v63, v63
	v_pk_mul_f32 v[52:53], v[52:53], v[60:61]
	v_mul_f32_e32 v60, 0x3d922279, v54
	v_fmaak_f32 v60, v54, v60, 0x3fcc422a
	v_mul_f32_e32 v60, v54, v60
	v_mul_f32_e32 v60, 0xbfb8aa3b, v60
	v_exp_f32_e32 v60, v60
	v_mul_f32_e32 v61, 0xbfb8aa3b, v50
	v_exp_f32_e32 v61, v61
	v_pk_mul_f32 v[48:49], v[52:53], v[48:49]
	v_add_f32_e32 v52, 1.0, v60
	v_mul_f32_e32 v60, 0x3d922279, v55
	v_fmaak_f32 v60, v55, v60, 0x3fcc422a
	v_mul_f32_e32 v60, v55, v60
	v_mul_f32_e32 v60, 0xbfb8aa3b, v60
	v_add_f32_e32 v53, 1.0, v61
	v_exp_f32_e32 v61, v60
	v_mul_f32_e32 v60, 0xbfb8aa3b, v51
	v_exp_f32_e32 v64, v60
	v_rcp_f32_e32 v60, v53
	v_add_f32_e32 v53, 1.0, v61
	v_rcp_f32_e32 v52, v52
	v_rcp_f32_e32 v53, v53
	v_add_f32_e32 v61, 1.0, v64
	v_rcp_f32_e32 v61, v61
	v_pk_mul_f32 v[62:63], v[48:49], v[62:63]
	v_pk_mul_f32 v[48:49], v[54:55], v[52:53]
	s_nop 0
	v_pk_mul_f32 v[48:49], v[48:49], v[50:51]
	v_cvt_pk_bf16_f32 v50, v62, v63
	v_pk_mul_f32 v[52:53], v[48:49], v[60:61]
	v_cvt_pk_bf16_f32 v48, v56, v57
	v_cvt_pk_bf16_f32 v51, v52, v53
	v_mul_f32_e32 v52, 0x3d922279, v44
	v_fmaak_f32 v52, v44, v52, 0x3fcc422a
	v_mul_f32_e32 v52, v44, v52
	v_mul_f32_e32 v52, 0xbfb8aa3b, v52
	v_exp_f32_e32 v54, v52
	v_add_co_u32_e32 v52, vcc, s3, v112
	v_cvt_pk_bf16_f32 v49, v58, v59
	s_nop 0
	v_addc_co_u32_e32 v53, vcc, 0, v113, vcc
	global_store_dwordx4 v[52:53], v[48:51], off nt
	s_mov_b32 s3, 0x90000
	s_nop 0
	v_mul_f32_e32 v50, 0x3d922279, v45
	v_fmaak_f32 v50, v45, v50, 0x3fcc422a
	v_mul_f32_e32 v49, 0xbfb8aa3b, v40
	v_mul_f32_e32 v50, v45, v50
	v_exp_f32_e32 v49, v49
	v_mul_f32_e32 v50, 0xbfb8aa3b, v50
	v_exp_f32_e32 v50, v50
	v_add_f32_e32 v48, 1.0, v54
	v_add_f32_e32 v51, 1.0, v49
	v_mul_f32_e32 v49, 0xbfb8aa3b, v41
	v_exp_f32_e32 v52, v49
	v_add_f32_e32 v49, 1.0, v50
	v_rcp_f32_e32 v48, v48
	v_rcp_f32_e32 v49, v49
	v_rcp_f32_e32 v50, v51
	v_add_f32_e32 v51, 1.0, v52
	v_rcp_f32_e32 v51, v51
	v_pk_mul_f32 v[44:45], v[44:45], v[48:49]
	v_mul_f32_e32 v48, 0x3d922279, v47
	v_pk_mul_f32 v[40:41], v[44:45], v[40:41]
	v_mul_f32_e32 v44, 0x3d922279, v46
	v_fmaak_f32 v44, v46, v44, 0x3fcc422a
	v_fmaak_f32 v48, v47, v48, 0x3fcc422a
	v_mul_f32_e32 v44, v46, v44
	v_mul_f32_e32 v45, 0xbfb8aa3b, v42
	v_mul_f32_e32 v48, v47, v48
	v_mul_f32_e32 v44, 0xbfb8aa3b, v44
	v_exp_f32_e32 v45, v45
	v_mul_f32_e32 v48, 0xbfb8aa3b, v48
	v_exp_f32_e32 v44, v44
	v_exp_f32_e32 v49, v48
	v_add_f32_e32 v45, 1.0, v45
	v_mul_f32_e32 v48, 0xbfb8aa3b, v43
	v_pk_mul_f32 v[40:41], v[40:41], v[50:51]
	v_add_f32_e32 v44, 1.0, v44
	v_exp_f32_e32 v50, v48
	v_rcp_f32_e32 v48, v45
	v_add_f32_e32 v45, 1.0, v49
	v_rcp_f32_e32 v44, v44
	v_rcp_f32_e32 v45, v45
	v_add_f32_e32 v49, 1.0, v50
	v_mul_f32_e32 v50, 0x3d922279, v36
	v_fmaak_f32 v50, v36, v50, 0x3fcc422a
	v_pk_mul_f32 v[44:45], v[46:47], v[44:45]
	v_mul_f32_e32 v46, 0x3d922279, v37
	v_fmaak_f32 v46, v37, v46, 0x3fcc422a
	v_mul_f32_e32 v50, v36, v50
	v_pk_mul_f32 v[42:43], v[44:45], v[42:43]
	v_mul_f32_e32 v45, 0xbfb8aa3b, v32
	v_mul_f32_e32 v46, v37, v46
	v_mul_f32_e32 v50, 0xbfb8aa3b, v50
	v_exp_f32_e32 v45, v45
	v_mul_f32_e32 v46, 0xbfb8aa3b, v46
	v_rcp_f32_e32 v49, v49
	v_exp_f32_e32 v50, v50
	v_exp_f32_e32 v46, v46
	v_add_f32_e32 v47, 1.0, v45
	v_mul_f32_e32 v45, 0xbfb8aa3b, v33
	v_pk_mul_f32 v[42:43], v[42:43], v[48:49]
	v_add_f32_e32 v44, 1.0, v50
	v_exp_f32_e32 v48, v45
	v_add_f32_e32 v45, 1.0, v46
	v_rcp_f32_e32 v44, v44
	v_rcp_f32_e32 v45, v45
	v_rcp_f32_e32 v46, v47
	v_add_f32_e32 v47, 1.0, v48
	v_rcp_f32_e32 v47, v47
	v_pk_mul_f32 v[36:37], v[36:37], v[44:45]
	v_mul_f32_e32 v44, 0x3d922279, v38
	v_fmaak_f32 v44, v38, v44, 0x3fcc422a
	v_mul_f32_e32 v44, v38, v44
	v_mul_f32_e32 v44, 0xbfb8aa3b, v44
	v_exp_f32_e32 v44, v44
	v_mul_f32_e32 v45, 0xbfb8aa3b, v34
	v_exp_f32_e32 v45, v45
	v_pk_mul_f32 v[32:33], v[36:37], v[32:33]
	v_add_f32_e32 v36, 1.0, v44
	v_mul_f32_e32 v44, 0x3d922279, v39
	v_fmaak_f32 v44, v39, v44, 0x3fcc422a
	v_mul_f32_e32 v44, v39, v44
	v_mul_f32_e32 v44, 0xbfb8aa3b, v44
	v_add_f32_e32 v37, 1.0, v45
	v_exp_f32_e32 v45, v44
	v_mul_f32_e32 v44, 0xbfb8aa3b, v35
	v_exp_f32_e32 v48, v44
	v_rcp_f32_e32 v44, v37
	v_add_f32_e32 v37, 1.0, v45
	v_rcp_f32_e32 v36, v36
	v_rcp_f32_e32 v37, v37
	v_add_f32_e32 v45, 1.0, v48
	v_rcp_f32_e32 v45, v45
	v_pk_mul_f32 v[46:47], v[32:33], v[46:47]
	v_pk_mul_f32 v[32:33], v[38:39], v[36:37]
	s_nop 0
	v_pk_mul_f32 v[32:33], v[32:33], v[34:35]
	v_cvt_pk_bf16_f32 v34, v46, v47
	v_pk_mul_f32 v[36:37], v[32:33], v[44:45]
	v_cvt_pk_bf16_f32 v32, v40, v41
	v_cvt_pk_bf16_f32 v35, v36, v37
	v_mul_f32_e32 v36, 0x3d922279, v28
	v_fmaak_f32 v36, v28, v36, 0x3fcc422a
	v_mul_f32_e32 v36, v28, v36
	v_mul_f32_e32 v36, 0xbfb8aa3b, v36
	v_exp_f32_e32 v38, v36
	v_add_co_u32_e32 v36, vcc, s3, v112
	v_cvt_pk_bf16_f32 v33, v42, v43
	s_nop 0
	v_addc_co_u32_e32 v37, vcc, 0, v113, vcc
	global_store_dwordx4 v[36:37], v[32:35], off nt
	s_mov_b32 s3, 0xa0000
	s_nop 0
	v_mul_f32_e32 v34, 0x3d922279, v29
	v_fmaak_f32 v34, v29, v34, 0x3fcc422a
	v_mul_f32_e32 v33, 0xbfb8aa3b, v24
	v_mul_f32_e32 v34, v29, v34
	v_exp_f32_e32 v33, v33
	v_mul_f32_e32 v34, 0xbfb8aa3b, v34
	v_exp_f32_e32 v34, v34
	v_add_f32_e32 v32, 1.0, v38
	v_add_f32_e32 v35, 1.0, v33
	v_mul_f32_e32 v33, 0xbfb8aa3b, v25
	v_exp_f32_e32 v36, v33
	v_add_f32_e32 v33, 1.0, v34
	v_rcp_f32_e32 v32, v32
	v_rcp_f32_e32 v33, v33
	v_rcp_f32_e32 v34, v35
	v_add_f32_e32 v35, 1.0, v36
	v_rcp_f32_e32 v35, v35
	v_pk_mul_f32 v[28:29], v[28:29], v[32:33]
	v_mul_f32_e32 v32, 0x3d922279, v31
	v_pk_mul_f32 v[24:25], v[28:29], v[24:25]
	v_mul_f32_e32 v28, 0x3d922279, v30
	v_fmaak_f32 v28, v30, v28, 0x3fcc422a
	v_fmaak_f32 v32, v31, v32, 0x3fcc422a
; __device__ __forceinline__ unsigned pk2(float lo, float hi) { return __builtin_bit_cast(unsigned, __builtin_convertvector((f32x2){lo, hi}, bf16x2_t)); }
; __device__ __forceinline__ float fsigmoid(float x) { return __builtin_amdgcn_rcpf(1.0f + fexp(-x)); }
; __device__ __forceinline__ float fgelu(float x) { return x * fsigmoid(x * (1.5957691216f + 0.0713548163f * x * x)); }
;     __device__ __forceinline__ void operator()(f32x4 (&acc)[2][2][4][2], const pg8::Unit& u, int wr, int wc, int fr, int fq) const {
;     ...
;         if (tile < 16) {
;             bf16_t* G = (bf16_t*)(ws + WS_GUZ) + tile * 128 + c8;
; #pragma unroll
;             for (int ai = 0; ai < 2; ++ai)
; #pragma unroll
;                 for (int m = 0; m < 4; ++m) {
;                     float y[8];
; #pragma unroll
;                     for (int n = 0; n < 2; ++n)
; #pragma unroll
;                         for (int j = 0; j < 4; ++j) { const float uu = acc[ai][0][m][n][j], zz = acc[ai][1][m][n][j]; y[4 * n + j] = fgelu(uu) * zz * fsigmoid(zz); }
;                     *(u32x4*)(G + (size_t)(row0 + ai * 128 + m * 16) * BW) = (u32x4){pk2(y[0], y[1]), pk2(y[2], y[3]), pk2(y[4], y[5]), pk2(y[6], y[7])};
;                 }
	v_mul_f32_e32 v28, v30, v28
	v_mul_f32_e32 v29, 0xbfb8aa3b, v26
	v_mul_f32_e32 v32, v31, v32
	v_mul_f32_e32 v28, 0xbfb8aa3b, v28
	v_exp_f32_e32 v29, v29
	v_mul_f32_e32 v32, 0xbfb8aa3b, v32
	v_exp_f32_e32 v28, v28
	v_exp_f32_e32 v33, v32
	v_add_f32_e32 v29, 1.0, v29
	v_mul_f32_e32 v32, 0xbfb8aa3b, v27
	v_pk_mul_f32 v[24:25], v[24:25], v[34:35]
	v_add_f32_e32 v28, 1.0, v28
	v_exp_f32_e32 v34, v32
	v_rcp_f32_e32 v32, v29
	v_add_f32_e32 v29, 1.0, v33
	v_rcp_f32_e32 v28, v28
	v_rcp_f32_e32 v29, v29
	v_add_f32_e32 v33, 1.0, v34
	v_mul_f32_e32 v34, 0x3d922279, v20
	v_fmaak_f32 v34, v20, v34, 0x3fcc422a
	v_pk_mul_f32 v[28:29], v[30:31], v[28:29]
	v_mul_f32_e32 v30, 0x3d922279, v21
	v_fmaak_f32 v30, v21, v30, 0x3fcc422a
	v_mul_f32_e32 v34, v20, v34
	v_pk_mul_f32 v[26:27], v[28:29], v[26:27]
	v_mul_f32_e32 v29, 0xbfb8aa3b, v16
	v_mul_f32_e32 v30, v21, v30
	v_mul_f32_e32 v34, 0xbfb8aa3b, v34
	v_exp_f32_e32 v29, v29
	v_mul_f32_e32 v30, 0xbfb8aa3b, v30
	v_rcp_f32_e32 v33, v33
	v_exp_f32_e32 v34, v34
	v_exp_f32_e32 v30, v30
	v_add_f32_e32 v31, 1.0, v29
	v_mul_f32_e32 v29, 0xbfb8aa3b, v17
	v_pk_mul_f32 v[26:27], v[26:27], v[32:33]
	v_add_f32_e32 v28, 1.0, v34
	v_exp_f32_e32 v32, v29
	v_add_f32_e32 v29, 1.0, v30
	v_rcp_f32_e32 v28, v28
	v_rcp_f32_e32 v29, v29
	v_rcp_f32_e32 v30, v31
	v_add_f32_e32 v31, 1.0, v32
	v_rcp_f32_e32 v31, v31
	v_pk_mul_f32 v[20:21], v[20:21], v[28:29]
	v_mul_f32_e32 v28, 0x3d922279, v22
	v_fmaak_f32 v28, v22, v28, 0x3fcc422a
	v_mul_f32_e32 v28, v22, v28
	v_mul_f32_e32 v28, 0xbfb8aa3b, v28
	v_exp_f32_e32 v28, v28
	v_mul_f32_e32 v29, 0xbfb8aa3b, v18
	v_exp_f32_e32 v29, v29
	v_pk_mul_f32 v[16:17], v[20:21], v[16:17]
	v_add_f32_e32 v20, 1.0, v28
	v_mul_f32_e32 v28, 0x3d922279, v23
	v_fmaak_f32 v28, v23, v28, 0x3fcc422a
	v_mul_f32_e32 v28, v23, v28
	v_mul_f32_e32 v28, 0xbfb8aa3b, v28
	v_add_f32_e32 v21, 1.0, v29
	v_exp_f32_e32 v29, v28
	v_mul_f32_e32 v28, 0xbfb8aa3b, v19
	v_exp_f32_e32 v32, v28
	v_rcp_f32_e32 v28, v21
	v_add_f32_e32 v21, 1.0, v29
	v_rcp_f32_e32 v20, v20
	v_rcp_f32_e32 v21, v21
	v_add_f32_e32 v29, 1.0, v32
	v_rcp_f32_e32 v29, v29
	v_pk_mul_f32 v[30:31], v[16:17], v[30:31]
	v_pk_mul_f32 v[16:17], v[22:23], v[20:21]
	s_nop 0
	v_pk_mul_f32 v[16:17], v[16:17], v[18:19]
	v_cvt_pk_bf16_f32 v18, v30, v31
	v_pk_mul_f32 v[20:21], v[16:17], v[28:29]
	v_cvt_pk_bf16_f32 v16, v24, v25
	v_cvt_pk_bf16_f32 v19, v20, v21
	v_mul_f32_e32 v20, 0x3d922279, v12
	v_fmaak_f32 v20, v12, v20, 0x3fcc422a
	v_mul_f32_e32 v20, v12, v20
	v_mul_f32_e32 v20, 0xbfb8aa3b, v20
	v_exp_f32_e32 v22, v20
	v_add_co_u32_e32 v20, vcc, s3, v112
	v_cvt_pk_bf16_f32 v17, v26, v27
	s_nop 0
	v_addc_co_u32_e32 v21, vcc, 0, v113, vcc
	global_store_dwordx4 v[20:21], v[16:19], off nt
	s_nop 1
	v_mul_f32_e32 v18, 0x3d922279, v13
	v_fmaak_f32 v18, v13, v18, 0x3fcc422a
	v_mul_f32_e32 v17, 0xbfb8aa3b, v8
	v_mul_f32_e32 v18, v13, v18
	v_exp_f32_e32 v17, v17
	v_mul_f32_e32 v18, 0xbfb8aa3b, v18
	v_exp_f32_e32 v18, v18
	v_add_f32_e32 v16, 1.0, v22
	v_add_f32_e32 v19, 1.0, v17
	v_mul_f32_e32 v17, 0xbfb8aa3b, v9
	v_exp_f32_e32 v20, v17
	v_add_f32_e32 v17, 1.0, v18
	v_rcp_f32_e32 v16, v16
	v_rcp_f32_e32 v17, v17
	v_rcp_f32_e32 v18, v19
	v_add_f32_e32 v19, 1.0, v20
	v_rcp_f32_e32 v19, v19
	v_pk_mul_f32 v[12:13], v[12:13], v[16:17]
	v_mul_f32_e32 v16, 0x3d922279, v15
	v_pk_mul_f32 v[8:9], v[12:13], v[8:9]
	v_mul_f32_e32 v12, 0x3d922279, v14
	v_fmaak_f32 v12, v14, v12, 0x3fcc422a
	v_fmaak_f32 v16, v15, v16, 0x3fcc422a
	v_mul_f32_e32 v12, v14, v12
	v_mul_f32_e32 v13, 0xbfb8aa3b, v10
	v_mul_f32_e32 v16, v15, v16
	v_mul_f32_e32 v12, 0xbfb8aa3b, v12
	v_exp_f32_e32 v13, v13
	v_mul_f32_e32 v16, 0xbfb8aa3b, v16
	v_exp_f32_e32 v12, v12
	v_exp_f32_e32 v17, v16
	v_add_f32_e32 v13, 1.0, v13
	v_mul_f32_e32 v16, 0xbfb8aa3b, v11
	v_pk_mul_f32 v[8:9], v[8:9], v[18:19]
	v_add_f32_e32 v12, 1.0, v12
	v_exp_f32_e32 v18, v16
	v_rcp_f32_e32 v16, v13
	v_add_f32_e32 v13, 1.0, v17
	v_rcp_f32_e32 v12, v12
	v_rcp_f32_e32 v13, v13
	v_add_f32_e32 v17, 1.0, v18
	v_mul_f32_e32 v18, 0x3d922279, v4
	v_fmaak_f32 v18, v4, v18, 0x3fcc422a
	v_pk_mul_f32 v[12:13], v[14:15], v[12:13]
	v_mul_f32_e32 v14, 0x3d922279, v5
	v_fmaak_f32 v14, v5, v14, 0x3fcc422a
	v_mul_f32_e32 v18, v4, v18
	v_pk_mul_f32 v[10:11], v[12:13], v[10:11]
	v_mul_f32_e32 v13, 0xbfb8aa3b, v0
	v_mul_f32_e32 v14, v5, v14
	v_mul_f32_e32 v18, 0xbfb8aa3b, v18
	v_exp_f32_e32 v13, v13
	v_mul_f32_e32 v14, 0xbfb8aa3b, v14
	v_rcp_f32_e32 v17, v17
	v_exp_f32_e32 v18, v18
	v_exp_f32_e32 v14, v14
	v_add_f32_e32 v15, 1.0, v13
	v_mul_f32_e32 v13, 0xbfb8aa3b, v1
	v_pk_mul_f32 v[10:11], v[10:11], v[16:17]
	v_add_f32_e32 v12, 1.0, v18
	v_exp_f32_e32 v16, v13
	v_add_f32_e32 v13, 1.0, v14
	v_rcp_f32_e32 v12, v12
	v_rcp_f32_e32 v13, v13
	v_rcp_f32_e32 v14, v15
	v_add_f32_e32 v15, 1.0, v16
	v_rcp_f32_e32 v15, v15
	v_pk_mul_f32 v[4:5], v[4:5], v[12:13]
	v_mul_f32_e32 v12, 0x3d922279, v6
	v_fmaak_f32 v12, v6, v12, 0x3fcc422a
	v_mul_f32_e32 v12, v6, v12
	v_mul_f32_e32 v12, 0xbfb8aa3b, v12
	v_exp_f32_e32 v12, v12
	v_mul_f32_e32 v13, 0xbfb8aa3b, v2
	v_exp_f32_e32 v13, v13
	v_pk_mul_f32 v[0:1], v[4:5], v[0:1]
	v_add_f32_e32 v4, 1.0, v12
	v_mul_f32_e32 v12, 0x3d922279, v7
	v_fmaak_f32 v12, v7, v12, 0x3fcc422a
	v_mul_f32_e32 v12, v7, v12
	v_mul_f32_e32 v12, 0xbfb8aa3b, v12
	v_add_f32_e32 v5, 1.0, v13
	v_exp_f32_e32 v13, v12
	v_mul_f32_e32 v12, 0xbfb8aa3b, v3
	v_exp_f32_e32 v16, v12
	v_rcp_f32_e32 v12, v5
	v_add_f32_e32 v5, 1.0, v13
	v_rcp_f32_e32 v4, v4
	v_rcp_f32_e32 v5, v5
	v_add_f32_e32 v13, 1.0, v16
	v_rcp_f32_e32 v13, v13
	v_pk_mul_f32 v[14:15], v[0:1], v[14:15]
	v_pk_mul_f32 v[0:1], v[6:7], v[4:5]
	s_nop 0
	v_pk_mul_f32 v[0:1], v[0:1], v[2:3]
	v_cvt_pk_bf16_f32 v2, v14, v15
	v_pk_mul_f32 v[4:5], v[0:1], v[12:13]
	v_cvt_pk_bf16_f32 v0, v8, v9
	v_cvt_pk_bf16_f32 v3, v4, v5
	v_add_co_u32_e32 v4, vcc, 0xb0000, v112
	v_cvt_pk_bf16_f32 v1, v10, v11
	s_nop 0
	v_addc_co_u32_e32 v5, vcc, 0, v113, vcc
	global_store_dwordx4 v[4:5], v[0:3], off nt
